# adds: K-loop hand-off tightened (priority raise ahead of the pre-MFMA barrier, repeated lgkmcnt(0) and the mid-block setprio pair removed)
# speedup vs baseline: 1.0157x; 1.0157x over previous
; #define PG8_STAGE(bufoff, gbase, voff) do { _Pragma("unroll") for (int _i = 0; _i < 2; ++_i) \
;         __builtin_amdgcn_global_load_lds((const unsigned*)((const char*)(gbase) + (voff)[_i]), (PG8_LAS unsigned*)(lds + (bufoff) + ldsw + _i * 8192), 16, 0, 0); } while (0)
; #define PG8_LDA(dst, b, h) do { _Pragma("unroll") for (int m = 0; m < 4; ++m) _Pragma("unroll") for (int k = 0; k < 2; ++k) dst[m][k] = *(const PG8_LAS bf16x8*)(lds + PG8_SA(b, h) + aoff + m * 2048 + k * 1024); } while (0)
; #define PG8_LDB(dst, b, h) do { _Pragma("unroll") for (int n = 0; n < 2; ++n) _Pragma("unroll") for (int k = 0; k < 2; ++k) dst[n][k] = *(const PG8_LAS bf16x8*)(lds + PG8_SB(b, h) + boff + n * 2048 + k * 1024); } while (0)
; #define PG8_MMA(ai, bj, At, Bt) do { __builtin_amdgcn_s_setprio(1); _Pragma("unroll") for (int m = 0; m < 4; ++m) _Pragma("unroll") for (int n = 0; n < 2; ++n) _Pragma("unroll") for (int k = 0; k < 2; ++k) \
;         acc[ai][bj][m][n] = __builtin_amdgcn_mfma_f32_16x16x32_bf16(Bt[n][k], At[m][k], acc[ai][bj][m][n], 0, 0, 0); __builtin_amdgcn_s_setprio(0); } while (0)
; #define PG8_WAIT_V(n) asm volatile("s_waitcnt vmcnt(" #n ")" ::: "memory")
; #define PG8_WAIT_L(n) asm volatile("s_waitcnt lgkmcnt(" #n ")" ::: "memory")
; #define PG8_BAR __builtin_amdgcn_s_barrier()
; #define PG8_SCHED __builtin_amdgcn_sched_barrier(0)
; template <class Epi, class Sched, bool ALIGN_EPI = false, bool SP2 = false>
; __device__ __forceinline__ void gemm_phase(PG8_LAS unsigned char* lds, const Gemm g, const Sched& S, const Epi& E) {
;     ...
;             PG8_LDB(B0, 0, 0); PG8_LDB(B1, 0, 1); PG8_SCHED; PG8_LDA(At, 0, 0); PG8_STAGE(PG8_SA(1, 1), a1 + hstep, voffA);
;             PG8_WAIT_V(8); PG8_WAIT_L(0); PG8_BAR; PG8_MMA(0, 0, At, B0); PG8_MMA(0, 1, At, B1); PG8_BAR; PG8_SCHED;
;             PG8_LDA(At, 0, 1); PG8_STAGE(PG8_SB(0, 0), b2, voffB); PG8_STAGE(PG8_SB(0, 1), b2 + hstep, voffB); PG8_STAGE(PG8_SA(0, 0), a2, voffA);
;             PG8_WAIT_V(8); PG8_WAIT_L(0); PG8_BAR; PG8_MMA(1, 0, At, B0); PG8_MMA(1, 1, At, B1); PG8_BAR; PG8_SCHED;
.LBB0_136:
	ds_read_b128 v[158:161], v152
	ds_read_b128 v[162:165], v152 offset:1024
	ds_read_b128 v[166:169], v152 offset:2048
	ds_read_b128 v[170:173], v152 offset:3072
	ds_read_b128 v[174:177], v153
	ds_read_b128 v[178:181], v153 offset:1024
	ds_read_b128 v[182:185], v153 offset:2048
	ds_read_b128 v[186:189], v153 offset:3072
	s_add_u32 s64, s62, 0xfffc0080
	s_addc_u32 s65, s63, -1
	s_cmp_eq_u32 s76, 12
	s_cselect_b32 s71, s5, s65
	s_cselect_b32 s70, s26, s64
	s_cselect_b32 s65, s27, s75
	s_cselect_b32 s64, s53, s55
	v_lshl_add_u64 v[146:147], s[62:63], 0, v[138:139]
	s_add_i32 m0, s61, 0xc000
	ds_read_b128 v[190:193], v154
	ds_read_b128 v[194:197], v154 offset:1024
	ds_read_b128 v[198:201], v154 offset:2048
	ds_read_b128 v[206:209], v154 offset:3072
	ds_read_b128 v[210:213], v154 offset:4096
	ds_read_b128 v[214:217], v154 offset:5120
	ds_read_b128 v[218:221], v154 offset:6144
	ds_read_b128 v[222:225], v154 offset:7168
	global_load_lds_dwordx4 v[146:147], off
	v_lshl_add_u64 v[146:147], s[62:63], 0, v[140:141]
	s_add_i32 m0, s61, 0xe000
	s_nop 0
	global_load_lds_dwordx4 v[146:147], off
	s_waitcnt vmcnt(8)
	s_waitcnt lgkmcnt(0)
	s_setprio 1
	s_barrier
	v_mfma_f32_16x16x32_bf16 v[124:127], v[158:161], v[190:193], v[124:127]
	v_mfma_f32_16x16x32_bf16 v[120:123], v[166:169], v[190:193], v[120:123]
	v_mfma_f32_16x16x32_bf16 v[108:111], v[158:161], v[198:201], v[108:111]
	v_mfma_f32_16x16x32_bf16 v[104:107], v[166:169], v[198:201], v[104:107]
	v_mfma_f32_16x16x32_bf16 v[92:95], v[158:161], v[210:213], v[92:95]
	v_mfma_f32_16x16x32_bf16 v[88:91], v[166:169], v[210:213], v[88:91]
	v_mfma_f32_16x16x32_bf16 v[76:79], v[158:161], v[218:221], v[76:79]
	v_mfma_f32_16x16x32_bf16 v[72:75], v[166:169], v[218:221], v[72:75]
	v_mfma_f32_16x16x32_bf16 v[124:127], v[162:165], v[194:197], v[124:127]
	v_mfma_f32_16x16x32_bf16 v[120:123], v[170:173], v[194:197], v[120:123]
	v_mfma_f32_16x16x32_bf16 v[108:111], v[162:165], v[206:209], v[108:111]
	v_mfma_f32_16x16x32_bf16 v[104:107], v[170:173], v[206:209], v[104:107]
	v_mfma_f32_16x16x32_bf16 v[92:95], v[162:165], v[214:217], v[92:95]
	v_mfma_f32_16x16x32_bf16 v[88:91], v[170:173], v[214:217], v[88:91]
	v_mfma_f32_16x16x32_bf16 v[76:79], v[162:165], v[222:225], v[76:79]
	v_mfma_f32_16x16x32_bf16 v[72:75], v[170:173], v[222:225], v[72:75]
	v_mfma_f32_16x16x32_bf16 v[116:119], v[174:177], v[190:193], v[116:119]
	v_mfma_f32_16x16x32_bf16 v[112:115], v[182:185], v[190:193], v[112:115]
	v_mfma_f32_16x16x32_bf16 v[100:103], v[174:177], v[198:201], v[100:103]
	v_mfma_f32_16x16x32_bf16 v[96:99], v[182:185], v[198:201], v[96:99]
	v_mfma_f32_16x16x32_bf16 v[84:87], v[174:177], v[210:213], v[84:87]
	v_mfma_f32_16x16x32_bf16 v[80:83], v[182:185], v[210:213], v[80:83]
	v_mfma_f32_16x16x32_bf16 v[68:71], v[174:177], v[218:221], v[68:71]
	v_mfma_f32_16x16x32_bf16 v[64:67], v[182:185], v[218:221], v[64:67]
	v_mfma_f32_16x16x32_bf16 v[116:119], v[178:181], v[194:197], v[116:119]
	v_mfma_f32_16x16x32_bf16 v[112:115], v[186:189], v[194:197], v[112:115]
	v_mfma_f32_16x16x32_bf16 v[100:103], v[178:181], v[206:209], v[100:103]
	v_mfma_f32_16x16x32_bf16 v[96:99], v[186:189], v[206:209], v[96:99]
	v_mfma_f32_16x16x32_bf16 v[84:87], v[178:181], v[214:217], v[84:87]
	v_mfma_f32_16x16x32_bf16 v[80:83], v[186:189], v[214:217], v[80:83]
	v_mfma_f32_16x16x32_bf16 v[68:71], v[178:181], v[222:225], v[68:71]
	v_mfma_f32_16x16x32_bf16 v[64:67], v[186:189], v[222:225], v[64:67]
	s_setprio 0
	s_barrier
	s_add_i32 s77, s72, s33
	v_lshl_add_u64 v[146:147], s[64:65], 0, v[132:133]
	s_mov_b32 m0, s77
	ds_read_b128 v[190:193], v154 offset:16384
	ds_read_b128 v[194:197], v154 offset:17408
	ds_read_b128 v[198:201], v154 offset:18432
	ds_read_b128 v[206:209], v154 offset:19456
	ds_read_b128 v[210:213], v154 offset:20480
	ds_read_b128 v[214:217], v154 offset:21504
	ds_read_b128 v[218:221], v154 offset:22528
	ds_read_b128 v[222:225], v154 offset:23552
	global_load_lds_dwordx4 v[146:147], off
	s_add_i32 m0, s77, 0x2000
	s_add_u32 s78, s64, 0x40000
	v_lshl_add_u64 v[202:203], s[64:65], 0, v[136:137]
	s_addc_u32 s79, s65, 0
	s_add_i32 s77, s73, s33
	global_load_lds_dwordx4 v[202:203], off
	v_lshl_add_u64 v[226:227], s[78:79], 0, v[132:133]
	s_mov_b32 m0, s77
	v_lshl_add_u64 v[228:229], s[70:71], 0, v[134:135]
	global_load_lds_dwordx4 v[226:227], off
	v_lshl_add_u64 v[226:227], s[78:79], 0, v[136:137]
	s_add_i32 m0, s77, 0x2000
	s_nop 0
	global_load_lds_dwordx4 v[226:227], off
	v_lshl_add_u64 v[226:227], s[70:71], 0, v[130:131]
	s_mov_b32 m0, s61
	s_nop 0
	global_load_lds_dwordx4 v[226:227], off
	s_mov_b32 m0, s66
	s_nop 0
	global_load_lds_dwordx4 v[228:229], off
	s_waitcnt vmcnt(8)
	s_waitcnt lgkmcnt(0)
	s_setprio 1
	s_barrier
; #define PG8_STAGE(bufoff, gbase, voff) do { _Pragma("unroll") for (int _i = 0; _i < 2; ++_i) \
;         __builtin_amdgcn_global_load_lds((const unsigned*)((const char*)(gbase) + (voff)[_i]), (PG8_LAS unsigned*)(lds + (bufoff) + ldsw + _i * 8192), 16, 0, 0); } while (0)
; #define PG8_LDA(dst, b, h) do { _Pragma("unroll") for (int m = 0; m < 4; ++m) _Pragma("unroll") for (int k = 0; k < 2; ++k) dst[m][k] = *(const PG8_LAS bf16x8*)(lds + PG8_SA(b, h) + aoff + m * 2048 + k * 1024); } while (0)
; #define PG8_LDB(dst, b, h) do { _Pragma("unroll") for (int n = 0; n < 2; ++n) _Pragma("unroll") for (int k = 0; k < 2; ++k) dst[n][k] = *(const PG8_LAS bf16x8*)(lds + PG8_SB(b, h) + boff + n * 2048 + k * 1024); } while (0)
; #define PG8_MMA(ai, bj, At, Bt) do { __builtin_amdgcn_s_setprio(1); _Pragma("unroll") for (int m = 0; m < 4; ++m) _Pragma("unroll") for (int n = 0; n < 2; ++n) _Pragma("unroll") for (int k = 0; k < 2; ++k) \
;         acc[ai][bj][m][n] = __builtin_amdgcn_mfma_f32_16x16x32_bf16(Bt[n][k], At[m][k], acc[ai][bj][m][n], 0, 0, 0); __builtin_amdgcn_s_setprio(0); } while (0)
; #define PG8_WAIT_V(n) asm volatile("s_waitcnt vmcnt(" #n ")" ::: "memory")
; #define PG8_WAIT_L(n) asm volatile("s_waitcnt lgkmcnt(" #n ")" ::: "memory")
; #define PG8_BAR __builtin_amdgcn_s_barrier()
; #define PG8_SCHED __builtin_amdgcn_sched_barrier(0)
; template <class Epi, class Sched, bool ALIGN_EPI = false, bool SP2 = false>
; __device__ __forceinline__ void gemm_phase(PG8_LAS unsigned char* lds, const Gemm g, const Sched& S, const Epi& E) {
;     ...
;             PG8_WAIT_V(8); PG8_WAIT_L(0); PG8_BAR; PG8_MMA(1, 0, At, B0); PG8_MMA(1, 1, At, B1); PG8_BAR; PG8_SCHED;
;             PG8_LDB(B0, 1, 0); PG8_LDB(B1, 1, 1); PG8_SCHED; PG8_LDA(At, 1, 0); PG8_STAGE(PG8_SA(0, 1), a2 + hstep, voffA);
;             PG8_WAIT_V(8); PG8_WAIT_L(0); PG8_BAR; PG8_MMA(0, 0, At, B0); PG8_MMA(0, 1, At, B1); PG8_BAR; PG8_SCHED;
	v_mfma_f32_16x16x32_bf16 v[60:63], v[158:161], v[190:193], v[60:63]
	v_mfma_f32_16x16x32_bf16 v[56:59], v[166:169], v[190:193], v[56:59]
	v_mfma_f32_16x16x32_bf16 v[44:47], v[158:161], v[198:201], v[44:47]
	v_mfma_f32_16x16x32_bf16 v[40:43], v[166:169], v[198:201], v[40:43]
	v_mfma_f32_16x16x32_bf16 v[28:31], v[158:161], v[210:213], v[28:31]
	v_mfma_f32_16x16x32_bf16 v[24:27], v[166:169], v[210:213], v[24:27]
	v_mfma_f32_16x16x32_bf16 v[12:15], v[158:161], v[218:221], v[12:15]
	v_mfma_f32_16x16x32_bf16 v[8:11], v[166:169], v[218:221], v[8:11]
	v_mfma_f32_16x16x32_bf16 v[60:63], v[162:165], v[194:197], v[60:63]
	v_mfma_f32_16x16x32_bf16 v[56:59], v[170:173], v[194:197], v[56:59]
	v_mfma_f32_16x16x32_bf16 v[44:47], v[162:165], v[206:209], v[44:47]
	v_mfma_f32_16x16x32_bf16 v[40:43], v[170:173], v[206:209], v[40:43]
	v_mfma_f32_16x16x32_bf16 v[28:31], v[162:165], v[214:217], v[28:31]
	v_mfma_f32_16x16x32_bf16 v[24:27], v[170:173], v[214:217], v[24:27]
	v_mfma_f32_16x16x32_bf16 v[12:15], v[162:165], v[222:225], v[12:15]
	v_mfma_f32_16x16x32_bf16 v[8:11], v[170:173], v[222:225], v[8:11]
	v_mfma_f32_16x16x32_bf16 v[52:55], v[174:177], v[190:193], v[52:55]
	v_mfma_f32_16x16x32_bf16 v[48:51], v[182:185], v[190:193], v[48:51]
	v_mfma_f32_16x16x32_bf16 v[36:39], v[174:177], v[198:201], v[36:39]
	v_mfma_f32_16x16x32_bf16 v[32:35], v[182:185], v[198:201], v[32:35]
	v_mfma_f32_16x16x32_bf16 v[20:23], v[174:177], v[210:213], v[20:23]
	v_mfma_f32_16x16x32_bf16 v[16:19], v[182:185], v[210:213], v[16:19]
	v_mfma_f32_16x16x32_bf16 v[4:7], v[174:177], v[218:221], v[4:7]
	v_mfma_f32_16x16x32_bf16 v[0:3], v[182:185], v[218:221], v[0:3]
	v_mfma_f32_16x16x32_bf16 v[52:55], v[178:181], v[194:197], v[52:55]
	v_mfma_f32_16x16x32_bf16 v[48:51], v[186:189], v[194:197], v[48:51]
	v_mfma_f32_16x16x32_bf16 v[36:39], v[178:181], v[206:209], v[36:39]
	v_mfma_f32_16x16x32_bf16 v[32:35], v[186:189], v[206:209], v[32:35]
	v_mfma_f32_16x16x32_bf16 v[20:23], v[178:181], v[214:217], v[20:23]
	v_mfma_f32_16x16x32_bf16 v[16:19], v[186:189], v[214:217], v[16:19]
	v_mfma_f32_16x16x32_bf16 v[4:7], v[178:181], v[222:225], v[4:7]
	v_mfma_f32_16x16x32_bf16 v[0:3], v[186:189], v[222:225], v[0:3]
	s_setprio 0
	s_barrier
	s_add_i32 s77, 0, 0x18000
	v_add_u32_e32 v148, s77, v149
	s_add_i32 s78, 0, 0x1c000
	ds_read_b128 v[158:161], v148
	ds_read_b128 v[162:165], v148 offset:1024
	ds_read_b128 v[166:169], v148 offset:2048
	ds_read_b128 v[170:173], v148 offset:3072
	v_add_u32_e32 v148, s78, v149
	ds_read_b128 v[174:177], v148
	ds_read_b128 v[178:181], v148 offset:1024
	ds_read_b128 v[182:185], v148 offset:2048
	ds_read_b128 v[186:189], v148 offset:3072
	s_add_u32 s70, s70, 0x40000
	s_addc_u32 s71, s71, 0
	s_mov_b32 m0, s67
	v_lshl_add_u64 v[230:231], s[70:71], 0, v[130:131]
	ds_read_b128 v[190:193], v154 offset:32768
	ds_read_b128 v[194:197], v154 offset:33792
	ds_read_b128 v[198:201], v154 offset:34816
	ds_read_b128 v[206:209], v154 offset:35840
	ds_read_b128 v[210:213], v154 offset:36864
	ds_read_b128 v[214:217], v154 offset:37888
	ds_read_b128 v[218:221], v154 offset:38912
	ds_read_b128 v[222:225], v154 offset:39936
	global_load_lds_dwordx4 v[230:231], off
	v_lshl_add_u64 v[230:231], s[70:71], 0, v[134:135]
	s_mov_b32 m0, s88
	s_nop 0
	global_load_lds_dwordx4 v[230:231], off
	s_waitcnt vmcnt(8)
	s_waitcnt lgkmcnt(0)
	s_setprio 1
	s_barrier
	v_mfma_f32_16x16x32_bf16 v[124:127], v[158:161], v[190:193], v[124:127]
	v_mfma_f32_16x16x32_bf16 v[120:123], v[166:169], v[190:193], v[120:123]
	v_mfma_f32_16x16x32_bf16 v[108:111], v[158:161], v[198:201], v[108:111]
	v_mfma_f32_16x16x32_bf16 v[104:107], v[166:169], v[198:201], v[104:107]
	v_mfma_f32_16x16x32_bf16 v[92:95], v[158:161], v[210:213], v[92:95]
	v_mfma_f32_16x16x32_bf16 v[88:91], v[166:169], v[210:213], v[88:91]
	v_mfma_f32_16x16x32_bf16 v[76:79], v[158:161], v[218:221], v[76:79]
	v_mfma_f32_16x16x32_bf16 v[72:75], v[166:169], v[218:221], v[72:75]
	v_mfma_f32_16x16x32_bf16 v[124:127], v[162:165], v[194:197], v[124:127]
	v_mfma_f32_16x16x32_bf16 v[120:123], v[170:173], v[194:197], v[120:123]
	v_mfma_f32_16x16x32_bf16 v[108:111], v[162:165], v[206:209], v[108:111]
	v_mfma_f32_16x16x32_bf16 v[104:107], v[170:173], v[206:209], v[104:107]
	v_mfma_f32_16x16x32_bf16 v[92:95], v[162:165], v[214:217], v[92:95]
	v_mfma_f32_16x16x32_bf16 v[88:91], v[170:173], v[214:217], v[88:91]
	v_mfma_f32_16x16x32_bf16 v[76:79], v[162:165], v[222:225], v[76:79]
	v_mfma_f32_16x16x32_bf16 v[72:75], v[170:173], v[222:225], v[72:75]
	v_mfma_f32_16x16x32_bf16 v[116:119], v[174:177], v[190:193], v[116:119]
	v_mfma_f32_16x16x32_bf16 v[112:115], v[182:185], v[190:193], v[112:115]
	v_mfma_f32_16x16x32_bf16 v[100:103], v[174:177], v[198:201], v[100:103]
	v_mfma_f32_16x16x32_bf16 v[96:99], v[182:185], v[198:201], v[96:99]
	v_mfma_f32_16x16x32_bf16 v[84:87], v[174:177], v[210:213], v[84:87]
	v_mfma_f32_16x16x32_bf16 v[80:83], v[182:185], v[210:213], v[80:83]
	v_mfma_f32_16x16x32_bf16 v[68:71], v[174:177], v[218:221], v[68:71]
	v_mfma_f32_16x16x32_bf16 v[64:67], v[182:185], v[218:221], v[64:67]
	v_mfma_f32_16x16x32_bf16 v[116:119], v[178:181], v[194:197], v[116:119]
	v_mfma_f32_16x16x32_bf16 v[112:115], v[186:189], v[194:197], v[112:115]
	v_mfma_f32_16x16x32_bf16 v[100:103], v[178:181], v[206:209], v[100:103]
	v_mfma_f32_16x16x32_bf16 v[96:99], v[186:189], v[206:209], v[96:99]
	v_mfma_f32_16x16x32_bf16 v[84:87], v[178:181], v[214:217], v[84:87]
	v_mfma_f32_16x16x32_bf16 v[80:83], v[186:189], v[214:217], v[80:83]
	v_mfma_f32_16x16x32_bf16 v[68:71], v[178:181], v[222:225], v[68:71]
	v_mfma_f32_16x16x32_bf16 v[64:67], v[186:189], v[222:225], v[64:67]
	s_setprio 0
	s_barrier
; #define PG8_STAGE(bufoff, gbase, voff) do { _Pragma("unroll") for (int _i = 0; _i < 2; ++_i) \
;         __builtin_amdgcn_global_load_lds((const unsigned*)((const char*)(gbase) + (voff)[_i]), (PG8_LAS unsigned*)(lds + (bufoff) + ldsw + _i * 8192), 16, 0, 0); } while (0)
; #define PG8_LDA(dst, b, h) do { _Pragma("unroll") for (int m = 0; m < 4; ++m) _Pragma("unroll") for (int k = 0; k < 2; ++k) dst[m][k] = *(const PG8_LAS bf16x8*)(lds + PG8_SA(b, h) + aoff + m * 2048 + k * 1024); } while (0)
; #define PG8_MMA(ai, bj, At, Bt) do { __builtin_amdgcn_s_setprio(1); _Pragma("unroll") for (int m = 0; m < 4; ++m) _Pragma("unroll") for (int n = 0; n < 2; ++n) _Pragma("unroll") for (int k = 0; k < 2; ++k) \
;         acc[ai][bj][m][n] = __builtin_amdgcn_mfma_f32_16x16x32_bf16(Bt[n][k], At[m][k], acc[ai][bj][m][n], 0, 0, 0); __builtin_amdgcn_s_setprio(0); } while (0)
; #define PG8_WAIT_V(n) asm volatile("s_waitcnt vmcnt(" #n ")" ::: "memory")
; #define PG8_WAIT_L(n) asm volatile("s_waitcnt lgkmcnt(" #n ")" ::: "memory")
; #define PG8_BAR __builtin_amdgcn_s_barrier()
; #define PG8_SCHED __builtin_amdgcn_sched_barrier(0)
; template <class Epi, class Sched, bool ALIGN_EPI = false, bool SP2 = false>
; __device__ __forceinline__ void gemm_phase(PG8_LAS unsigned char* lds, const Gemm g, const Sched& S, const Epi& E) {
;     ...
;             PG8_LDA(At, 1, 1); PG8_STAGE(PG8_SB(1, 0), b3, voffB); PG8_STAGE(PG8_SB(1, 1), b3 + hstep, voffB); PG8_STAGE(PG8_SA(1, 0), a3, voffA);
;             PG8_WAIT_V(8); PG8_WAIT_L(0); PG8_BAR; PG8_MMA(1, 0, At, B0); PG8_MMA(1, 1, At, B1); PG8_BAR; PG8_SCHED;
	s_add_i32 s70, s77, s33
	v_lshl_add_u64 v[146:147], v[146:147], 0, s[34:35]
	s_mov_b32 m0, s70
	ds_read_b128 v[190:193], v154 offset:49152
	ds_read_b128 v[194:197], v154 offset:50176
	ds_read_b128 v[198:201], v154 offset:51200
	ds_read_b128 v[206:209], v154 offset:52224
	ds_read_b128 v[210:213], v154 offset:53248
	ds_read_b128 v[214:217], v154 offset:54272
	ds_read_b128 v[218:221], v154 offset:55296
	ds_read_b128 v[222:225], v154 offset:56320
	global_load_lds_dwordx4 v[146:147], off
	s_add_i32 m0, s70, 0x2000
	s_add_u32 s64, s64, 0x40080
	v_lshl_add_u64 v[146:147], v[202:203], 0, s[34:35]
	s_addc_u32 s65, s65, 0
	s_add_i32 s70, s78, s33
	global_load_lds_dwordx4 v[146:147], off
	v_lshl_add_u64 v[146:147], s[64:65], 0, v[132:133]
	s_mov_b32 m0, s70
	s_nop 0
	global_load_lds_dwordx4 v[146:147], off
	v_lshl_add_u64 v[146:147], s[64:65], 0, v[136:137]
	s_add_i32 m0, s70, 0x2000
	s_nop 0
	global_load_lds_dwordx4 v[146:147], off
	v_lshl_add_u64 v[146:147], v[226:227], 0, s[34:35]
	s_mov_b32 m0, s3
	s_nop 0
	global_load_lds_dwordx4 v[146:147], off
	v_lshl_add_u64 v[146:147], v[228:229], 0, s[34:35]
	s_mov_b32 m0, s68
	s_nop 0
	global_load_lds_dwordx4 v[146:147], off
	s_waitcnt vmcnt(8)
	s_waitcnt lgkmcnt(0)
	s_setprio 1
	s_barrier
	v_mfma_f32_16x16x32_bf16 v[60:63], v[158:161], v[190:193], v[60:63]
	v_mfma_f32_16x16x32_bf16 v[56:59], v[166:169], v[190:193], v[56:59]
	v_mfma_f32_16x16x32_bf16 v[44:47], v[158:161], v[198:201], v[44:47]
	v_mfma_f32_16x16x32_bf16 v[40:43], v[166:169], v[198:201], v[40:43]
	v_mfma_f32_16x16x32_bf16 v[28:31], v[158:161], v[210:213], v[28:31]
	v_mfma_f32_16x16x32_bf16 v[24:27], v[166:169], v[210:213], v[24:27]
	v_mfma_f32_16x16x32_bf16 v[12:15], v[158:161], v[218:221], v[12:15]
	v_mfma_f32_16x16x32_bf16 v[8:11], v[166:169], v[218:221], v[8:11]
	v_mfma_f32_16x16x32_bf16 v[60:63], v[162:165], v[194:197], v[60:63]
	v_mfma_f32_16x16x32_bf16 v[56:59], v[170:173], v[194:197], v[56:59]
	v_mfma_f32_16x16x32_bf16 v[44:47], v[162:165], v[206:209], v[44:47]
	v_mfma_f32_16x16x32_bf16 v[40:43], v[170:173], v[206:209], v[40:43]
	v_mfma_f32_16x16x32_bf16 v[28:31], v[162:165], v[214:217], v[28:31]
	v_mfma_f32_16x16x32_bf16 v[24:27], v[170:173], v[214:217], v[24:27]
	v_mfma_f32_16x16x32_bf16 v[12:15], v[162:165], v[222:225], v[12:15]
	v_mfma_f32_16x16x32_bf16 v[8:11], v[170:173], v[222:225], v[8:11]
	v_mfma_f32_16x16x32_bf16 v[52:55], v[174:177], v[190:193], v[52:55]
	v_mfma_f32_16x16x32_bf16 v[48:51], v[182:185], v[190:193], v[48:51]
	v_mfma_f32_16x16x32_bf16 v[36:39], v[174:177], v[198:201], v[36:39]
	v_mfma_f32_16x16x32_bf16 v[32:35], v[182:185], v[198:201], v[32:35]
	v_mfma_f32_16x16x32_bf16 v[20:23], v[174:177], v[210:213], v[20:23]
	v_mfma_f32_16x16x32_bf16 v[16:19], v[182:185], v[210:213], v[16:19]
	v_mfma_f32_16x16x32_bf16 v[4:7], v[174:177], v[218:221], v[4:7]
	v_mfma_f32_16x16x32_bf16 v[0:3], v[182:185], v[218:221], v[0:3]
	v_mfma_f32_16x16x32_bf16 v[52:55], v[178:181], v[194:197], v[52:55]
	v_mfma_f32_16x16x32_bf16 v[48:51], v[186:189], v[194:197], v[48:51]
	v_mfma_f32_16x16x32_bf16 v[36:39], v[178:181], v[206:209], v[36:39]
	v_mfma_f32_16x16x32_bf16 v[32:35], v[186:189], v[206:209], v[32:35]
	v_mfma_f32_16x16x32_bf16 v[20:23], v[178:181], v[214:217], v[20:23]
	v_mfma_f32_16x16x32_bf16 v[16:19], v[186:189], v[214:217], v[16:19]
	v_mfma_f32_16x16x32_bf16 v[4:7], v[178:181], v[222:225], v[4:7]
	v_mfma_f32_16x16x32_bf16 v[0:3], v[186:189], v[222:225], v[0:3]
	s_setprio 0
	s_barrier
	s_add_i32 s76, s76, 2
	s_add_u32 s62, s62, 0x100
	s_addc_u32 s63, s63, 0
	s_add_u32 s55, s55, 0x100
	s_addc_u32 s75, s75, 0
	s_cmp_gt_u32 s76, 13
	s_cbranch_scc0 .LBB0_136
	s_and_b64 vcc, exec, s[50:51]
	s_cbranch_vccz .LBB0_139
	s_barrier

; #define PG8_STAGE(bufoff, gbase, voff) do { _Pragma("unroll") for (int _i = 0; _i < 2; ++_i) \
;         __builtin_amdgcn_global_load_lds((const unsigned*)((const char*)(gbase) + (voff)[_i]), (PG8_LAS unsigned*)(lds + (bufoff) + ldsw + _i * 8192), 16, 0, 0); } while (0)
; #define PG8_LDA(dst, b, h) do { _Pragma("unroll") for (int m = 0; m < 4; ++m) _Pragma("unroll") for (int k = 0; k < 2; ++k) dst[m][k] = *(const PG8_LAS bf16x8*)(lds + PG8_SA(b, h) + aoff + m * 2048 + k * 1024); } while (0)
; #define PG8_LDB(dst, b, h) do { _Pragma("unroll") for (int n = 0; n < 2; ++n) _Pragma("unroll") for (int k = 0; k < 2; ++k) dst[n][k] = *(const PG8_LAS bf16x8*)(lds + PG8_SB(b, h) + boff + n * 2048 + k * 1024); } while (0)
; #define PG8_MMA(ai, bj, At, Bt) do { __builtin_amdgcn_s_setprio(1); _Pragma("unroll") for (int m = 0; m < 4; ++m) _Pragma("unroll") for (int n = 0; n < 2; ++n) _Pragma("unroll") for (int k = 0; k < 2; ++k) \
;         acc[ai][bj][m][n] = __builtin_amdgcn_mfma_f32_16x16x32_bf16(Bt[n][k], At[m][k], acc[ai][bj][m][n], 0, 0, 0); __builtin_amdgcn_s_setprio(0); } while (0)
; #define PG8_WAIT_V(n) asm volatile("s_waitcnt vmcnt(" #n ")" ::: "memory")
; #define PG8_WAIT_L(n) asm volatile("s_waitcnt lgkmcnt(" #n ")" ::: "memory")
; #define PG8_BAR __builtin_amdgcn_s_barrier()
; #define PG8_SCHED __builtin_amdgcn_sched_barrier(0)
; template <class Epi, class Sched, bool ALIGN_EPI = false, bool SP2 = false>
; __device__ __forceinline__ void gemm_phase(PG8_LAS unsigned char* lds, const Gemm g, const Sched& S, const Epi& E) {
;     ...
;             PG8_LDB(B0, 0, 0); PG8_LDB(B1, 0, 1); PG8_SCHED; PG8_LDA(At, 0, 0); PG8_STAGE(PG8_SA(1, 1), a1 + hstep, voffA);
;             PG8_WAIT_V(8); PG8_WAIT_L(0); PG8_BAR; PG8_MMA(0, 0, At, B0); PG8_MMA(0, 1, At, B1); PG8_BAR; PG8_SCHED;
;             PG8_LDA(At, 0, 1); PG8_STAGE(PG8_SB(0, 0), b2, voffB); PG8_STAGE(PG8_SB(0, 1), b2 + hstep, voffB); PG8_STAGE(PG8_SA(0, 0), a2, voffA);
;             PG8_WAIT_V(8); PG8_WAIT_L(0); PG8_BAR; PG8_MMA(1, 0, At, B0); PG8_MMA(1, 1, At, B1); PG8_BAR; PG8_SCHED;
.LBB0_520:
	ds_read_b128 v[146:149], v152
	ds_read_b128 v[156:159], v152 offset:1024
	ds_read_b128 v[160:163], v152 offset:2048
	ds_read_b128 v[164:167], v152 offset:3072
	ds_read_b128 v[168:171], v153
	ds_read_b128 v[172:175], v153 offset:1024
	ds_read_b128 v[176:179], v153 offset:2048
	ds_read_b128 v[180:183], v153 offset:3072
	s_add_u32 s46, s44, 0xfffc0080
	s_addc_u32 s47, s45, -1
	s_cmp_eq_u32 s63, 12
	s_cselect_b32 s49, s35, s47
	s_cselect_b32 s48, s41, s46
	s_cselect_b32 s47, s31, s62
	s_cselect_b32 s46, s60, s61
	v_lshl_add_u64 v[218:219], s[44:45], 0, v[138:139]
	s_add_i32 m0, s43, 0xc000
	ds_read_b128 v[184:187], v154
	ds_read_b128 v[188:191], v154 offset:1024
	ds_read_b128 v[192:195], v154 offset:2048
	ds_read_b128 v[196:199], v154 offset:3072
	ds_read_b128 v[200:203], v154 offset:4096
	ds_read_b128 v[206:209], v154 offset:5120
	ds_read_b128 v[210:213], v154 offset:6144
	ds_read_b128 v[214:217], v154 offset:7168
	global_load_lds_dwordx4 v[218:219], off
	v_lshl_add_u64 v[218:219], s[44:45], 0, v[140:141]
	s_add_i32 m0, s43, 0xe000
	s_nop 0
	global_load_lds_dwordx4 v[218:219], off
	s_waitcnt vmcnt(8)
	s_waitcnt lgkmcnt(0)
	s_setprio 1
	s_barrier
	v_mfma_f32_16x16x32_bf16 v[124:127], v[146:149], v[184:187], v[124:127]
	v_mfma_f32_16x16x32_bf16 v[120:123], v[160:163], v[184:187], v[120:123]
	v_mfma_f32_16x16x32_bf16 v[108:111], v[146:149], v[192:195], v[108:111]
	v_mfma_f32_16x16x32_bf16 v[104:107], v[160:163], v[192:195], v[104:107]
	v_mfma_f32_16x16x32_bf16 v[92:95], v[146:149], v[200:203], v[92:95]
	v_mfma_f32_16x16x32_bf16 v[88:91], v[160:163], v[200:203], v[88:91]
	v_mfma_f32_16x16x32_bf16 v[76:79], v[146:149], v[210:213], v[76:79]
	v_mfma_f32_16x16x32_bf16 v[72:75], v[160:163], v[210:213], v[72:75]
	v_mfma_f32_16x16x32_bf16 v[124:127], v[156:159], v[188:191], v[124:127]
	v_mfma_f32_16x16x32_bf16 v[120:123], v[164:167], v[188:191], v[120:123]
	v_mfma_f32_16x16x32_bf16 v[108:111], v[156:159], v[196:199], v[108:111]
	v_mfma_f32_16x16x32_bf16 v[104:107], v[164:167], v[196:199], v[104:107]
	v_mfma_f32_16x16x32_bf16 v[92:95], v[156:159], v[206:209], v[92:95]
	v_mfma_f32_16x16x32_bf16 v[88:91], v[164:167], v[206:209], v[88:91]
	v_mfma_f32_16x16x32_bf16 v[76:79], v[156:159], v[214:217], v[76:79]
	v_mfma_f32_16x16x32_bf16 v[72:75], v[164:167], v[214:217], v[72:75]
	v_mfma_f32_16x16x32_bf16 v[116:119], v[168:171], v[184:187], v[116:119]
	v_mfma_f32_16x16x32_bf16 v[112:115], v[176:179], v[184:187], v[112:115]
	v_mfma_f32_16x16x32_bf16 v[100:103], v[168:171], v[192:195], v[100:103]
	v_mfma_f32_16x16x32_bf16 v[96:99], v[176:179], v[192:195], v[96:99]
	v_mfma_f32_16x16x32_bf16 v[84:87], v[168:171], v[200:203], v[84:87]
	v_mfma_f32_16x16x32_bf16 v[80:83], v[176:179], v[200:203], v[80:83]
	v_mfma_f32_16x16x32_bf16 v[68:71], v[168:171], v[210:213], v[68:71]
	v_mfma_f32_16x16x32_bf16 v[64:67], v[176:179], v[210:213], v[64:67]
	v_mfma_f32_16x16x32_bf16 v[116:119], v[172:175], v[188:191], v[116:119]
	v_mfma_f32_16x16x32_bf16 v[112:115], v[180:183], v[188:191], v[112:115]
	v_mfma_f32_16x16x32_bf16 v[100:103], v[172:175], v[196:199], v[100:103]
	v_mfma_f32_16x16x32_bf16 v[96:99], v[180:183], v[196:199], v[96:99]
	v_mfma_f32_16x16x32_bf16 v[84:87], v[172:175], v[206:209], v[84:87]
	v_mfma_f32_16x16x32_bf16 v[80:83], v[180:183], v[206:209], v[80:83]
	v_mfma_f32_16x16x32_bf16 v[68:71], v[172:175], v[214:217], v[68:71]
	v_mfma_f32_16x16x32_bf16 v[64:67], v[180:183], v[214:217], v[64:67]
	s_setprio 0
	s_barrier
	s_add_i32 s64, s58, s13
	v_lshl_add_u64 v[218:219], s[46:47], 0, v[132:133]
	s_mov_b32 m0, s64
	ds_read_b128 v[184:187], v154 offset:16384
	ds_read_b128 v[188:191], v154 offset:17408
	ds_read_b128 v[192:195], v154 offset:18432
	ds_read_b128 v[196:199], v154 offset:19456
	ds_read_b128 v[200:203], v154 offset:20480
	ds_read_b128 v[206:209], v154 offset:21504
	ds_read_b128 v[210:213], v154 offset:22528
	ds_read_b128 v[214:217], v154 offset:23552
	global_load_lds_dwordx4 v[218:219], off
	s_add_i32 m0, s64, 0x2000
	s_add_u32 s64, s46, 0x40000
	v_lshl_add_u64 v[220:221], s[46:47], 0, v[136:137]
	s_addc_u32 s65, s47, 0
	s_add_i32 s66, s59, s13
	global_load_lds_dwordx4 v[220:221], off
	v_lshl_add_u64 v[222:223], s[64:65], 0, v[132:133]
	s_mov_b32 m0, s66
	v_lshl_add_u64 v[224:225], s[48:49], 0, v[134:135]
	global_load_lds_dwordx4 v[222:223], off
	v_lshl_add_u64 v[222:223], s[64:65], 0, v[136:137]
	s_add_i32 m0, s66, 0x2000
	s_nop 0
	global_load_lds_dwordx4 v[222:223], off
	v_lshl_add_u64 v[222:223], s[48:49], 0, v[130:131]
	s_mov_b32 m0, s43
	s_nop 0
	global_load_lds_dwordx4 v[222:223], off
	s_mov_b32 m0, s50
	s_nop 0
	global_load_lds_dwordx4 v[224:225], off
	s_waitcnt vmcnt(8)
	s_waitcnt lgkmcnt(0)
	s_setprio 1
	s_barrier
; #define PG8_STAGE(bufoff, gbase, voff) do { _Pragma("unroll") for (int _i = 0; _i < 2; ++_i) \
;         __builtin_amdgcn_global_load_lds((const unsigned*)((const char*)(gbase) + (voff)[_i]), (PG8_LAS unsigned*)(lds + (bufoff) + ldsw + _i * 8192), 16, 0, 0); } while (0)
; #define PG8_LDA(dst, b, h) do { _Pragma("unroll") for (int m = 0; m < 4; ++m) _Pragma("unroll") for (int k = 0; k < 2; ++k) dst[m][k] = *(const PG8_LAS bf16x8*)(lds + PG8_SA(b, h) + aoff + m * 2048 + k * 1024); } while (0)
; #define PG8_LDB(dst, b, h) do { _Pragma("unroll") for (int n = 0; n < 2; ++n) _Pragma("unroll") for (int k = 0; k < 2; ++k) dst[n][k] = *(const PG8_LAS bf16x8*)(lds + PG8_SB(b, h) + boff + n * 2048 + k * 1024); } while (0)
; #define PG8_MMA(ai, bj, At, Bt) do { __builtin_amdgcn_s_setprio(1); _Pragma("unroll") for (int m = 0; m < 4; ++m) _Pragma("unroll") for (int n = 0; n < 2; ++n) _Pragma("unroll") for (int k = 0; k < 2; ++k) \
;         acc[ai][bj][m][n] = __builtin_amdgcn_mfma_f32_16x16x32_bf16(Bt[n][k], At[m][k], acc[ai][bj][m][n], 0, 0, 0); __builtin_amdgcn_s_setprio(0); } while (0)
; #define PG8_WAIT_V(n) asm volatile("s_waitcnt vmcnt(" #n ")" ::: "memory")
; #define PG8_WAIT_L(n) asm volatile("s_waitcnt lgkmcnt(" #n ")" ::: "memory")
; #define PG8_BAR __builtin_amdgcn_s_barrier()
; #define PG8_SCHED __builtin_amdgcn_sched_barrier(0)
; template <class Epi, class Sched, bool ALIGN_EPI = false, bool SP2 = false>
; __device__ __forceinline__ void gemm_phase(PG8_LAS unsigned char* lds, const Gemm g, const Sched& S, const Epi& E) {
;     ...
;             PG8_WAIT_V(8); PG8_WAIT_L(0); PG8_BAR; PG8_MMA(1, 0, At, B0); PG8_MMA(1, 1, At, B1); PG8_BAR; PG8_SCHED;
;             PG8_LDB(B0, 1, 0); PG8_LDB(B1, 1, 1); PG8_SCHED; PG8_LDA(At, 1, 0); PG8_STAGE(PG8_SA(0, 1), a2 + hstep, voffA);
;             PG8_WAIT_V(8); PG8_WAIT_L(0); PG8_BAR; PG8_MMA(0, 0, At, B0); PG8_MMA(0, 1, At, B1); PG8_BAR; PG8_SCHED;
	v_mfma_f32_16x16x32_bf16 v[60:63], v[146:149], v[184:187], v[60:63]
	v_mfma_f32_16x16x32_bf16 v[56:59], v[160:163], v[184:187], v[56:59]
	v_mfma_f32_16x16x32_bf16 v[44:47], v[146:149], v[192:195], v[44:47]
	v_mfma_f32_16x16x32_bf16 v[40:43], v[160:163], v[192:195], v[40:43]
	v_mfma_f32_16x16x32_bf16 v[28:31], v[146:149], v[200:203], v[28:31]
	v_mfma_f32_16x16x32_bf16 v[24:27], v[160:163], v[200:203], v[24:27]
	v_mfma_f32_16x16x32_bf16 v[12:15], v[146:149], v[210:213], v[12:15]
	v_mfma_f32_16x16x32_bf16 v[8:11], v[160:163], v[210:213], v[8:11]
	v_mfma_f32_16x16x32_bf16 v[60:63], v[156:159], v[188:191], v[60:63]
	v_mfma_f32_16x16x32_bf16 v[56:59], v[164:167], v[188:191], v[56:59]
	v_mfma_f32_16x16x32_bf16 v[44:47], v[156:159], v[196:199], v[44:47]
	v_mfma_f32_16x16x32_bf16 v[40:43], v[164:167], v[196:199], v[40:43]
	v_mfma_f32_16x16x32_bf16 v[28:31], v[156:159], v[206:209], v[28:31]
	v_mfma_f32_16x16x32_bf16 v[24:27], v[164:167], v[206:209], v[24:27]
	v_mfma_f32_16x16x32_bf16 v[12:15], v[156:159], v[214:217], v[12:15]
	v_mfma_f32_16x16x32_bf16 v[8:11], v[164:167], v[214:217], v[8:11]
	v_mfma_f32_16x16x32_bf16 v[52:55], v[168:171], v[184:187], v[52:55]
	v_mfma_f32_16x16x32_bf16 v[48:51], v[176:179], v[184:187], v[48:51]
	v_mfma_f32_16x16x32_bf16 v[36:39], v[168:171], v[192:195], v[36:39]
	v_mfma_f32_16x16x32_bf16 v[32:35], v[176:179], v[192:195], v[32:35]
	v_mfma_f32_16x16x32_bf16 v[20:23], v[168:171], v[200:203], v[20:23]
	v_mfma_f32_16x16x32_bf16 v[16:19], v[176:179], v[200:203], v[16:19]
	v_mfma_f32_16x16x32_bf16 v[4:7], v[168:171], v[210:213], v[4:7]
	v_mfma_f32_16x16x32_bf16 v[0:3], v[176:179], v[210:213], v[0:3]
	v_mfma_f32_16x16x32_bf16 v[52:55], v[172:175], v[188:191], v[52:55]
	v_mfma_f32_16x16x32_bf16 v[48:51], v[180:183], v[188:191], v[48:51]
	v_mfma_f32_16x16x32_bf16 v[36:39], v[172:175], v[196:199], v[36:39]
	v_mfma_f32_16x16x32_bf16 v[32:35], v[180:183], v[196:199], v[32:35]
	v_mfma_f32_16x16x32_bf16 v[20:23], v[172:175], v[206:209], v[20:23]
	v_mfma_f32_16x16x32_bf16 v[16:19], v[180:183], v[206:209], v[16:19]
	v_mfma_f32_16x16x32_bf16 v[4:7], v[172:175], v[214:217], v[4:7]
	v_mfma_f32_16x16x32_bf16 v[0:3], v[180:183], v[214:217], v[0:3]
	s_setprio 0
	s_barrier
	s_add_i32 s64, 0, 0x18000
	s_add_i32 s65, 0, 0x1c000
	v_add_u32_e32 v164, s64, v150
	v_add_u32_e32 v180, s65, v150
	ds_read_b128 v[146:149], v164
	ds_read_b128 v[156:159], v164 offset:1024
	ds_read_b128 v[160:163], v164 offset:2048
	ds_read_b128 v[164:167], v164 offset:3072
	ds_read_b128 v[168:171], v180
	ds_read_b128 v[172:175], v180 offset:1024
	ds_read_b128 v[176:179], v180 offset:2048
	ds_read_b128 v[180:183], v180 offset:3072
	s_add_u32 s48, s48, 0x40000
	s_addc_u32 s49, s49, 0
	s_mov_b32 m0, s51
	v_lshl_add_u64 v[226:227], s[48:49], 0, v[130:131]
	ds_read_b128 v[184:187], v154 offset:32768
	ds_read_b128 v[188:191], v154 offset:33792
	ds_read_b128 v[192:195], v154 offset:34816
	ds_read_b128 v[196:199], v154 offset:35840
	ds_read_b128 v[200:203], v154 offset:36864
	ds_read_b128 v[206:209], v154 offset:37888
	ds_read_b128 v[210:213], v154 offset:38912
	ds_read_b128 v[214:217], v154 offset:39936
	global_load_lds_dwordx4 v[226:227], off
	v_lshl_add_u64 v[226:227], s[48:49], 0, v[134:135]
	s_mov_b32 m0, s52
	s_nop 0
	global_load_lds_dwordx4 v[226:227], off
	s_waitcnt vmcnt(8)
	s_waitcnt lgkmcnt(0)
	s_setprio 1
	s_barrier
	v_mfma_f32_16x16x32_bf16 v[124:127], v[146:149], v[184:187], v[124:127]
	v_mfma_f32_16x16x32_bf16 v[120:123], v[160:163], v[184:187], v[120:123]
	v_mfma_f32_16x16x32_bf16 v[108:111], v[146:149], v[192:195], v[108:111]
	v_mfma_f32_16x16x32_bf16 v[104:107], v[160:163], v[192:195], v[104:107]
	v_mfma_f32_16x16x32_bf16 v[92:95], v[146:149], v[200:203], v[92:95]
	v_mfma_f32_16x16x32_bf16 v[88:91], v[160:163], v[200:203], v[88:91]
	v_mfma_f32_16x16x32_bf16 v[76:79], v[146:149], v[210:213], v[76:79]
	v_mfma_f32_16x16x32_bf16 v[72:75], v[160:163], v[210:213], v[72:75]
	v_mfma_f32_16x16x32_bf16 v[124:127], v[156:159], v[188:191], v[124:127]
	v_mfma_f32_16x16x32_bf16 v[120:123], v[164:167], v[188:191], v[120:123]
	v_mfma_f32_16x16x32_bf16 v[108:111], v[156:159], v[196:199], v[108:111]
	v_mfma_f32_16x16x32_bf16 v[104:107], v[164:167], v[196:199], v[104:107]
	v_mfma_f32_16x16x32_bf16 v[92:95], v[156:159], v[206:209], v[92:95]
	v_mfma_f32_16x16x32_bf16 v[88:91], v[164:167], v[206:209], v[88:91]
	v_mfma_f32_16x16x32_bf16 v[76:79], v[156:159], v[214:217], v[76:79]
	v_mfma_f32_16x16x32_bf16 v[72:75], v[164:167], v[214:217], v[72:75]
	v_mfma_f32_16x16x32_bf16 v[116:119], v[168:171], v[184:187], v[116:119]
	v_mfma_f32_16x16x32_bf16 v[112:115], v[176:179], v[184:187], v[112:115]
	v_mfma_f32_16x16x32_bf16 v[100:103], v[168:171], v[192:195], v[100:103]
	v_mfma_f32_16x16x32_bf16 v[96:99], v[176:179], v[192:195], v[96:99]
	v_mfma_f32_16x16x32_bf16 v[84:87], v[168:171], v[200:203], v[84:87]
	v_mfma_f32_16x16x32_bf16 v[80:83], v[176:179], v[200:203], v[80:83]
	v_mfma_f32_16x16x32_bf16 v[68:71], v[168:171], v[210:213], v[68:71]
	v_mfma_f32_16x16x32_bf16 v[64:67], v[176:179], v[210:213], v[64:67]
	v_mfma_f32_16x16x32_bf16 v[116:119], v[172:175], v[188:191], v[116:119]
	v_mfma_f32_16x16x32_bf16 v[112:115], v[180:183], v[188:191], v[112:115]
	v_mfma_f32_16x16x32_bf16 v[100:103], v[172:175], v[196:199], v[100:103]
	v_mfma_f32_16x16x32_bf16 v[96:99], v[180:183], v[196:199], v[96:99]
	v_mfma_f32_16x16x32_bf16 v[84:87], v[172:175], v[206:209], v[84:87]
	v_mfma_f32_16x16x32_bf16 v[80:83], v[180:183], v[206:209], v[80:83]
	v_mfma_f32_16x16x32_bf16 v[68:71], v[172:175], v[214:217], v[68:71]
	v_mfma_f32_16x16x32_bf16 v[64:67], v[180:183], v[214:217], v[64:67]
	s_setprio 0
	s_barrier
; #define PG8_STAGE(bufoff, gbase, voff) do { _Pragma("unroll") for (int _i = 0; _i < 2; ++_i) \
;         __builtin_amdgcn_global_load_lds((const unsigned*)((const char*)(gbase) + (voff)[_i]), (PG8_LAS unsigned*)(lds + (bufoff) + ldsw + _i * 8192), 16, 0, 0); } while (0)
; #define PG8_LDA(dst, b, h) do { _Pragma("unroll") for (int m = 0; m < 4; ++m) _Pragma("unroll") for (int k = 0; k < 2; ++k) dst[m][k] = *(const PG8_LAS bf16x8*)(lds + PG8_SA(b, h) + aoff + m * 2048 + k * 1024); } while (0)
; #define PG8_MMA(ai, bj, At, Bt) do { __builtin_amdgcn_s_setprio(1); _Pragma("unroll") for (int m = 0; m < 4; ++m) _Pragma("unroll") for (int n = 0; n < 2; ++n) _Pragma("unroll") for (int k = 0; k < 2; ++k) \
;         acc[ai][bj][m][n] = __builtin_amdgcn_mfma_f32_16x16x32_bf16(Bt[n][k], At[m][k], acc[ai][bj][m][n], 0, 0, 0); __builtin_amdgcn_s_setprio(0); } while (0)
; #define PG8_WAIT_V(n) asm volatile("s_waitcnt vmcnt(" #n ")" ::: "memory")
; #define PG8_WAIT_L(n) asm volatile("s_waitcnt lgkmcnt(" #n ")" ::: "memory")
; #define PG8_BAR __builtin_amdgcn_s_barrier()
; #define PG8_SCHED __builtin_amdgcn_sched_barrier(0)
; template <class Epi, class Sched, bool ALIGN_EPI = false, bool SP2 = false>
; __device__ __forceinline__ void gemm_phase(PG8_LAS unsigned char* lds, const Gemm g, const Sched& S, const Epi& E) {
;     ...
;             PG8_LDA(At, 1, 1); PG8_STAGE(PG8_SB(1, 0), b3, voffB); PG8_STAGE(PG8_SB(1, 1), b3 + hstep, voffB); PG8_STAGE(PG8_SA(1, 0), a3, voffA);
;             PG8_WAIT_V(8); PG8_WAIT_L(0); PG8_BAR; PG8_MMA(1, 0, At, B0); PG8_MMA(1, 1, At, B1); PG8_BAR; PG8_SCHED;
	s_add_i32 s48, s64, s13
	v_lshl_add_u64 v[218:219], v[218:219], 0, s[20:21]
	s_mov_b32 m0, s48
	ds_read_b128 v[184:187], v154 offset:49152
	ds_read_b128 v[188:191], v154 offset:50176
	ds_read_b128 v[192:195], v154 offset:51200
	ds_read_b128 v[196:199], v154 offset:52224
	ds_read_b128 v[200:203], v154 offset:53248
	ds_read_b128 v[206:209], v154 offset:54272
	ds_read_b128 v[210:213], v154 offset:55296
	ds_read_b128 v[214:217], v154 offset:56320
	global_load_lds_dwordx4 v[218:219], off
	s_add_i32 m0, s48, 0x2000
	s_add_u32 s46, s46, 0x40080
	v_lshl_add_u64 v[218:219], v[220:221], 0, s[20:21]
	s_addc_u32 s47, s47, 0
	s_add_i32 s48, s65, s13
	global_load_lds_dwordx4 v[218:219], off
	v_lshl_add_u64 v[218:219], s[46:47], 0, v[132:133]
	s_mov_b32 m0, s48
	s_nop 0
	global_load_lds_dwordx4 v[218:219], off
	v_lshl_add_u64 v[218:219], s[46:47], 0, v[136:137]
	s_add_i32 m0, s48, 0x2000
	s_nop 0
	global_load_lds_dwordx4 v[218:219], off
	v_lshl_add_u64 v[218:219], v[222:223], 0, s[20:21]
	s_mov_b32 m0, s54
	s_nop 0
	global_load_lds_dwordx4 v[218:219], off
	v_lshl_add_u64 v[218:219], v[224:225], 0, s[20:21]
	s_mov_b32 m0, s55
	s_nop 0
	global_load_lds_dwordx4 v[218:219], off
	s_waitcnt vmcnt(8)
	s_waitcnt lgkmcnt(0)
	s_setprio 1
	s_barrier
	v_mfma_f32_16x16x32_bf16 v[60:63], v[146:149], v[184:187], v[60:63]
	v_mfma_f32_16x16x32_bf16 v[56:59], v[160:163], v[184:187], v[56:59]
	v_mfma_f32_16x16x32_bf16 v[44:47], v[146:149], v[192:195], v[44:47]
	v_mfma_f32_16x16x32_bf16 v[40:43], v[160:163], v[192:195], v[40:43]
	v_mfma_f32_16x16x32_bf16 v[28:31], v[146:149], v[200:203], v[28:31]
	v_mfma_f32_16x16x32_bf16 v[24:27], v[160:163], v[200:203], v[24:27]
	v_mfma_f32_16x16x32_bf16 v[12:15], v[146:149], v[210:213], v[12:15]
	v_mfma_f32_16x16x32_bf16 v[8:11], v[160:163], v[210:213], v[8:11]
	v_mfma_f32_16x16x32_bf16 v[60:63], v[156:159], v[188:191], v[60:63]
	v_mfma_f32_16x16x32_bf16 v[56:59], v[164:167], v[188:191], v[56:59]
	v_mfma_f32_16x16x32_bf16 v[44:47], v[156:159], v[196:199], v[44:47]
	v_mfma_f32_16x16x32_bf16 v[40:43], v[164:167], v[196:199], v[40:43]
	v_mfma_f32_16x16x32_bf16 v[28:31], v[156:159], v[206:209], v[28:31]
	v_mfma_f32_16x16x32_bf16 v[24:27], v[164:167], v[206:209], v[24:27]
	v_mfma_f32_16x16x32_bf16 v[12:15], v[156:159], v[214:217], v[12:15]
	v_mfma_f32_16x16x32_bf16 v[8:11], v[164:167], v[214:217], v[8:11]
	v_mfma_f32_16x16x32_bf16 v[52:55], v[168:171], v[184:187], v[52:55]
	v_mfma_f32_16x16x32_bf16 v[48:51], v[176:179], v[184:187], v[48:51]
	v_mfma_f32_16x16x32_bf16 v[36:39], v[168:171], v[192:195], v[36:39]
	v_mfma_f32_16x16x32_bf16 v[32:35], v[176:179], v[192:195], v[32:35]
	v_mfma_f32_16x16x32_bf16 v[20:23], v[168:171], v[200:203], v[20:23]
	v_mfma_f32_16x16x32_bf16 v[16:19], v[176:179], v[200:203], v[16:19]
	v_mfma_f32_16x16x32_bf16 v[4:7], v[168:171], v[210:213], v[4:7]
	v_mfma_f32_16x16x32_bf16 v[0:3], v[176:179], v[210:213], v[0:3]
	v_mfma_f32_16x16x32_bf16 v[52:55], v[172:175], v[188:191], v[52:55]
	v_mfma_f32_16x16x32_bf16 v[48:51], v[180:183], v[188:191], v[48:51]
	v_mfma_f32_16x16x32_bf16 v[36:39], v[172:175], v[196:199], v[36:39]
	v_mfma_f32_16x16x32_bf16 v[32:35], v[180:183], v[196:199], v[32:35]
	v_mfma_f32_16x16x32_bf16 v[20:23], v[172:175], v[206:209], v[20:23]
	v_mfma_f32_16x16x32_bf16 v[16:19], v[180:183], v[206:209], v[16:19]
	v_mfma_f32_16x16x32_bf16 v[4:7], v[172:175], v[214:217], v[4:7]
	v_mfma_f32_16x16x32_bf16 v[0:3], v[180:183], v[214:217], v[0:3]
	s_setprio 0
	s_barrier
	s_add_i32 s63, s63, 2
	s_add_u32 s44, s44, 0x100
	s_addc_u32 s45, s45, 0
	s_add_u32 s61, s61, 0x100
	s_addc_u32 s62, s62, 0
	s_cmp_gt_u32 s63, 13
	s_cbranch_scc0 .LBB0_520
	s_and_b64 vcc, exec, s[28:29]
	s_cbranch_vccz .LBB0_523
	s_barrier

; #define PG8_STAGE(bufoff, gbase, voff) do { _Pragma("unroll") for (int _i = 0; _i < 2; ++_i) \
;         __builtin_amdgcn_global_load_lds((const unsigned*)((const char*)(gbase) + (voff)[_i]), (PG8_LAS unsigned*)(lds + (bufoff) + ldsw + _i * 8192), 16, 0, 0); } while (0)
; #define PG8_LDA(dst, b, h) do { _Pragma("unroll") for (int m = 0; m < 4; ++m) _Pragma("unroll") for (int k = 0; k < 2; ++k) dst[m][k] = *(const PG8_LAS bf16x8*)(lds + PG8_SA(b, h) + aoff + m * 2048 + k * 1024); } while (0)
; #define PG8_LDB(dst, b, h) do { _Pragma("unroll") for (int n = 0; n < 2; ++n) _Pragma("unroll") for (int k = 0; k < 2; ++k) dst[n][k] = *(const PG8_LAS bf16x8*)(lds + PG8_SB(b, h) + boff + n * 2048 + k * 1024); } while (0)
; #define PG8_MMA(ai, bj, At, Bt) do { __builtin_amdgcn_s_setprio(1); _Pragma("unroll") for (int m = 0; m < 4; ++m) _Pragma("unroll") for (int n = 0; n < 2; ++n) _Pragma("unroll") for (int k = 0; k < 2; ++k) \
;         acc[ai][bj][m][n] = __builtin_amdgcn_mfma_f32_16x16x32_bf16(Bt[n][k], At[m][k], acc[ai][bj][m][n], 0, 0, 0); __builtin_amdgcn_s_setprio(0); } while (0)
; #define PG8_WAIT_V(n) asm volatile("s_waitcnt vmcnt(" #n ")" ::: "memory")
; #define PG8_WAIT_L(n) asm volatile("s_waitcnt lgkmcnt(" #n ")" ::: "memory")
; #define PG8_BAR __builtin_amdgcn_s_barrier()
; #define PG8_SCHED __builtin_amdgcn_sched_barrier(0)
; template <class Epi, class Sched, bool ALIGN_EPI = false, bool SP2 = false>
; __device__ __forceinline__ void gemm_phase(PG8_LAS unsigned char* lds, const Gemm g, const Sched& S, const Epi& E) {
;     ...
;             PG8_LDB(B0, 0, 0); PG8_LDB(B1, 0, 1); PG8_SCHED; PG8_LDA(At, 0, 0); PG8_STAGE(PG8_SA(1, 1), a1 + hstep, voffA);
;             PG8_WAIT_V(8); PG8_WAIT_L(0); PG8_BAR; PG8_MMA(0, 0, At, B0); PG8_MMA(0, 1, At, B1); PG8_BAR; PG8_SCHED;
;             PG8_LDA(At, 0, 1); PG8_STAGE(PG8_SB(0, 0), b2, voffB); PG8_STAGE(PG8_SB(0, 1), b2 + hstep, voffB); PG8_STAGE(PG8_SA(0, 0), a2, voffA);
;             PG8_WAIT_V(8); PG8_WAIT_L(0); PG8_BAR; PG8_MMA(1, 0, At, B0); PG8_MMA(1, 1, At, B1); PG8_BAR; PG8_SCHED;
.LBB0_627:
	ds_read_b128 v[154:157], v149
	ds_read_b128 v[158:161], v149 offset:1024
	ds_read_b128 v[162:165], v149 offset:2048
	ds_read_b128 v[166:169], v149 offset:3072
	ds_read_b128 v[170:173], v150
	ds_read_b128 v[174:177], v150 offset:1024
	ds_read_b128 v[178:181], v150 offset:2048
	ds_read_b128 v[182:185], v150 offset:3072
	s_add_u32 s44, s42, 0xfffc0080
	s_addc_u32 s45, s43, -1
	s_cmp_eq_u32 s64, 12
	s_cselect_b32 s47, s37, s45
	s_cselect_b32 s46, s60, s44
	s_cselect_b32 s45, s35, s63
	s_cselect_b32 s44, s61, s62
	v_lshl_add_u64 v[146:147], s[42:43], 0, v[138:139]
	s_add_i32 m0, s48, 0xc000
	ds_read_b128 v[186:189], v151
	ds_read_b128 v[190:193], v151 offset:1024
	ds_read_b128 v[194:197], v151 offset:2048
	ds_read_b128 v[198:201], v151 offset:3072
	ds_read_b128 v[206:209], v151 offset:4096
	ds_read_b128 v[210:213], v151 offset:5120
	ds_read_b128 v[214:217], v151 offset:6144
	ds_read_b128 v[218:221], v151 offset:7168
	global_load_lds_dwordx4 v[146:147], off
	v_lshl_add_u64 v[146:147], s[42:43], 0, v[140:141]
	s_add_i32 m0, s48, 0xe000
	s_nop 0
	global_load_lds_dwordx4 v[146:147], off
	s_waitcnt vmcnt(8)
	s_waitcnt lgkmcnt(0)
	s_setprio 1
	s_barrier
	v_mfma_f32_16x16x32_bf16 v[124:127], v[154:157], v[186:189], v[124:127]
	v_mfma_f32_16x16x32_bf16 v[120:123], v[162:165], v[186:189], v[120:123]
	v_mfma_f32_16x16x32_bf16 v[108:111], v[154:157], v[194:197], v[108:111]
	v_mfma_f32_16x16x32_bf16 v[104:107], v[162:165], v[194:197], v[104:107]
	v_mfma_f32_16x16x32_bf16 v[92:95], v[154:157], v[206:209], v[92:95]
	v_mfma_f32_16x16x32_bf16 v[88:91], v[162:165], v[206:209], v[88:91]
	v_mfma_f32_16x16x32_bf16 v[76:79], v[154:157], v[214:217], v[76:79]
	v_mfma_f32_16x16x32_bf16 v[72:75], v[162:165], v[214:217], v[72:75]
	v_mfma_f32_16x16x32_bf16 v[124:127], v[158:161], v[190:193], v[124:127]
	v_mfma_f32_16x16x32_bf16 v[120:123], v[166:169], v[190:193], v[120:123]
	v_mfma_f32_16x16x32_bf16 v[108:111], v[158:161], v[198:201], v[108:111]
	v_mfma_f32_16x16x32_bf16 v[104:107], v[166:169], v[198:201], v[104:107]
	v_mfma_f32_16x16x32_bf16 v[92:95], v[158:161], v[210:213], v[92:95]
	v_mfma_f32_16x16x32_bf16 v[88:91], v[166:169], v[210:213], v[88:91]
	v_mfma_f32_16x16x32_bf16 v[76:79], v[158:161], v[218:221], v[76:79]
	v_mfma_f32_16x16x32_bf16 v[72:75], v[166:169], v[218:221], v[72:75]
	v_mfma_f32_16x16x32_bf16 v[116:119], v[170:173], v[186:189], v[116:119]
	v_mfma_f32_16x16x32_bf16 v[112:115], v[178:181], v[186:189], v[112:115]
	v_mfma_f32_16x16x32_bf16 v[100:103], v[170:173], v[194:197], v[100:103]
	v_mfma_f32_16x16x32_bf16 v[96:99], v[178:181], v[194:197], v[96:99]
	v_mfma_f32_16x16x32_bf16 v[84:87], v[170:173], v[206:209], v[84:87]
	v_mfma_f32_16x16x32_bf16 v[80:83], v[178:181], v[206:209], v[80:83]
	v_mfma_f32_16x16x32_bf16 v[68:71], v[170:173], v[214:217], v[68:71]
	v_mfma_f32_16x16x32_bf16 v[64:67], v[178:181], v[214:217], v[64:67]
	v_mfma_f32_16x16x32_bf16 v[116:119], v[174:177], v[190:193], v[116:119]
	v_mfma_f32_16x16x32_bf16 v[112:115], v[182:185], v[190:193], v[112:115]
	v_mfma_f32_16x16x32_bf16 v[100:103], v[174:177], v[198:201], v[100:103]
	v_mfma_f32_16x16x32_bf16 v[96:99], v[182:185], v[198:201], v[96:99]
	v_mfma_f32_16x16x32_bf16 v[84:87], v[174:177], v[210:213], v[84:87]
	v_mfma_f32_16x16x32_bf16 v[80:83], v[182:185], v[210:213], v[80:83]
	v_mfma_f32_16x16x32_bf16 v[68:71], v[174:177], v[218:221], v[68:71]
	v_mfma_f32_16x16x32_bf16 v[64:67], v[182:185], v[218:221], v[64:67]
	s_setprio 0
	s_barrier
	s_add_i32 s65, s57, s13
	v_lshl_add_u64 v[146:147], s[44:45], 0, v[132:133]
	s_mov_b32 m0, s65
	ds_read_b128 v[186:189], v151 offset:16384
	ds_read_b128 v[190:193], v151 offset:17408
	ds_read_b128 v[194:197], v151 offset:18432
	ds_read_b128 v[198:201], v151 offset:19456
	ds_read_b128 v[206:209], v151 offset:20480
	ds_read_b128 v[210:213], v151 offset:21504
	ds_read_b128 v[214:217], v151 offset:22528
	ds_read_b128 v[218:221], v151 offset:23552
	global_load_lds_dwordx4 v[146:147], off
	s_add_i32 m0, s65, 0x2000
	s_add_u32 s66, s44, 0x40000
	v_lshl_add_u64 v[202:203], s[44:45], 0, v[136:137]
	s_addc_u32 s67, s45, 0
	s_add_i32 s65, s58, s13
	global_load_lds_dwordx4 v[202:203], off
	v_lshl_add_u64 v[222:223], s[66:67], 0, v[132:133]
	s_mov_b32 m0, s65
	v_lshl_add_u64 v[224:225], s[46:47], 0, v[134:135]
	global_load_lds_dwordx4 v[222:223], off
	v_lshl_add_u64 v[222:223], s[66:67], 0, v[136:137]
	s_add_i32 m0, s65, 0x2000
	s_nop 0
	global_load_lds_dwordx4 v[222:223], off
	v_lshl_add_u64 v[222:223], s[46:47], 0, v[130:131]
	s_mov_b32 m0, s48
	s_nop 0
	global_load_lds_dwordx4 v[222:223], off
	s_mov_b32 m0, s49
	s_nop 0
	global_load_lds_dwordx4 v[224:225], off
	s_waitcnt vmcnt(8)
	s_waitcnt lgkmcnt(0)
	s_setprio 1
	s_barrier
; #define PG8_STAGE(bufoff, gbase, voff) do { _Pragma("unroll") for (int _i = 0; _i < 2; ++_i) \
;         __builtin_amdgcn_global_load_lds((const unsigned*)((const char*)(gbase) + (voff)[_i]), (PG8_LAS unsigned*)(lds + (bufoff) + ldsw + _i * 8192), 16, 0, 0); } while (0)
; #define PG8_LDA(dst, b, h) do { _Pragma("unroll") for (int m = 0; m < 4; ++m) _Pragma("unroll") for (int k = 0; k < 2; ++k) dst[m][k] = *(const PG8_LAS bf16x8*)(lds + PG8_SA(b, h) + aoff + m * 2048 + k * 1024); } while (0)
; #define PG8_LDB(dst, b, h) do { _Pragma("unroll") for (int n = 0; n < 2; ++n) _Pragma("unroll") for (int k = 0; k < 2; ++k) dst[n][k] = *(const PG8_LAS bf16x8*)(lds + PG8_SB(b, h) + boff + n * 2048 + k * 1024); } while (0)
; #define PG8_MMA(ai, bj, At, Bt) do { __builtin_amdgcn_s_setprio(1); _Pragma("unroll") for (int m = 0; m < 4; ++m) _Pragma("unroll") for (int n = 0; n < 2; ++n) _Pragma("unroll") for (int k = 0; k < 2; ++k) \
;         acc[ai][bj][m][n] = __builtin_amdgcn_mfma_f32_16x16x32_bf16(Bt[n][k], At[m][k], acc[ai][bj][m][n], 0, 0, 0); __builtin_amdgcn_s_setprio(0); } while (0)
; #define PG8_WAIT_V(n) asm volatile("s_waitcnt vmcnt(" #n ")" ::: "memory")
; #define PG8_WAIT_L(n) asm volatile("s_waitcnt lgkmcnt(" #n ")" ::: "memory")
; #define PG8_BAR __builtin_amdgcn_s_barrier()
; #define PG8_SCHED __builtin_amdgcn_sched_barrier(0)
; template <class Epi, class Sched, bool ALIGN_EPI = false, bool SP2 = false>
; __device__ __forceinline__ void gemm_phase(PG8_LAS unsigned char* lds, const Gemm g, const Sched& S, const Epi& E) {
;     ...
;             PG8_WAIT_V(8); PG8_WAIT_L(0); PG8_BAR; PG8_MMA(1, 0, At, B0); PG8_MMA(1, 1, At, B1); PG8_BAR; PG8_SCHED;
;             PG8_LDB(B0, 1, 0); PG8_LDB(B1, 1, 1); PG8_SCHED; PG8_LDA(At, 1, 0); PG8_STAGE(PG8_SA(0, 1), a2 + hstep, voffA);
;             PG8_WAIT_V(8); PG8_WAIT_L(0); PG8_BAR; PG8_MMA(0, 0, At, B0); PG8_MMA(0, 1, At, B1); PG8_BAR; PG8_SCHED;
	v_mfma_f32_16x16x32_bf16 v[60:63], v[154:157], v[186:189], v[60:63]
	v_mfma_f32_16x16x32_bf16 v[56:59], v[162:165], v[186:189], v[56:59]
	v_mfma_f32_16x16x32_bf16 v[44:47], v[154:157], v[194:197], v[44:47]
	v_mfma_f32_16x16x32_bf16 v[40:43], v[162:165], v[194:197], v[40:43]
	v_mfma_f32_16x16x32_bf16 v[28:31], v[154:157], v[206:209], v[28:31]
	v_mfma_f32_16x16x32_bf16 v[24:27], v[162:165], v[206:209], v[24:27]
	v_mfma_f32_16x16x32_bf16 v[12:15], v[154:157], v[214:217], v[12:15]
	v_mfma_f32_16x16x32_bf16 v[8:11], v[162:165], v[214:217], v[8:11]
	v_mfma_f32_16x16x32_bf16 v[60:63], v[158:161], v[190:193], v[60:63]
	v_mfma_f32_16x16x32_bf16 v[56:59], v[166:169], v[190:193], v[56:59]
	v_mfma_f32_16x16x32_bf16 v[44:47], v[158:161], v[198:201], v[44:47]
	v_mfma_f32_16x16x32_bf16 v[40:43], v[166:169], v[198:201], v[40:43]
	v_mfma_f32_16x16x32_bf16 v[28:31], v[158:161], v[210:213], v[28:31]
	v_mfma_f32_16x16x32_bf16 v[24:27], v[166:169], v[210:213], v[24:27]
	v_mfma_f32_16x16x32_bf16 v[12:15], v[158:161], v[218:221], v[12:15]
	v_mfma_f32_16x16x32_bf16 v[8:11], v[166:169], v[218:221], v[8:11]
	v_mfma_f32_16x16x32_bf16 v[52:55], v[170:173], v[186:189], v[52:55]
	v_mfma_f32_16x16x32_bf16 v[48:51], v[178:181], v[186:189], v[48:51]
	v_mfma_f32_16x16x32_bf16 v[36:39], v[170:173], v[194:197], v[36:39]
	v_mfma_f32_16x16x32_bf16 v[32:35], v[178:181], v[194:197], v[32:35]
	v_mfma_f32_16x16x32_bf16 v[20:23], v[170:173], v[206:209], v[20:23]
	v_mfma_f32_16x16x32_bf16 v[16:19], v[178:181], v[206:209], v[16:19]
	v_mfma_f32_16x16x32_bf16 v[4:7], v[170:173], v[214:217], v[4:7]
	v_mfma_f32_16x16x32_bf16 v[0:3], v[178:181], v[214:217], v[0:3]
	v_mfma_f32_16x16x32_bf16 v[52:55], v[174:177], v[190:193], v[52:55]
	v_mfma_f32_16x16x32_bf16 v[48:51], v[182:185], v[190:193], v[48:51]
	v_mfma_f32_16x16x32_bf16 v[36:39], v[174:177], v[198:201], v[36:39]
	v_mfma_f32_16x16x32_bf16 v[32:35], v[182:185], v[198:201], v[32:35]
	v_mfma_f32_16x16x32_bf16 v[20:23], v[174:177], v[210:213], v[20:23]
	v_mfma_f32_16x16x32_bf16 v[16:19], v[182:185], v[210:213], v[16:19]
	v_mfma_f32_16x16x32_bf16 v[4:7], v[174:177], v[218:221], v[4:7]
	v_mfma_f32_16x16x32_bf16 v[0:3], v[182:185], v[218:221], v[0:3]
	s_setprio 0
	s_barrier
	s_add_i32 s65, 0, 0x18000
	s_add_i32 s66, 0, 0x1c000
	v_add_u32_e32 v166, s65, v148
	v_add_u32_e32 v182, s66, v148
	ds_read_b128 v[154:157], v166
	ds_read_b128 v[158:161], v166 offset:1024
	ds_read_b128 v[162:165], v166 offset:2048
	ds_read_b128 v[166:169], v166 offset:3072
	ds_read_b128 v[170:173], v182
	ds_read_b128 v[174:177], v182 offset:1024
	ds_read_b128 v[178:181], v182 offset:2048
	ds_read_b128 v[182:185], v182 offset:3072
	s_add_u32 s46, s46, 0x40000
	s_addc_u32 s47, s47, 0
	s_mov_b32 m0, s50
	v_lshl_add_u64 v[226:227], s[46:47], 0, v[130:131]
	ds_read_b128 v[186:189], v151 offset:32768
	ds_read_b128 v[190:193], v151 offset:33792
	ds_read_b128 v[194:197], v151 offset:34816
	ds_read_b128 v[198:201], v151 offset:35840
	ds_read_b128 v[206:209], v151 offset:36864
	ds_read_b128 v[210:213], v151 offset:37888
	ds_read_b128 v[214:217], v151 offset:38912
	ds_read_b128 v[218:221], v151 offset:39936
	global_load_lds_dwordx4 v[226:227], off
	v_lshl_add_u64 v[226:227], s[46:47], 0, v[134:135]
	s_mov_b32 m0, s51
	s_nop 0
	global_load_lds_dwordx4 v[226:227], off
	s_waitcnt vmcnt(8)
	s_waitcnt lgkmcnt(0)
	s_setprio 1
	s_barrier
	v_mfma_f32_16x16x32_bf16 v[124:127], v[154:157], v[186:189], v[124:127]
	v_mfma_f32_16x16x32_bf16 v[120:123], v[162:165], v[186:189], v[120:123]
	v_mfma_f32_16x16x32_bf16 v[108:111], v[154:157], v[194:197], v[108:111]
	v_mfma_f32_16x16x32_bf16 v[104:107], v[162:165], v[194:197], v[104:107]
	v_mfma_f32_16x16x32_bf16 v[92:95], v[154:157], v[206:209], v[92:95]
	v_mfma_f32_16x16x32_bf16 v[88:91], v[162:165], v[206:209], v[88:91]
	v_mfma_f32_16x16x32_bf16 v[76:79], v[154:157], v[214:217], v[76:79]
	v_mfma_f32_16x16x32_bf16 v[72:75], v[162:165], v[214:217], v[72:75]
	v_mfma_f32_16x16x32_bf16 v[124:127], v[158:161], v[190:193], v[124:127]
	v_mfma_f32_16x16x32_bf16 v[120:123], v[166:169], v[190:193], v[120:123]
	v_mfma_f32_16x16x32_bf16 v[108:111], v[158:161], v[198:201], v[108:111]
	v_mfma_f32_16x16x32_bf16 v[104:107], v[166:169], v[198:201], v[104:107]
	v_mfma_f32_16x16x32_bf16 v[92:95], v[158:161], v[210:213], v[92:95]
	v_mfma_f32_16x16x32_bf16 v[88:91], v[166:169], v[210:213], v[88:91]
	v_mfma_f32_16x16x32_bf16 v[76:79], v[158:161], v[218:221], v[76:79]
	v_mfma_f32_16x16x32_bf16 v[72:75], v[166:169], v[218:221], v[72:75]
	v_mfma_f32_16x16x32_bf16 v[116:119], v[170:173], v[186:189], v[116:119]
	v_mfma_f32_16x16x32_bf16 v[112:115], v[178:181], v[186:189], v[112:115]
	v_mfma_f32_16x16x32_bf16 v[100:103], v[170:173], v[194:197], v[100:103]
	v_mfma_f32_16x16x32_bf16 v[96:99], v[178:181], v[194:197], v[96:99]
	v_mfma_f32_16x16x32_bf16 v[84:87], v[170:173], v[206:209], v[84:87]
	v_mfma_f32_16x16x32_bf16 v[80:83], v[178:181], v[206:209], v[80:83]
	v_mfma_f32_16x16x32_bf16 v[68:71], v[170:173], v[214:217], v[68:71]
	v_mfma_f32_16x16x32_bf16 v[64:67], v[178:181], v[214:217], v[64:67]
	v_mfma_f32_16x16x32_bf16 v[116:119], v[174:177], v[190:193], v[116:119]
	v_mfma_f32_16x16x32_bf16 v[112:115], v[182:185], v[190:193], v[112:115]
	v_mfma_f32_16x16x32_bf16 v[100:103], v[174:177], v[198:201], v[100:103]
	v_mfma_f32_16x16x32_bf16 v[96:99], v[182:185], v[198:201], v[96:99]
	v_mfma_f32_16x16x32_bf16 v[84:87], v[174:177], v[210:213], v[84:87]
	v_mfma_f32_16x16x32_bf16 v[80:83], v[182:185], v[210:213], v[80:83]
	v_mfma_f32_16x16x32_bf16 v[68:71], v[174:177], v[218:221], v[68:71]
	v_mfma_f32_16x16x32_bf16 v[64:67], v[182:185], v[218:221], v[64:67]
	s_setprio 0
	s_barrier
; #define PG8_STAGE(bufoff, gbase, voff) do { _Pragma("unroll") for (int _i = 0; _i < 2; ++_i) \
;         __builtin_amdgcn_global_load_lds((const unsigned*)((const char*)(gbase) + (voff)[_i]), (PG8_LAS unsigned*)(lds + (bufoff) + ldsw + _i * 8192), 16, 0, 0); } while (0)
; #define PG8_LDA(dst, b, h) do { _Pragma("unroll") for (int m = 0; m < 4; ++m) _Pragma("unroll") for (int k = 0; k < 2; ++k) dst[m][k] = *(const PG8_LAS bf16x8*)(lds + PG8_SA(b, h) + aoff + m * 2048 + k * 1024); } while (0)
; #define PG8_MMA(ai, bj, At, Bt) do { __builtin_amdgcn_s_setprio(1); _Pragma("unroll") for (int m = 0; m < 4; ++m) _Pragma("unroll") for (int n = 0; n < 2; ++n) _Pragma("unroll") for (int k = 0; k < 2; ++k) \
;         acc[ai][bj][m][n] = __builtin_amdgcn_mfma_f32_16x16x32_bf16(Bt[n][k], At[m][k], acc[ai][bj][m][n], 0, 0, 0); __builtin_amdgcn_s_setprio(0); } while (0)
; #define PG8_WAIT_V(n) asm volatile("s_waitcnt vmcnt(" #n ")" ::: "memory")
; #define PG8_WAIT_L(n) asm volatile("s_waitcnt lgkmcnt(" #n ")" ::: "memory")
; #define PG8_BAR __builtin_amdgcn_s_barrier()
; #define PG8_SCHED __builtin_amdgcn_sched_barrier(0)
; template <class Epi, class Sched, bool ALIGN_EPI = false, bool SP2 = false>
; __device__ __forceinline__ void gemm_phase(PG8_LAS unsigned char* lds, const Gemm g, const Sched& S, const Epi& E) {
;     ...
;             PG8_LDA(At, 1, 1); PG8_STAGE(PG8_SB(1, 0), b3, voffB); PG8_STAGE(PG8_SB(1, 1), b3 + hstep, voffB); PG8_STAGE(PG8_SA(1, 0), a3, voffA);
;             PG8_WAIT_V(8); PG8_WAIT_L(0); PG8_BAR; PG8_MMA(1, 0, At, B0); PG8_MMA(1, 1, At, B1); PG8_BAR; PG8_SCHED;
;     ...
;         if constexpr (ALIGN_EPI) { if (wr == 0) PG8_BAR; }
	s_add_i32 s46, s65, s13
	v_lshl_add_u64 v[146:147], v[146:147], 0, s[28:29]
	s_mov_b32 m0, s46
	ds_read_b128 v[186:189], v151 offset:49152
	ds_read_b128 v[190:193], v151 offset:50176
	ds_read_b128 v[194:197], v151 offset:51200
	ds_read_b128 v[198:201], v151 offset:52224
	ds_read_b128 v[206:209], v151 offset:53248
	ds_read_b128 v[210:213], v151 offset:54272
	ds_read_b128 v[214:217], v151 offset:55296
	ds_read_b128 v[218:221], v151 offset:56320
	global_load_lds_dwordx4 v[146:147], off
	s_add_i32 m0, s46, 0x2000
	s_add_u32 s44, s44, 0x40080
	v_lshl_add_u64 v[146:147], v[202:203], 0, s[28:29]
	s_addc_u32 s45, s45, 0
	s_add_i32 s46, s66, s13
	global_load_lds_dwordx4 v[146:147], off
	v_lshl_add_u64 v[146:147], s[44:45], 0, v[132:133]
	s_mov_b32 m0, s46
	s_nop 0
	global_load_lds_dwordx4 v[146:147], off
	v_lshl_add_u64 v[146:147], s[44:45], 0, v[136:137]
	s_add_i32 m0, s46, 0x2000
	s_nop 0
	global_load_lds_dwordx4 v[146:147], off
	v_lshl_add_u64 v[146:147], v[222:223], 0, s[28:29]
	s_mov_b32 m0, s54
	s_nop 0
	global_load_lds_dwordx4 v[146:147], off
	v_lshl_add_u64 v[146:147], v[224:225], 0, s[28:29]
	s_mov_b32 m0, s55
	s_nop 0
	global_load_lds_dwordx4 v[146:147], off
	s_waitcnt vmcnt(8)
	s_waitcnt lgkmcnt(0)
	s_setprio 1
	s_barrier
	v_mfma_f32_16x16x32_bf16 v[60:63], v[154:157], v[186:189], v[60:63]
	v_mfma_f32_16x16x32_bf16 v[56:59], v[162:165], v[186:189], v[56:59]
	v_mfma_f32_16x16x32_bf16 v[44:47], v[154:157], v[194:197], v[44:47]
	v_mfma_f32_16x16x32_bf16 v[40:43], v[162:165], v[194:197], v[40:43]
	v_mfma_f32_16x16x32_bf16 v[28:31], v[154:157], v[206:209], v[28:31]
	v_mfma_f32_16x16x32_bf16 v[24:27], v[162:165], v[206:209], v[24:27]
	v_mfma_f32_16x16x32_bf16 v[12:15], v[154:157], v[214:217], v[12:15]
	v_mfma_f32_16x16x32_bf16 v[8:11], v[162:165], v[214:217], v[8:11]
	v_mfma_f32_16x16x32_bf16 v[60:63], v[158:161], v[190:193], v[60:63]
	v_mfma_f32_16x16x32_bf16 v[56:59], v[166:169], v[190:193], v[56:59]
	v_mfma_f32_16x16x32_bf16 v[44:47], v[158:161], v[198:201], v[44:47]
	v_mfma_f32_16x16x32_bf16 v[40:43], v[166:169], v[198:201], v[40:43]
	v_mfma_f32_16x16x32_bf16 v[28:31], v[158:161], v[210:213], v[28:31]
	v_mfma_f32_16x16x32_bf16 v[24:27], v[166:169], v[210:213], v[24:27]
	v_mfma_f32_16x16x32_bf16 v[12:15], v[158:161], v[218:221], v[12:15]
	v_mfma_f32_16x16x32_bf16 v[8:11], v[166:169], v[218:221], v[8:11]
	v_mfma_f32_16x16x32_bf16 v[52:55], v[170:173], v[186:189], v[52:55]
	v_mfma_f32_16x16x32_bf16 v[48:51], v[178:181], v[186:189], v[48:51]
	v_mfma_f32_16x16x32_bf16 v[36:39], v[170:173], v[194:197], v[36:39]
	v_mfma_f32_16x16x32_bf16 v[32:35], v[178:181], v[194:197], v[32:35]
	v_mfma_f32_16x16x32_bf16 v[20:23], v[170:173], v[206:209], v[20:23]
	v_mfma_f32_16x16x32_bf16 v[16:19], v[178:181], v[206:209], v[16:19]
	v_mfma_f32_16x16x32_bf16 v[4:7], v[170:173], v[214:217], v[4:7]
	v_mfma_f32_16x16x32_bf16 v[0:3], v[178:181], v[214:217], v[0:3]
	v_mfma_f32_16x16x32_bf16 v[52:55], v[174:177], v[190:193], v[52:55]
	v_mfma_f32_16x16x32_bf16 v[48:51], v[182:185], v[190:193], v[48:51]
	v_mfma_f32_16x16x32_bf16 v[36:39], v[174:177], v[198:201], v[36:39]
	v_mfma_f32_16x16x32_bf16 v[32:35], v[182:185], v[198:201], v[32:35]
	v_mfma_f32_16x16x32_bf16 v[20:23], v[174:177], v[210:213], v[20:23]
	v_mfma_f32_16x16x32_bf16 v[16:19], v[182:185], v[210:213], v[16:19]
	v_mfma_f32_16x16x32_bf16 v[4:7], v[174:177], v[218:221], v[4:7]
	v_mfma_f32_16x16x32_bf16 v[0:3], v[182:185], v[218:221], v[0:3]
	s_setprio 0
	s_barrier
	s_add_i32 s64, s64, 2
	s_add_u32 s42, s42, 0x100
	s_addc_u32 s43, s43, 0
	s_add_u32 s62, s62, 0x100
	s_addc_u32 s63, s63, 0
	s_cmp_gt_u32 s64, 13
	s_cbranch_scc0 .LBB0_627
	s_and_b64 vcc, exec, s[30:31]
	s_cbranch_vccz .LBB0_630
	s_barrier

; #define PG8_STAGE(bufoff, gbase, voff) do { _Pragma("unroll") for (int _i = 0; _i < 2; ++_i) \
;         __builtin_amdgcn_global_load_lds((const unsigned*)((const char*)(gbase) + (voff)[_i]), (PG8_LAS unsigned*)(lds + (bufoff) + ldsw + _i * 8192), 16, 0, 0); } while (0)
; #define PG8_LDA(dst, b, h) do { _Pragma("unroll") for (int m = 0; m < 4; ++m) _Pragma("unroll") for (int k = 0; k < 2; ++k) dst[m][k] = *(const PG8_LAS bf16x8*)(lds + PG8_SA(b, h) + aoff + m * 2048 + k * 1024); } while (0)
; #define PG8_LDB(dst, b, h) do { _Pragma("unroll") for (int n = 0; n < 2; ++n) _Pragma("unroll") for (int k = 0; k < 2; ++k) dst[n][k] = *(const PG8_LAS bf16x8*)(lds + PG8_SB(b, h) + boff + n * 2048 + k * 1024); } while (0)
; #define PG8_MMA(ai, bj, At, Bt) do { __builtin_amdgcn_s_setprio(1); _Pragma("unroll") for (int m = 0; m < 4; ++m) _Pragma("unroll") for (int n = 0; n < 2; ++n) _Pragma("unroll") for (int k = 0; k < 2; ++k) \
;         acc[ai][bj][m][n] = __builtin_amdgcn_mfma_f32_16x16x32_bf16(Bt[n][k], At[m][k], acc[ai][bj][m][n], 0, 0, 0); __builtin_amdgcn_s_setprio(0); } while (0)
; #define PG8_WAIT_V(n) asm volatile("s_waitcnt vmcnt(" #n ")" ::: "memory")
; #define PG8_WAIT_L(n) asm volatile("s_waitcnt lgkmcnt(" #n ")" ::: "memory")
; template <class Epi, class Sched, bool ALIGN_EPI = false, bool SP2 = false>
; __device__ __forceinline__ void gemm_phase(PG8_LAS unsigned char* lds, const Gemm g, const Sched& S, const Epi& E) {
;     ...
;             const bool last = (t == nt - 2);
;             const char* a1 = cA + (size_t)(t + 1) * kstep;
;             const char* a2 = last ? nA : cA + (size_t)(t + 2) * kstep; const char* b2 = last ? nB : cB + (size_t)(t + 2) * kstep;
;             const char* a3 = a2 + kstep; const char* b3 = b2 + kstep;
;             if (last && has_next) S.a_ready(nxt);
;             if constexpr (SP2) {
;             PG8_LDB(B0, 0, 0); PG8_LDB(B1, 0, 1); PG8_SCHED; PG8_LDA(At, 0, 0); PG8_STAGE(PG8_SA(1, 1), a1 + hstep, voffA);
;             PG8_WAIT_V(8); PG8_WAIT_L(0); PG8_BAR; PG8_MMA(0, 0, At, B0); PG8_MMA(0, 1, At, B1); PG8_BAR; PG8_SCHED;
;             PG8_LDA(At, 0, 1); PG8_STAGE(PG8_SB(0, 0), b2, voffB); PG8_STAGE(PG8_SB(0, 1), b2 + hstep, voffB); PG8_STAGE(PG8_SA(0, 0), a2, voffA);
;             PG8_WAIT_V(8); PG8_WAIT_L(0); PG8_BAR; PG8_MMA(1, 0, At, B0); PG8_MMA(1, 1, At, B1); PG8_BAR; PG8_SCHED;
.LBB0_798:
	ds_read_b128 v[146:149], v152
	ds_read_b128 v[156:159], v152 offset:1024
	ds_read_b128 v[160:163], v152 offset:2048
	ds_read_b128 v[164:167], v152 offset:3072
	ds_read_b128 v[168:171], v153
	ds_read_b128 v[172:175], v153 offset:1024
	ds_read_b128 v[176:179], v153 offset:2048
	ds_read_b128 v[180:183], v153 offset:3072
	s_add_u32 s46, s44, 0xfffc0080
	s_addc_u32 s47, s45, -1
	s_cmp_eq_u32 s63, 12
	s_cselect_b32 s49, s35, s47
	s_cselect_b32 s48, s41, s46
	s_cselect_b32 s47, s31, s62
	s_cselect_b32 s46, s60, s61
	v_lshl_add_u64 v[218:219], s[44:45], 0, v[138:139]
	s_add_i32 m0, s43, 0xc000
	ds_read_b128 v[184:187], v154
	ds_read_b128 v[188:191], v154 offset:1024
	ds_read_b128 v[192:195], v154 offset:2048
	ds_read_b128 v[196:199], v154 offset:3072
	ds_read_b128 v[200:203], v154 offset:4096
	ds_read_b128 v[206:209], v154 offset:5120
	ds_read_b128 v[210:213], v154 offset:6144
	ds_read_b128 v[214:217], v154 offset:7168
	global_load_lds_dwordx4 v[218:219], off
	v_lshl_add_u64 v[218:219], s[44:45], 0, v[140:141]
	s_add_i32 m0, s43, 0xe000
	s_nop 0
	global_load_lds_dwordx4 v[218:219], off
	s_waitcnt vmcnt(8)
	s_waitcnt lgkmcnt(0)
	s_setprio 1
	s_barrier
	v_mfma_f32_16x16x32_bf16 v[124:127], v[146:149], v[184:187], v[124:127]
	v_mfma_f32_16x16x32_bf16 v[120:123], v[160:163], v[184:187], v[120:123]
	v_mfma_f32_16x16x32_bf16 v[108:111], v[146:149], v[192:195], v[108:111]
	v_mfma_f32_16x16x32_bf16 v[104:107], v[160:163], v[192:195], v[104:107]
	v_mfma_f32_16x16x32_bf16 v[92:95], v[146:149], v[200:203], v[92:95]
	v_mfma_f32_16x16x32_bf16 v[88:91], v[160:163], v[200:203], v[88:91]
	v_mfma_f32_16x16x32_bf16 v[76:79], v[146:149], v[210:213], v[76:79]
	v_mfma_f32_16x16x32_bf16 v[72:75], v[160:163], v[210:213], v[72:75]
	v_mfma_f32_16x16x32_bf16 v[124:127], v[156:159], v[188:191], v[124:127]
	v_mfma_f32_16x16x32_bf16 v[120:123], v[164:167], v[188:191], v[120:123]
	v_mfma_f32_16x16x32_bf16 v[108:111], v[156:159], v[196:199], v[108:111]
	v_mfma_f32_16x16x32_bf16 v[104:107], v[164:167], v[196:199], v[104:107]
	v_mfma_f32_16x16x32_bf16 v[92:95], v[156:159], v[206:209], v[92:95]
	v_mfma_f32_16x16x32_bf16 v[88:91], v[164:167], v[206:209], v[88:91]
	v_mfma_f32_16x16x32_bf16 v[76:79], v[156:159], v[214:217], v[76:79]
	v_mfma_f32_16x16x32_bf16 v[72:75], v[164:167], v[214:217], v[72:75]
	v_mfma_f32_16x16x32_bf16 v[116:119], v[168:171], v[184:187], v[116:119]
	v_mfma_f32_16x16x32_bf16 v[112:115], v[176:179], v[184:187], v[112:115]
	v_mfma_f32_16x16x32_bf16 v[100:103], v[168:171], v[192:195], v[100:103]
	v_mfma_f32_16x16x32_bf16 v[96:99], v[176:179], v[192:195], v[96:99]
	v_mfma_f32_16x16x32_bf16 v[84:87], v[168:171], v[200:203], v[84:87]
	v_mfma_f32_16x16x32_bf16 v[80:83], v[176:179], v[200:203], v[80:83]
	v_mfma_f32_16x16x32_bf16 v[68:71], v[168:171], v[210:213], v[68:71]
	v_mfma_f32_16x16x32_bf16 v[64:67], v[176:179], v[210:213], v[64:67]
	v_mfma_f32_16x16x32_bf16 v[116:119], v[172:175], v[188:191], v[116:119]
	v_mfma_f32_16x16x32_bf16 v[112:115], v[180:183], v[188:191], v[112:115]
	v_mfma_f32_16x16x32_bf16 v[100:103], v[172:175], v[196:199], v[100:103]
	v_mfma_f32_16x16x32_bf16 v[96:99], v[180:183], v[196:199], v[96:99]
	v_mfma_f32_16x16x32_bf16 v[84:87], v[172:175], v[206:209], v[84:87]
	v_mfma_f32_16x16x32_bf16 v[80:83], v[180:183], v[206:209], v[80:83]
	v_mfma_f32_16x16x32_bf16 v[68:71], v[172:175], v[214:217], v[68:71]
	v_mfma_f32_16x16x32_bf16 v[64:67], v[180:183], v[214:217], v[64:67]
	s_setprio 0
	s_barrier
	s_add_i32 s64, s58, s33
	v_lshl_add_u64 v[218:219], s[46:47], 0, v[132:133]
	s_mov_b32 m0, s64
	ds_read_b128 v[184:187], v154 offset:16384
	ds_read_b128 v[188:191], v154 offset:17408
	ds_read_b128 v[192:195], v154 offset:18432
	ds_read_b128 v[196:199], v154 offset:19456
	ds_read_b128 v[200:203], v154 offset:20480
	ds_read_b128 v[206:209], v154 offset:21504
	ds_read_b128 v[210:213], v154 offset:22528
	ds_read_b128 v[214:217], v154 offset:23552
	global_load_lds_dwordx4 v[218:219], off
	s_add_i32 m0, s64, 0x2000
	s_add_u32 s64, s46, 0x40000
	v_lshl_add_u64 v[220:221], s[46:47], 0, v[136:137]
	s_addc_u32 s65, s47, 0
	s_add_i32 s66, s59, s33
	global_load_lds_dwordx4 v[220:221], off
	v_lshl_add_u64 v[222:223], s[64:65], 0, v[132:133]
	s_mov_b32 m0, s66
	v_lshl_add_u64 v[224:225], s[48:49], 0, v[134:135]
	global_load_lds_dwordx4 v[222:223], off
	v_lshl_add_u64 v[222:223], s[64:65], 0, v[136:137]
	s_add_i32 m0, s66, 0x2000
	s_nop 0
	global_load_lds_dwordx4 v[222:223], off
	v_lshl_add_u64 v[222:223], s[48:49], 0, v[130:131]
	s_mov_b32 m0, s43
	s_nop 0
	global_load_lds_dwordx4 v[222:223], off
	s_mov_b32 m0, s50
	s_nop 0
	global_load_lds_dwordx4 v[224:225], off
	s_waitcnt vmcnt(8)
	s_waitcnt lgkmcnt(0)
	s_setprio 1
	s_barrier
; #define PG8_STAGE(bufoff, gbase, voff) do { _Pragma("unroll") for (int _i = 0; _i < 2; ++_i) \
;         __builtin_amdgcn_global_load_lds((const unsigned*)((const char*)(gbase) + (voff)[_i]), (PG8_LAS unsigned*)(lds + (bufoff) + ldsw + _i * 8192), 16, 0, 0); } while (0)
; #define PG8_LDA(dst, b, h) do { _Pragma("unroll") for (int m = 0; m < 4; ++m) _Pragma("unroll") for (int k = 0; k < 2; ++k) dst[m][k] = *(const PG8_LAS bf16x8*)(lds + PG8_SA(b, h) + aoff + m * 2048 + k * 1024); } while (0)
; #define PG8_LDB(dst, b, h) do { _Pragma("unroll") for (int n = 0; n < 2; ++n) _Pragma("unroll") for (int k = 0; k < 2; ++k) dst[n][k] = *(const PG8_LAS bf16x8*)(lds + PG8_SB(b, h) + boff + n * 2048 + k * 1024); } while (0)
; #define PG8_MMA(ai, bj, At, Bt) do { __builtin_amdgcn_s_setprio(1); _Pragma("unroll") for (int m = 0; m < 4; ++m) _Pragma("unroll") for (int n = 0; n < 2; ++n) _Pragma("unroll") for (int k = 0; k < 2; ++k) \
;         acc[ai][bj][m][n] = __builtin_amdgcn_mfma_f32_16x16x32_bf16(Bt[n][k], At[m][k], acc[ai][bj][m][n], 0, 0, 0); __builtin_amdgcn_s_setprio(0); } while (0)
; #define PG8_WAIT_V(n) asm volatile("s_waitcnt vmcnt(" #n ")" ::: "memory")
; #define PG8_WAIT_L(n) asm volatile("s_waitcnt lgkmcnt(" #n ")" ::: "memory")
; #define PG8_BAR __builtin_amdgcn_s_barrier()
; #define PG8_SCHED __builtin_amdgcn_sched_barrier(0)
; template <class Epi, class Sched, bool ALIGN_EPI = false, bool SP2 = false>
; __device__ __forceinline__ void gemm_phase(PG8_LAS unsigned char* lds, const Gemm g, const Sched& S, const Epi& E) {
;     ...
;             PG8_WAIT_V(8); PG8_WAIT_L(0); PG8_BAR; PG8_MMA(1, 0, At, B0); PG8_MMA(1, 1, At, B1); PG8_BAR; PG8_SCHED;
;             PG8_LDB(B0, 1, 0); PG8_LDB(B1, 1, 1); PG8_SCHED; PG8_LDA(At, 1, 0); PG8_STAGE(PG8_SA(0, 1), a2 + hstep, voffA);
;             PG8_WAIT_V(8); PG8_WAIT_L(0); PG8_BAR; PG8_MMA(0, 0, At, B0); PG8_MMA(0, 1, At, B1); PG8_BAR; PG8_SCHED;
	v_mfma_f32_16x16x32_bf16 v[60:63], v[146:149], v[184:187], v[60:63]
	v_mfma_f32_16x16x32_bf16 v[56:59], v[160:163], v[184:187], v[56:59]
	v_mfma_f32_16x16x32_bf16 v[44:47], v[146:149], v[192:195], v[44:47]
	v_mfma_f32_16x16x32_bf16 v[40:43], v[160:163], v[192:195], v[40:43]
	v_mfma_f32_16x16x32_bf16 v[28:31], v[146:149], v[200:203], v[28:31]
	v_mfma_f32_16x16x32_bf16 v[24:27], v[160:163], v[200:203], v[24:27]
	v_mfma_f32_16x16x32_bf16 v[12:15], v[146:149], v[210:213], v[12:15]
	v_mfma_f32_16x16x32_bf16 v[8:11], v[160:163], v[210:213], v[8:11]
	v_mfma_f32_16x16x32_bf16 v[60:63], v[156:159], v[188:191], v[60:63]
	v_mfma_f32_16x16x32_bf16 v[56:59], v[164:167], v[188:191], v[56:59]
	v_mfma_f32_16x16x32_bf16 v[44:47], v[156:159], v[196:199], v[44:47]
	v_mfma_f32_16x16x32_bf16 v[40:43], v[164:167], v[196:199], v[40:43]
	v_mfma_f32_16x16x32_bf16 v[28:31], v[156:159], v[206:209], v[28:31]
	v_mfma_f32_16x16x32_bf16 v[24:27], v[164:167], v[206:209], v[24:27]
	v_mfma_f32_16x16x32_bf16 v[12:15], v[156:159], v[214:217], v[12:15]
	v_mfma_f32_16x16x32_bf16 v[8:11], v[164:167], v[214:217], v[8:11]
	v_mfma_f32_16x16x32_bf16 v[52:55], v[168:171], v[184:187], v[52:55]
	v_mfma_f32_16x16x32_bf16 v[48:51], v[176:179], v[184:187], v[48:51]
	v_mfma_f32_16x16x32_bf16 v[36:39], v[168:171], v[192:195], v[36:39]
	v_mfma_f32_16x16x32_bf16 v[32:35], v[176:179], v[192:195], v[32:35]
	v_mfma_f32_16x16x32_bf16 v[20:23], v[168:171], v[200:203], v[20:23]
	v_mfma_f32_16x16x32_bf16 v[16:19], v[176:179], v[200:203], v[16:19]
	v_mfma_f32_16x16x32_bf16 v[4:7], v[168:171], v[210:213], v[4:7]
	v_mfma_f32_16x16x32_bf16 v[0:3], v[176:179], v[210:213], v[0:3]
	v_mfma_f32_16x16x32_bf16 v[52:55], v[172:175], v[188:191], v[52:55]
	v_mfma_f32_16x16x32_bf16 v[48:51], v[180:183], v[188:191], v[48:51]
	v_mfma_f32_16x16x32_bf16 v[36:39], v[172:175], v[196:199], v[36:39]
	v_mfma_f32_16x16x32_bf16 v[32:35], v[180:183], v[196:199], v[32:35]
	v_mfma_f32_16x16x32_bf16 v[20:23], v[172:175], v[206:209], v[20:23]
	v_mfma_f32_16x16x32_bf16 v[16:19], v[180:183], v[206:209], v[16:19]
	v_mfma_f32_16x16x32_bf16 v[4:7], v[172:175], v[214:217], v[4:7]
	v_mfma_f32_16x16x32_bf16 v[0:3], v[180:183], v[214:217], v[0:3]
	s_setprio 0
	s_barrier
	s_add_i32 s64, 0, 0x18000
	s_add_i32 s65, 0, 0x1c000
	v_add_u32_e32 v164, s64, v150
	v_add_u32_e32 v180, s65, v150
	ds_read_b128 v[146:149], v164
	ds_read_b128 v[156:159], v164 offset:1024
	ds_read_b128 v[160:163], v164 offset:2048
	ds_read_b128 v[164:167], v164 offset:3072
	ds_read_b128 v[168:171], v180
	ds_read_b128 v[172:175], v180 offset:1024
	ds_read_b128 v[176:179], v180 offset:2048
	ds_read_b128 v[180:183], v180 offset:3072
	s_add_u32 s48, s48, 0x40000
	s_addc_u32 s49, s49, 0
	s_mov_b32 m0, s51
	v_lshl_add_u64 v[226:227], s[48:49], 0, v[130:131]
	ds_read_b128 v[184:187], v154 offset:32768
	ds_read_b128 v[188:191], v154 offset:33792
	ds_read_b128 v[192:195], v154 offset:34816
	ds_read_b128 v[196:199], v154 offset:35840
	ds_read_b128 v[200:203], v154 offset:36864
	ds_read_b128 v[206:209], v154 offset:37888
	ds_read_b128 v[210:213], v154 offset:38912
	ds_read_b128 v[214:217], v154 offset:39936
	global_load_lds_dwordx4 v[226:227], off
	v_lshl_add_u64 v[226:227], s[48:49], 0, v[134:135]
	s_mov_b32 m0, s52
	s_nop 0
	global_load_lds_dwordx4 v[226:227], off
	s_waitcnt vmcnt(8)
	s_waitcnt lgkmcnt(0)
	s_setprio 1
	s_barrier
	v_mfma_f32_16x16x32_bf16 v[124:127], v[146:149], v[184:187], v[124:127]
	v_mfma_f32_16x16x32_bf16 v[120:123], v[160:163], v[184:187], v[120:123]
	v_mfma_f32_16x16x32_bf16 v[108:111], v[146:149], v[192:195], v[108:111]
	v_mfma_f32_16x16x32_bf16 v[104:107], v[160:163], v[192:195], v[104:107]
	v_mfma_f32_16x16x32_bf16 v[92:95], v[146:149], v[200:203], v[92:95]
	v_mfma_f32_16x16x32_bf16 v[88:91], v[160:163], v[200:203], v[88:91]
	v_mfma_f32_16x16x32_bf16 v[76:79], v[146:149], v[210:213], v[76:79]
	v_mfma_f32_16x16x32_bf16 v[72:75], v[160:163], v[210:213], v[72:75]
	v_mfma_f32_16x16x32_bf16 v[124:127], v[156:159], v[188:191], v[124:127]
	v_mfma_f32_16x16x32_bf16 v[120:123], v[164:167], v[188:191], v[120:123]
	v_mfma_f32_16x16x32_bf16 v[108:111], v[156:159], v[196:199], v[108:111]
	v_mfma_f32_16x16x32_bf16 v[104:107], v[164:167], v[196:199], v[104:107]
	v_mfma_f32_16x16x32_bf16 v[92:95], v[156:159], v[206:209], v[92:95]
	v_mfma_f32_16x16x32_bf16 v[88:91], v[164:167], v[206:209], v[88:91]
	v_mfma_f32_16x16x32_bf16 v[76:79], v[156:159], v[214:217], v[76:79]
	v_mfma_f32_16x16x32_bf16 v[72:75], v[164:167], v[214:217], v[72:75]
	v_mfma_f32_16x16x32_bf16 v[116:119], v[168:171], v[184:187], v[116:119]
	v_mfma_f32_16x16x32_bf16 v[112:115], v[176:179], v[184:187], v[112:115]
	v_mfma_f32_16x16x32_bf16 v[100:103], v[168:171], v[192:195], v[100:103]
	v_mfma_f32_16x16x32_bf16 v[96:99], v[176:179], v[192:195], v[96:99]
	v_mfma_f32_16x16x32_bf16 v[84:87], v[168:171], v[200:203], v[84:87]
	v_mfma_f32_16x16x32_bf16 v[80:83], v[176:179], v[200:203], v[80:83]
	v_mfma_f32_16x16x32_bf16 v[68:71], v[168:171], v[210:213], v[68:71]
	v_mfma_f32_16x16x32_bf16 v[64:67], v[176:179], v[210:213], v[64:67]
	v_mfma_f32_16x16x32_bf16 v[116:119], v[172:175], v[188:191], v[116:119]
	v_mfma_f32_16x16x32_bf16 v[112:115], v[180:183], v[188:191], v[112:115]
	v_mfma_f32_16x16x32_bf16 v[100:103], v[172:175], v[196:199], v[100:103]
	v_mfma_f32_16x16x32_bf16 v[96:99], v[180:183], v[196:199], v[96:99]
	v_mfma_f32_16x16x32_bf16 v[84:87], v[172:175], v[206:209], v[84:87]
	v_mfma_f32_16x16x32_bf16 v[80:83], v[180:183], v[206:209], v[80:83]
	v_mfma_f32_16x16x32_bf16 v[68:71], v[172:175], v[214:217], v[68:71]
	v_mfma_f32_16x16x32_bf16 v[64:67], v[180:183], v[214:217], v[64:67]
	s_setprio 0
	s_barrier
; #define PG8_STAGE(bufoff, gbase, voff) do { _Pragma("unroll") for (int _i = 0; _i < 2; ++_i) \
;         __builtin_amdgcn_global_load_lds((const unsigned*)((const char*)(gbase) + (voff)[_i]), (PG8_LAS unsigned*)(lds + (bufoff) + ldsw + _i * 8192), 16, 0, 0); } while (0)
; #define PG8_LDA(dst, b, h) do { _Pragma("unroll") for (int m = 0; m < 4; ++m) _Pragma("unroll") for (int k = 0; k < 2; ++k) dst[m][k] = *(const PG8_LAS bf16x8*)(lds + PG8_SA(b, h) + aoff + m * 2048 + k * 1024); } while (0)
; #define PG8_MMA(ai, bj, At, Bt) do { __builtin_amdgcn_s_setprio(1); _Pragma("unroll") for (int m = 0; m < 4; ++m) _Pragma("unroll") for (int n = 0; n < 2; ++n) _Pragma("unroll") for (int k = 0; k < 2; ++k) \
;         acc[ai][bj][m][n] = __builtin_amdgcn_mfma_f32_16x16x32_bf16(Bt[n][k], At[m][k], acc[ai][bj][m][n], 0, 0, 0); __builtin_amdgcn_s_setprio(0); } while (0)
; #define PG8_WAIT_V(n) asm volatile("s_waitcnt vmcnt(" #n ")" ::: "memory")
; #define PG8_WAIT_L(n) asm volatile("s_waitcnt lgkmcnt(" #n ")" ::: "memory")
; #define PG8_BAR __builtin_amdgcn_s_barrier()
; #define PG8_SCHED __builtin_amdgcn_sched_barrier(0)
; template <class Epi, class Sched, bool ALIGN_EPI = false, bool SP2 = false>
; __device__ __forceinline__ void gemm_phase(PG8_LAS unsigned char* lds, const Gemm g, const Sched& S, const Epi& E) {
;     ...
;             PG8_LDA(At, 1, 1); PG8_STAGE(PG8_SB(1, 0), b3, voffB); PG8_STAGE(PG8_SB(1, 1), b3 + hstep, voffB); PG8_STAGE(PG8_SA(1, 0), a3, voffA);
;             PG8_WAIT_V(8); PG8_WAIT_L(0); PG8_BAR; PG8_MMA(1, 0, At, B0); PG8_MMA(1, 1, At, B1); PG8_BAR; PG8_SCHED;
;     ...
;         if constexpr (ALIGN_EPI) { if (wr == 0) PG8_BAR; }
	s_add_i32 s48, s64, s33
	v_lshl_add_u64 v[218:219], v[218:219], 0, s[26:27]
	s_mov_b32 m0, s48
	ds_read_b128 v[184:187], v154 offset:49152
	ds_read_b128 v[188:191], v154 offset:50176
	ds_read_b128 v[192:195], v154 offset:51200
	ds_read_b128 v[196:199], v154 offset:52224
	ds_read_b128 v[200:203], v154 offset:53248
	ds_read_b128 v[206:209], v154 offset:54272
	ds_read_b128 v[210:213], v154 offset:55296
	ds_read_b128 v[214:217], v154 offset:56320
	global_load_lds_dwordx4 v[218:219], off
	s_add_i32 m0, s48, 0x2000
	s_add_u32 s46, s46, 0x40080
	v_lshl_add_u64 v[218:219], v[220:221], 0, s[26:27]
	s_addc_u32 s47, s47, 0
	s_add_i32 s48, s65, s33
	global_load_lds_dwordx4 v[218:219], off
	v_lshl_add_u64 v[218:219], s[46:47], 0, v[132:133]
	s_mov_b32 m0, s48
	s_nop 0
	global_load_lds_dwordx4 v[218:219], off
	v_lshl_add_u64 v[218:219], s[46:47], 0, v[136:137]
	s_add_i32 m0, s48, 0x2000
	s_nop 0
	global_load_lds_dwordx4 v[218:219], off
	v_lshl_add_u64 v[218:219], v[222:223], 0, s[26:27]
	s_mov_b32 m0, s54
	s_nop 0
	global_load_lds_dwordx4 v[218:219], off
	v_lshl_add_u64 v[218:219], v[224:225], 0, s[26:27]
	s_mov_b32 m0, s55
	s_nop 0
	global_load_lds_dwordx4 v[218:219], off
	s_waitcnt vmcnt(8)
	s_waitcnt lgkmcnt(0)
	s_setprio 1
	s_barrier
	v_mfma_f32_16x16x32_bf16 v[60:63], v[146:149], v[184:187], v[60:63]
	v_mfma_f32_16x16x32_bf16 v[56:59], v[160:163], v[184:187], v[56:59]
	v_mfma_f32_16x16x32_bf16 v[44:47], v[146:149], v[192:195], v[44:47]
	v_mfma_f32_16x16x32_bf16 v[40:43], v[160:163], v[192:195], v[40:43]
	v_mfma_f32_16x16x32_bf16 v[28:31], v[146:149], v[200:203], v[28:31]
	v_mfma_f32_16x16x32_bf16 v[24:27], v[160:163], v[200:203], v[24:27]
	v_mfma_f32_16x16x32_bf16 v[12:15], v[146:149], v[210:213], v[12:15]
	v_mfma_f32_16x16x32_bf16 v[8:11], v[160:163], v[210:213], v[8:11]
	v_mfma_f32_16x16x32_bf16 v[60:63], v[156:159], v[188:191], v[60:63]
	v_mfma_f32_16x16x32_bf16 v[56:59], v[164:167], v[188:191], v[56:59]
	v_mfma_f32_16x16x32_bf16 v[44:47], v[156:159], v[196:199], v[44:47]
	v_mfma_f32_16x16x32_bf16 v[40:43], v[164:167], v[196:199], v[40:43]
	v_mfma_f32_16x16x32_bf16 v[28:31], v[156:159], v[206:209], v[28:31]
	v_mfma_f32_16x16x32_bf16 v[24:27], v[164:167], v[206:209], v[24:27]
	v_mfma_f32_16x16x32_bf16 v[12:15], v[156:159], v[214:217], v[12:15]
	v_mfma_f32_16x16x32_bf16 v[8:11], v[164:167], v[214:217], v[8:11]
	v_mfma_f32_16x16x32_bf16 v[52:55], v[168:171], v[184:187], v[52:55]
	v_mfma_f32_16x16x32_bf16 v[48:51], v[176:179], v[184:187], v[48:51]
	v_mfma_f32_16x16x32_bf16 v[36:39], v[168:171], v[192:195], v[36:39]
	v_mfma_f32_16x16x32_bf16 v[32:35], v[176:179], v[192:195], v[32:35]
	v_mfma_f32_16x16x32_bf16 v[20:23], v[168:171], v[200:203], v[20:23]
	v_mfma_f32_16x16x32_bf16 v[16:19], v[176:179], v[200:203], v[16:19]
	v_mfma_f32_16x16x32_bf16 v[4:7], v[168:171], v[210:213], v[4:7]
	v_mfma_f32_16x16x32_bf16 v[0:3], v[176:179], v[210:213], v[0:3]
	v_mfma_f32_16x16x32_bf16 v[52:55], v[172:175], v[188:191], v[52:55]
	v_mfma_f32_16x16x32_bf16 v[48:51], v[180:183], v[188:191], v[48:51]
	v_mfma_f32_16x16x32_bf16 v[36:39], v[172:175], v[196:199], v[36:39]
	v_mfma_f32_16x16x32_bf16 v[32:35], v[180:183], v[196:199], v[32:35]
	v_mfma_f32_16x16x32_bf16 v[20:23], v[172:175], v[206:209], v[20:23]
	v_mfma_f32_16x16x32_bf16 v[16:19], v[180:183], v[206:209], v[16:19]
	v_mfma_f32_16x16x32_bf16 v[4:7], v[172:175], v[214:217], v[4:7]
	v_mfma_f32_16x16x32_bf16 v[0:3], v[180:183], v[214:217], v[0:3]
	s_setprio 0
	s_barrier
	s_add_i32 s63, s63, 2
	s_add_u32 s44, s44, 0x100
	s_addc_u32 s45, s45, 0
	s_add_u32 s61, s61, 0x100
	s_addc_u32 s62, s62, 0
	s_cmp_gt_u32 s63, 13
	s_cbranch_scc0 .LBB0_798
	s_and_b64 vcc, exec, s[28:29]
	s_cbranch_vccz .LBB0_801
	s_barrier

; #define PG8_STAGE(bufoff, gbase, voff) do { _Pragma("unroll") for (int _i = 0; _i < 2; ++_i) \
;         __builtin_amdgcn_global_load_lds((const unsigned*)((const char*)(gbase) + (voff)[_i]), (PG8_LAS unsigned*)(lds + (bufoff) + ldsw + _i * 8192), 16, 0, 0); } while (0)
; #define PG8_LDA(dst, b, h) do { _Pragma("unroll") for (int m = 0; m < 4; ++m) _Pragma("unroll") for (int k = 0; k < 2; ++k) dst[m][k] = *(const PG8_LAS bf16x8*)(lds + PG8_SA(b, h) + aoff + m * 2048 + k * 1024); } while (0)
; #define PG8_LDB(dst, b, h) do { _Pragma("unroll") for (int n = 0; n < 2; ++n) _Pragma("unroll") for (int k = 0; k < 2; ++k) dst[n][k] = *(const PG8_LAS bf16x8*)(lds + PG8_SB(b, h) + boff + n * 2048 + k * 1024); } while (0)
; #define PG8_MMA(ai, bj, At, Bt) do { __builtin_amdgcn_s_setprio(1); _Pragma("unroll") for (int m = 0; m < 4; ++m) _Pragma("unroll") for (int n = 0; n < 2; ++n) _Pragma("unroll") for (int k = 0; k < 2; ++k) \
;         acc[ai][bj][m][n] = __builtin_amdgcn_mfma_f32_16x16x32_bf16(Bt[n][k], At[m][k], acc[ai][bj][m][n], 0, 0, 0); __builtin_amdgcn_s_setprio(0); } while (0)
; #define PG8_WAIT_V(n) asm volatile("s_waitcnt vmcnt(" #n ")" ::: "memory")
; #define PG8_WAIT_L(n) asm volatile("s_waitcnt lgkmcnt(" #n ")" ::: "memory")
; template <class Epi, class Sched, bool ALIGN_EPI = false, bool SP2 = false>
; __device__ __forceinline__ void gemm_phase(PG8_LAS unsigned char* lds, const Gemm g, const Sched& S, const Epi& E) {
;     ...
;             const bool last = (t == nt - 2);
;             const char* a1 = cA + (size_t)(t + 1) * kstep;
;             const char* a2 = last ? nA : cA + (size_t)(t + 2) * kstep; const char* b2 = last ? nB : cB + (size_t)(t + 2) * kstep;
;             const char* a3 = a2 + kstep; const char* b3 = b2 + kstep;
;             if (last && has_next) S.a_ready(nxt);
;             if constexpr (SP2) {
;             PG8_LDB(B0, 0, 0); PG8_LDB(B1, 0, 1); PG8_SCHED; PG8_LDA(At, 0, 0); PG8_STAGE(PG8_SA(1, 1), a1 + hstep, voffA);
;             PG8_WAIT_V(8); PG8_WAIT_L(0); PG8_BAR; PG8_MMA(0, 0, At, B0); PG8_MMA(0, 1, At, B1); PG8_BAR; PG8_SCHED;
;             PG8_LDA(At, 0, 1); PG8_STAGE(PG8_SB(0, 0), b2, voffB); PG8_STAGE(PG8_SB(0, 1), b2 + hstep, voffB); PG8_STAGE(PG8_SA(0, 0), a2, voffA);
;             PG8_WAIT_V(8); PG8_WAIT_L(0); PG8_BAR; PG8_MMA(1, 0, At, B0); PG8_MMA(1, 1, At, B1); PG8_BAR; PG8_SCHED;
.LBB0_905:
	ds_read_b128 v[146:149], v151
	ds_read_b128 v[156:159], v151 offset:1024
	ds_read_b128 v[160:163], v151 offset:2048
	ds_read_b128 v[164:167], v151 offset:3072
	ds_read_b128 v[168:171], v152
	ds_read_b128 v[172:175], v152 offset:1024
	ds_read_b128 v[176:179], v152 offset:2048
	ds_read_b128 v[180:183], v152 offset:3072
	s_add_u32 s42, s40, 0xfffc0080
	s_addc_u32 s43, s41, -1
	s_cmp_eq_u32 s62, 12
	s_cselect_b32 s45, s35, s43
	s_cselect_b32 s44, s58, s42
	s_cselect_b32 s43, s31, s61
	s_cselect_b32 s42, s59, s60
	v_lshl_add_u64 v[218:219], s[40:41], 0, v[138:139]
	s_add_i32 m0, s46, 0xc000
	ds_read_b128 v[184:187], v153
	ds_read_b128 v[188:191], v153 offset:1024
	ds_read_b128 v[192:195], v153 offset:2048
	ds_read_b128 v[196:199], v153 offset:3072
	ds_read_b128 v[200:203], v153 offset:4096
	ds_read_b128 v[206:209], v153 offset:5120
	ds_read_b128 v[210:213], v153 offset:6144
	ds_read_b128 v[214:217], v153 offset:7168
	global_load_lds_dwordx4 v[218:219], off
	v_lshl_add_u64 v[218:219], s[40:41], 0, v[140:141]
	s_add_i32 m0, s46, 0xe000
	s_nop 0
	global_load_lds_dwordx4 v[218:219], off
	s_waitcnt vmcnt(8)
	s_waitcnt lgkmcnt(0)
	s_setprio 1
	s_barrier
	v_mfma_f32_16x16x32_bf16 v[124:127], v[146:149], v[184:187], v[124:127]
	v_mfma_f32_16x16x32_bf16 v[120:123], v[160:163], v[184:187], v[120:123]
	v_mfma_f32_16x16x32_bf16 v[108:111], v[146:149], v[192:195], v[108:111]
	v_mfma_f32_16x16x32_bf16 v[104:107], v[160:163], v[192:195], v[104:107]
	v_mfma_f32_16x16x32_bf16 v[92:95], v[146:149], v[200:203], v[92:95]
	v_mfma_f32_16x16x32_bf16 v[88:91], v[160:163], v[200:203], v[88:91]
	v_mfma_f32_16x16x32_bf16 v[76:79], v[146:149], v[210:213], v[76:79]
	v_mfma_f32_16x16x32_bf16 v[72:75], v[160:163], v[210:213], v[72:75]
	v_mfma_f32_16x16x32_bf16 v[124:127], v[156:159], v[188:191], v[124:127]
	v_mfma_f32_16x16x32_bf16 v[120:123], v[164:167], v[188:191], v[120:123]
	v_mfma_f32_16x16x32_bf16 v[108:111], v[156:159], v[196:199], v[108:111]
	v_mfma_f32_16x16x32_bf16 v[104:107], v[164:167], v[196:199], v[104:107]
	v_mfma_f32_16x16x32_bf16 v[92:95], v[156:159], v[206:209], v[92:95]
	v_mfma_f32_16x16x32_bf16 v[88:91], v[164:167], v[206:209], v[88:91]
	v_mfma_f32_16x16x32_bf16 v[76:79], v[156:159], v[214:217], v[76:79]
	v_mfma_f32_16x16x32_bf16 v[72:75], v[164:167], v[214:217], v[72:75]
	v_mfma_f32_16x16x32_bf16 v[116:119], v[168:171], v[184:187], v[116:119]
	v_mfma_f32_16x16x32_bf16 v[112:115], v[176:179], v[184:187], v[112:115]
	v_mfma_f32_16x16x32_bf16 v[100:103], v[168:171], v[192:195], v[100:103]
	v_mfma_f32_16x16x32_bf16 v[96:99], v[176:179], v[192:195], v[96:99]
	v_mfma_f32_16x16x32_bf16 v[84:87], v[168:171], v[200:203], v[84:87]
	v_mfma_f32_16x16x32_bf16 v[80:83], v[176:179], v[200:203], v[80:83]
	v_mfma_f32_16x16x32_bf16 v[68:71], v[168:171], v[210:213], v[68:71]
	v_mfma_f32_16x16x32_bf16 v[64:67], v[176:179], v[210:213], v[64:67]
	v_mfma_f32_16x16x32_bf16 v[116:119], v[172:175], v[188:191], v[116:119]
	v_mfma_f32_16x16x32_bf16 v[112:115], v[180:183], v[188:191], v[112:115]
	v_mfma_f32_16x16x32_bf16 v[100:103], v[172:175], v[196:199], v[100:103]
	v_mfma_f32_16x16x32_bf16 v[96:99], v[180:183], v[196:199], v[96:99]
	v_mfma_f32_16x16x32_bf16 v[84:87], v[172:175], v[206:209], v[84:87]
	v_mfma_f32_16x16x32_bf16 v[80:83], v[180:183], v[206:209], v[80:83]
	v_mfma_f32_16x16x32_bf16 v[68:71], v[172:175], v[214:217], v[68:71]
	v_mfma_f32_16x16x32_bf16 v[64:67], v[180:183], v[214:217], v[64:67]
	s_setprio 0
	s_barrier
	s_add_i32 s63, s55, s33
	v_lshl_add_u64 v[218:219], s[42:43], 0, v[132:133]
	s_mov_b32 m0, s63
	ds_read_b128 v[184:187], v153 offset:16384
	ds_read_b128 v[188:191], v153 offset:17408
	ds_read_b128 v[192:195], v153 offset:18432
	ds_read_b128 v[196:199], v153 offset:19456
	ds_read_b128 v[200:203], v153 offset:20480
	ds_read_b128 v[206:209], v153 offset:21504
	ds_read_b128 v[210:213], v153 offset:22528
	ds_read_b128 v[214:217], v153 offset:23552
	global_load_lds_dwordx4 v[218:219], off
	s_add_i32 m0, s63, 0x2000
	s_add_u32 s64, s42, 0x40000
	v_lshl_add_u64 v[220:221], s[42:43], 0, v[136:137]
	s_addc_u32 s65, s43, 0
	s_add_i32 s63, s56, s33
	global_load_lds_dwordx4 v[220:221], off
	v_lshl_add_u64 v[222:223], s[64:65], 0, v[132:133]
	s_mov_b32 m0, s63
	v_lshl_add_u64 v[224:225], s[44:45], 0, v[134:135]
	global_load_lds_dwordx4 v[222:223], off
	v_lshl_add_u64 v[222:223], s[64:65], 0, v[136:137]
	s_add_i32 m0, s63, 0x2000
	s_nop 0
	global_load_lds_dwordx4 v[222:223], off
	v_lshl_add_u64 v[222:223], s[44:45], 0, v[130:131]
	s_mov_b32 m0, s46
	s_nop 0
	global_load_lds_dwordx4 v[222:223], off
	s_mov_b32 m0, s47
	s_nop 0
	global_load_lds_dwordx4 v[224:225], off
	s_waitcnt vmcnt(8)
	s_waitcnt lgkmcnt(0)
	s_setprio 1
	s_barrier
; #define PG8_STAGE(bufoff, gbase, voff) do { _Pragma("unroll") for (int _i = 0; _i < 2; ++_i) \
;         __builtin_amdgcn_global_load_lds((const unsigned*)((const char*)(gbase) + (voff)[_i]), (PG8_LAS unsigned*)(lds + (bufoff) + ldsw + _i * 8192), 16, 0, 0); } while (0)
; #define PG8_LDA(dst, b, h) do { _Pragma("unroll") for (int m = 0; m < 4; ++m) _Pragma("unroll") for (int k = 0; k < 2; ++k) dst[m][k] = *(const PG8_LAS bf16x8*)(lds + PG8_SA(b, h) + aoff + m * 2048 + k * 1024); } while (0)
; #define PG8_LDB(dst, b, h) do { _Pragma("unroll") for (int n = 0; n < 2; ++n) _Pragma("unroll") for (int k = 0; k < 2; ++k) dst[n][k] = *(const PG8_LAS bf16x8*)(lds + PG8_SB(b, h) + boff + n * 2048 + k * 1024); } while (0)
; #define PG8_MMA(ai, bj, At, Bt) do { __builtin_amdgcn_s_setprio(1); _Pragma("unroll") for (int m = 0; m < 4; ++m) _Pragma("unroll") for (int n = 0; n < 2; ++n) _Pragma("unroll") for (int k = 0; k < 2; ++k) \
;         acc[ai][bj][m][n] = __builtin_amdgcn_mfma_f32_16x16x32_bf16(Bt[n][k], At[m][k], acc[ai][bj][m][n], 0, 0, 0); __builtin_amdgcn_s_setprio(0); } while (0)
; #define PG8_WAIT_V(n) asm volatile("s_waitcnt vmcnt(" #n ")" ::: "memory")
; #define PG8_WAIT_L(n) asm volatile("s_waitcnt lgkmcnt(" #n ")" ::: "memory")
; #define PG8_BAR __builtin_amdgcn_s_barrier()
; #define PG8_SCHED __builtin_amdgcn_sched_barrier(0)
; template <class Epi, class Sched, bool ALIGN_EPI = false, bool SP2 = false>
; __device__ __forceinline__ void gemm_phase(PG8_LAS unsigned char* lds, const Gemm g, const Sched& S, const Epi& E) {
;     ...
;             PG8_WAIT_V(8); PG8_WAIT_L(0); PG8_BAR; PG8_MMA(1, 0, At, B0); PG8_MMA(1, 1, At, B1); PG8_BAR; PG8_SCHED;
;             PG8_LDB(B0, 1, 0); PG8_LDB(B1, 1, 1); PG8_SCHED; PG8_LDA(At, 1, 0); PG8_STAGE(PG8_SA(0, 1), a2 + hstep, voffA);
;             PG8_WAIT_V(8); PG8_WAIT_L(0); PG8_BAR; PG8_MMA(0, 0, At, B0); PG8_MMA(0, 1, At, B1); PG8_BAR; PG8_SCHED;
	v_mfma_f32_16x16x32_bf16 v[60:63], v[146:149], v[184:187], v[60:63]
	v_mfma_f32_16x16x32_bf16 v[56:59], v[160:163], v[184:187], v[56:59]
	v_mfma_f32_16x16x32_bf16 v[44:47], v[146:149], v[192:195], v[44:47]
	v_mfma_f32_16x16x32_bf16 v[40:43], v[160:163], v[192:195], v[40:43]
	v_mfma_f32_16x16x32_bf16 v[28:31], v[146:149], v[200:203], v[28:31]
	v_mfma_f32_16x16x32_bf16 v[24:27], v[160:163], v[200:203], v[24:27]
	v_mfma_f32_16x16x32_bf16 v[12:15], v[146:149], v[210:213], v[12:15]
	v_mfma_f32_16x16x32_bf16 v[8:11], v[160:163], v[210:213], v[8:11]
	v_mfma_f32_16x16x32_bf16 v[60:63], v[156:159], v[188:191], v[60:63]
	v_mfma_f32_16x16x32_bf16 v[56:59], v[164:167], v[188:191], v[56:59]
	v_mfma_f32_16x16x32_bf16 v[44:47], v[156:159], v[196:199], v[44:47]
	v_mfma_f32_16x16x32_bf16 v[40:43], v[164:167], v[196:199], v[40:43]
	v_mfma_f32_16x16x32_bf16 v[28:31], v[156:159], v[206:209], v[28:31]
	v_mfma_f32_16x16x32_bf16 v[24:27], v[164:167], v[206:209], v[24:27]
	v_mfma_f32_16x16x32_bf16 v[12:15], v[156:159], v[214:217], v[12:15]
	v_mfma_f32_16x16x32_bf16 v[8:11], v[164:167], v[214:217], v[8:11]
	v_mfma_f32_16x16x32_bf16 v[52:55], v[168:171], v[184:187], v[52:55]
	v_mfma_f32_16x16x32_bf16 v[48:51], v[176:179], v[184:187], v[48:51]
	v_mfma_f32_16x16x32_bf16 v[36:39], v[168:171], v[192:195], v[36:39]
	v_mfma_f32_16x16x32_bf16 v[32:35], v[176:179], v[192:195], v[32:35]
	v_mfma_f32_16x16x32_bf16 v[20:23], v[168:171], v[200:203], v[20:23]
	v_mfma_f32_16x16x32_bf16 v[16:19], v[176:179], v[200:203], v[16:19]
	v_mfma_f32_16x16x32_bf16 v[4:7], v[168:171], v[210:213], v[4:7]
	v_mfma_f32_16x16x32_bf16 v[0:3], v[176:179], v[210:213], v[0:3]
	v_mfma_f32_16x16x32_bf16 v[52:55], v[172:175], v[188:191], v[52:55]
	v_mfma_f32_16x16x32_bf16 v[48:51], v[180:183], v[188:191], v[48:51]
	v_mfma_f32_16x16x32_bf16 v[36:39], v[172:175], v[196:199], v[36:39]
	v_mfma_f32_16x16x32_bf16 v[32:35], v[180:183], v[196:199], v[32:35]
	v_mfma_f32_16x16x32_bf16 v[20:23], v[172:175], v[206:209], v[20:23]
	v_mfma_f32_16x16x32_bf16 v[16:19], v[180:183], v[206:209], v[16:19]
	v_mfma_f32_16x16x32_bf16 v[4:7], v[172:175], v[214:217], v[4:7]
	v_mfma_f32_16x16x32_bf16 v[0:3], v[180:183], v[214:217], v[0:3]
	s_setprio 0
	s_barrier
	s_add_i32 s63, 0, 0x18000
	s_add_i32 s64, 0, 0x1c000
	v_add_u32_e32 v164, s63, v150
	v_add_u32_e32 v180, s64, v150
	ds_read_b128 v[146:149], v164
	ds_read_b128 v[156:159], v164 offset:1024
	ds_read_b128 v[160:163], v164 offset:2048
	ds_read_b128 v[164:167], v164 offset:3072
	ds_read_b128 v[168:171], v180
	ds_read_b128 v[172:175], v180 offset:1024
	ds_read_b128 v[176:179], v180 offset:2048
	ds_read_b128 v[180:183], v180 offset:3072
	s_add_u32 s44, s44, 0x40000
	s_addc_u32 s45, s45, 0
	s_mov_b32 m0, s48
	v_lshl_add_u64 v[226:227], s[44:45], 0, v[130:131]
	ds_read_b128 v[184:187], v153 offset:32768
	ds_read_b128 v[188:191], v153 offset:33792
	ds_read_b128 v[192:195], v153 offset:34816
	ds_read_b128 v[196:199], v153 offset:35840
	ds_read_b128 v[200:203], v153 offset:36864
	ds_read_b128 v[206:209], v153 offset:37888
	ds_read_b128 v[210:213], v153 offset:38912
	ds_read_b128 v[214:217], v153 offset:39936
	global_load_lds_dwordx4 v[226:227], off
	v_lshl_add_u64 v[226:227], s[44:45], 0, v[134:135]
	s_mov_b32 m0, s49
	s_nop 0
	global_load_lds_dwordx4 v[226:227], off
	s_waitcnt vmcnt(8)
	s_waitcnt lgkmcnt(0)
	s_setprio 1
	s_barrier
	v_mfma_f32_16x16x32_bf16 v[124:127], v[146:149], v[184:187], v[124:127]
	v_mfma_f32_16x16x32_bf16 v[120:123], v[160:163], v[184:187], v[120:123]
	v_mfma_f32_16x16x32_bf16 v[108:111], v[146:149], v[192:195], v[108:111]
	v_mfma_f32_16x16x32_bf16 v[104:107], v[160:163], v[192:195], v[104:107]
	v_mfma_f32_16x16x32_bf16 v[92:95], v[146:149], v[200:203], v[92:95]
	v_mfma_f32_16x16x32_bf16 v[88:91], v[160:163], v[200:203], v[88:91]
	v_mfma_f32_16x16x32_bf16 v[76:79], v[146:149], v[210:213], v[76:79]
	v_mfma_f32_16x16x32_bf16 v[72:75], v[160:163], v[210:213], v[72:75]
	v_mfma_f32_16x16x32_bf16 v[124:127], v[156:159], v[188:191], v[124:127]
	v_mfma_f32_16x16x32_bf16 v[120:123], v[164:167], v[188:191], v[120:123]
	v_mfma_f32_16x16x32_bf16 v[108:111], v[156:159], v[196:199], v[108:111]
	v_mfma_f32_16x16x32_bf16 v[104:107], v[164:167], v[196:199], v[104:107]
	v_mfma_f32_16x16x32_bf16 v[92:95], v[156:159], v[206:209], v[92:95]
	v_mfma_f32_16x16x32_bf16 v[88:91], v[164:167], v[206:209], v[88:91]
	v_mfma_f32_16x16x32_bf16 v[76:79], v[156:159], v[214:217], v[76:79]
	v_mfma_f32_16x16x32_bf16 v[72:75], v[164:167], v[214:217], v[72:75]
	v_mfma_f32_16x16x32_bf16 v[116:119], v[168:171], v[184:187], v[116:119]
	v_mfma_f32_16x16x32_bf16 v[112:115], v[176:179], v[184:187], v[112:115]
	v_mfma_f32_16x16x32_bf16 v[100:103], v[168:171], v[192:195], v[100:103]
	v_mfma_f32_16x16x32_bf16 v[96:99], v[176:179], v[192:195], v[96:99]
	v_mfma_f32_16x16x32_bf16 v[84:87], v[168:171], v[200:203], v[84:87]
	v_mfma_f32_16x16x32_bf16 v[80:83], v[176:179], v[200:203], v[80:83]
	v_mfma_f32_16x16x32_bf16 v[68:71], v[168:171], v[210:213], v[68:71]
	v_mfma_f32_16x16x32_bf16 v[64:67], v[176:179], v[210:213], v[64:67]
	v_mfma_f32_16x16x32_bf16 v[116:119], v[172:175], v[188:191], v[116:119]
	v_mfma_f32_16x16x32_bf16 v[112:115], v[180:183], v[188:191], v[112:115]
	v_mfma_f32_16x16x32_bf16 v[100:103], v[172:175], v[196:199], v[100:103]
	v_mfma_f32_16x16x32_bf16 v[96:99], v[180:183], v[196:199], v[96:99]
	v_mfma_f32_16x16x32_bf16 v[84:87], v[172:175], v[206:209], v[84:87]
	v_mfma_f32_16x16x32_bf16 v[80:83], v[180:183], v[206:209], v[80:83]
	v_mfma_f32_16x16x32_bf16 v[68:71], v[172:175], v[214:217], v[68:71]
	v_mfma_f32_16x16x32_bf16 v[64:67], v[180:183], v[214:217], v[64:67]
	s_setprio 0
	s_barrier
; #define PG8_STAGE(bufoff, gbase, voff) do { _Pragma("unroll") for (int _i = 0; _i < 2; ++_i) \
;         __builtin_amdgcn_global_load_lds((const unsigned*)((const char*)(gbase) + (voff)[_i]), (PG8_LAS unsigned*)(lds + (bufoff) + ldsw + _i * 8192), 16, 0, 0); } while (0)
; #define PG8_LDA(dst, b, h) do { _Pragma("unroll") for (int m = 0; m < 4; ++m) _Pragma("unroll") for (int k = 0; k < 2; ++k) dst[m][k] = *(const PG8_LAS bf16x8*)(lds + PG8_SA(b, h) + aoff + m * 2048 + k * 1024); } while (0)
; #define PG8_MMA(ai, bj, At, Bt) do { __builtin_amdgcn_s_setprio(1); _Pragma("unroll") for (int m = 0; m < 4; ++m) _Pragma("unroll") for (int n = 0; n < 2; ++n) _Pragma("unroll") for (int k = 0; k < 2; ++k) \
;         acc[ai][bj][m][n] = __builtin_amdgcn_mfma_f32_16x16x32_bf16(Bt[n][k], At[m][k], acc[ai][bj][m][n], 0, 0, 0); __builtin_amdgcn_s_setprio(0); } while (0)
; #define PG8_WAIT_V(n) asm volatile("s_waitcnt vmcnt(" #n ")" ::: "memory")
; #define PG8_WAIT_L(n) asm volatile("s_waitcnt lgkmcnt(" #n ")" ::: "memory")
; #define PG8_BAR __builtin_amdgcn_s_barrier()
; #define PG8_SCHED __builtin_amdgcn_sched_barrier(0)
; template <class Epi, class Sched, bool ALIGN_EPI = false, bool SP2 = false>
; __device__ __forceinline__ void gemm_phase(PG8_LAS unsigned char* lds, const Gemm g, const Sched& S, const Epi& E) {
;     ...
;             PG8_LDA(At, 1, 1); PG8_STAGE(PG8_SB(1, 0), b3, voffB); PG8_STAGE(PG8_SB(1, 1), b3 + hstep, voffB); PG8_STAGE(PG8_SA(1, 0), a3, voffA);
;             PG8_WAIT_V(8); PG8_WAIT_L(0); PG8_BAR; PG8_MMA(1, 0, At, B0); PG8_MMA(1, 1, At, B1); PG8_BAR; PG8_SCHED;
;     ...
;         if constexpr (ALIGN_EPI) { if (wr == 0) PG8_BAR; }
	s_add_i32 s44, s63, s33
	v_lshl_add_u64 v[218:219], v[218:219], 0, s[26:27]
	s_mov_b32 m0, s44
	ds_read_b128 v[184:187], v153 offset:49152
	ds_read_b128 v[188:191], v153 offset:50176
	ds_read_b128 v[192:195], v153 offset:51200
	ds_read_b128 v[196:199], v153 offset:52224
	ds_read_b128 v[200:203], v153 offset:53248
	ds_read_b128 v[206:209], v153 offset:54272
	ds_read_b128 v[210:213], v153 offset:55296
	ds_read_b128 v[214:217], v153 offset:56320
	global_load_lds_dwordx4 v[218:219], off
	s_add_i32 m0, s44, 0x2000
	s_add_u32 s42, s42, 0x40080
	v_lshl_add_u64 v[218:219], v[220:221], 0, s[26:27]
	s_addc_u32 s43, s43, 0
	s_add_i32 s44, s64, s33
	global_load_lds_dwordx4 v[218:219], off
	v_lshl_add_u64 v[218:219], s[42:43], 0, v[132:133]
	s_mov_b32 m0, s44
	s_nop 0
	global_load_lds_dwordx4 v[218:219], off
	v_lshl_add_u64 v[218:219], s[42:43], 0, v[136:137]
	s_add_i32 m0, s44, 0x2000
	s_nop 0
	global_load_lds_dwordx4 v[218:219], off
	v_lshl_add_u64 v[218:219], v[222:223], 0, s[26:27]
	s_mov_b32 m0, s52
	s_nop 0
	global_load_lds_dwordx4 v[218:219], off
	v_lshl_add_u64 v[218:219], v[224:225], 0, s[26:27]
	s_mov_b32 m0, s53
	s_nop 0
	global_load_lds_dwordx4 v[218:219], off
	s_waitcnt vmcnt(8)
	s_waitcnt lgkmcnt(0)
	s_setprio 1
	s_barrier
	v_mfma_f32_16x16x32_bf16 v[60:63], v[146:149], v[184:187], v[60:63]
	v_mfma_f32_16x16x32_bf16 v[56:59], v[160:163], v[184:187], v[56:59]
	v_mfma_f32_16x16x32_bf16 v[44:47], v[146:149], v[192:195], v[44:47]
	v_mfma_f32_16x16x32_bf16 v[40:43], v[160:163], v[192:195], v[40:43]
	v_mfma_f32_16x16x32_bf16 v[28:31], v[146:149], v[200:203], v[28:31]
	v_mfma_f32_16x16x32_bf16 v[24:27], v[160:163], v[200:203], v[24:27]
	v_mfma_f32_16x16x32_bf16 v[12:15], v[146:149], v[210:213], v[12:15]
	v_mfma_f32_16x16x32_bf16 v[8:11], v[160:163], v[210:213], v[8:11]
	v_mfma_f32_16x16x32_bf16 v[60:63], v[156:159], v[188:191], v[60:63]
	v_mfma_f32_16x16x32_bf16 v[56:59], v[164:167], v[188:191], v[56:59]
	v_mfma_f32_16x16x32_bf16 v[44:47], v[156:159], v[196:199], v[44:47]
	v_mfma_f32_16x16x32_bf16 v[40:43], v[164:167], v[196:199], v[40:43]
	v_mfma_f32_16x16x32_bf16 v[28:31], v[156:159], v[206:209], v[28:31]
	v_mfma_f32_16x16x32_bf16 v[24:27], v[164:167], v[206:209], v[24:27]
	v_mfma_f32_16x16x32_bf16 v[12:15], v[156:159], v[214:217], v[12:15]
	v_mfma_f32_16x16x32_bf16 v[8:11], v[164:167], v[214:217], v[8:11]
	v_mfma_f32_16x16x32_bf16 v[52:55], v[168:171], v[184:187], v[52:55]
	v_mfma_f32_16x16x32_bf16 v[48:51], v[176:179], v[184:187], v[48:51]
	v_mfma_f32_16x16x32_bf16 v[36:39], v[168:171], v[192:195], v[36:39]
	v_mfma_f32_16x16x32_bf16 v[32:35], v[176:179], v[192:195], v[32:35]
	v_mfma_f32_16x16x32_bf16 v[20:23], v[168:171], v[200:203], v[20:23]
	v_mfma_f32_16x16x32_bf16 v[16:19], v[176:179], v[200:203], v[16:19]
	v_mfma_f32_16x16x32_bf16 v[4:7], v[168:171], v[210:213], v[4:7]
	v_mfma_f32_16x16x32_bf16 v[0:3], v[176:179], v[210:213], v[0:3]
	v_mfma_f32_16x16x32_bf16 v[52:55], v[172:175], v[188:191], v[52:55]
	v_mfma_f32_16x16x32_bf16 v[48:51], v[180:183], v[188:191], v[48:51]
	v_mfma_f32_16x16x32_bf16 v[36:39], v[172:175], v[196:199], v[36:39]
	v_mfma_f32_16x16x32_bf16 v[32:35], v[180:183], v[196:199], v[32:35]
	v_mfma_f32_16x16x32_bf16 v[20:23], v[172:175], v[206:209], v[20:23]
	v_mfma_f32_16x16x32_bf16 v[16:19], v[180:183], v[206:209], v[16:19]
	v_mfma_f32_16x16x32_bf16 v[4:7], v[172:175], v[214:217], v[4:7]
	v_mfma_f32_16x16x32_bf16 v[0:3], v[180:183], v[214:217], v[0:3]
	s_setprio 0
	s_barrier
	s_add_i32 s62, s62, 2
	s_add_u32 s40, s40, 0x100
	s_addc_u32 s41, s41, 0
	s_add_u32 s60, s60, 0x100
	s_addc_u32 s61, s61, 0
	s_cmp_gt_u32 s62, 13
	s_cbranch_scc0 .LBB0_905
	s_and_b64 vcc, exec, s[28:29]
	s_cbranch_vccz .LBB0_908
	s_barrier

; #define PG8_STAGE(bufoff, gbase, voff) do { _Pragma("unroll") for (int _i = 0; _i < 2; ++_i) \
;         __builtin_amdgcn_global_load_lds((const unsigned*)((const char*)(gbase) + (voff)[_i]), (PG8_LAS unsigned*)(lds + (bufoff) + ldsw + _i * 8192), 16, 0, 0); } while (0)
; #define PG8_LDA(dst, b, h) do { _Pragma("unroll") for (int m = 0; m < 4; ++m) _Pragma("unroll") for (int k = 0; k < 2; ++k) dst[m][k] = *(const PG8_LAS bf16x8*)(lds + PG8_SA(b, h) + aoff + m * 2048 + k * 1024); } while (0)
; #define PG8_LDB(dst, b, h) do { _Pragma("unroll") for (int n = 0; n < 2; ++n) _Pragma("unroll") for (int k = 0; k < 2; ++k) dst[n][k] = *(const PG8_LAS bf16x8*)(lds + PG8_SB(b, h) + boff + n * 2048 + k * 1024); } while (0)
; #define PG8_MMA(ai, bj, At, Bt) do { __builtin_amdgcn_s_setprio(1); _Pragma("unroll") for (int m = 0; m < 4; ++m) _Pragma("unroll") for (int n = 0; n < 2; ++n) _Pragma("unroll") for (int k = 0; k < 2; ++k) \
;         acc[ai][bj][m][n] = __builtin_amdgcn_mfma_f32_16x16x32_bf16(Bt[n][k], At[m][k], acc[ai][bj][m][n], 0, 0, 0); __builtin_amdgcn_s_setprio(0); } while (0)
; #define PG8_WAIT_V(n) asm volatile("s_waitcnt vmcnt(" #n ")" ::: "memory")
; #define PG8_WAIT_L(n) asm volatile("s_waitcnt lgkmcnt(" #n ")" ::: "memory")
; template <class Epi, class Sched, bool ALIGN_EPI = false, bool SP2 = false>
; __device__ __forceinline__ void gemm_phase(PG8_LAS unsigned char* lds, const Gemm g, const Sched& S, const Epi& E) {
;     ...
;             const bool last = (t == nt - 2);
;             const char* a1 = cA + (size_t)(t + 1) * kstep;
;             const char* a2 = last ? nA : cA + (size_t)(t + 2) * kstep; const char* b2 = last ? nB : cB + (size_t)(t + 2) * kstep;
;             const char* a3 = a2 + kstep; const char* b3 = b2 + kstep;
;             if (last && has_next) S.a_ready(nxt);
;             if constexpr (SP2) {
;             PG8_LDB(B0, 0, 0); PG8_LDB(B1, 0, 1); PG8_SCHED; PG8_LDA(At, 0, 0); PG8_STAGE(PG8_SA(1, 1), a1 + hstep, voffA);
;             PG8_WAIT_V(8); PG8_WAIT_L(0); PG8_BAR; PG8_MMA(0, 0, At, B0); PG8_MMA(0, 1, At, B1); PG8_BAR; PG8_SCHED;
;             PG8_LDA(At, 0, 1); PG8_STAGE(PG8_SB(0, 0), b2, voffB); PG8_STAGE(PG8_SB(0, 1), b2 + hstep, voffB); PG8_STAGE(PG8_SA(0, 0), a2, voffA);
;             PG8_WAIT_V(8); PG8_WAIT_L(0); PG8_BAR; PG8_MMA(1, 0, At, B0); PG8_MMA(1, 1, At, B1); PG8_BAR; PG8_SCHED;
.LBB0_1001:
	ds_read_b128 v[146:149], v152
	ds_read_b128 v[156:159], v152 offset:1024
	ds_read_b128 v[160:163], v152 offset:2048
	ds_read_b128 v[164:167], v152 offset:3072
	ds_read_b128 v[168:171], v153
	ds_read_b128 v[172:175], v153 offset:1024
	ds_read_b128 v[176:179], v153 offset:2048
	ds_read_b128 v[180:183], v153 offset:3072
	s_add_u32 s30, s28, 0xfff00080
	s_addc_u32 s31, s29, -1
	s_cmp_eq_u32 s51, 60
	s_cselect_b32 s35, s21, s31
	s_cselect_b32 s34, s47, s30
	s_cselect_b32 s31, s19, s50
	s_cselect_b32 s30, s48, s49
	v_lshl_add_u64 v[218:219], s[28:29], 0, v[138:139]
	s_add_i32 m0, s27, 0xc000
	ds_read_b128 v[184:187], v154
	ds_read_b128 v[188:191], v154 offset:1024
	ds_read_b128 v[192:195], v154 offset:2048
	ds_read_b128 v[196:199], v154 offset:3072
	ds_read_b128 v[200:203], v154 offset:4096
	ds_read_b128 v[206:209], v154 offset:5120
	ds_read_b128 v[210:213], v154 offset:6144
	ds_read_b128 v[214:217], v154 offset:7168
	global_load_lds_dwordx4 v[218:219], off
	v_lshl_add_u64 v[218:219], s[28:29], 0, v[140:141]
	s_add_i32 m0, s27, 0xe000
	s_nop 0
	global_load_lds_dwordx4 v[218:219], off
	s_waitcnt vmcnt(8)
	s_waitcnt lgkmcnt(0)
	s_setprio 1
	s_barrier
	v_mfma_f32_16x16x32_bf16 v[124:127], v[146:149], v[184:187], v[124:127]
	v_mfma_f32_16x16x32_bf16 v[120:123], v[160:163], v[184:187], v[120:123]
	v_mfma_f32_16x16x32_bf16 v[108:111], v[146:149], v[192:195], v[108:111]
	v_mfma_f32_16x16x32_bf16 v[104:107], v[160:163], v[192:195], v[104:107]
	v_mfma_f32_16x16x32_bf16 v[92:95], v[146:149], v[200:203], v[92:95]
	v_mfma_f32_16x16x32_bf16 v[88:91], v[160:163], v[200:203], v[88:91]
	v_mfma_f32_16x16x32_bf16 v[76:79], v[146:149], v[210:213], v[76:79]
	v_mfma_f32_16x16x32_bf16 v[72:75], v[160:163], v[210:213], v[72:75]
	v_mfma_f32_16x16x32_bf16 v[124:127], v[156:159], v[188:191], v[124:127]
	v_mfma_f32_16x16x32_bf16 v[120:123], v[164:167], v[188:191], v[120:123]
	v_mfma_f32_16x16x32_bf16 v[108:111], v[156:159], v[196:199], v[108:111]
	v_mfma_f32_16x16x32_bf16 v[104:107], v[164:167], v[196:199], v[104:107]
	v_mfma_f32_16x16x32_bf16 v[92:95], v[156:159], v[206:209], v[92:95]
	v_mfma_f32_16x16x32_bf16 v[88:91], v[164:167], v[206:209], v[88:91]
	v_mfma_f32_16x16x32_bf16 v[76:79], v[156:159], v[214:217], v[76:79]
	v_mfma_f32_16x16x32_bf16 v[72:75], v[164:167], v[214:217], v[72:75]
	v_mfma_f32_16x16x32_bf16 v[116:119], v[168:171], v[184:187], v[116:119]
	v_mfma_f32_16x16x32_bf16 v[112:115], v[176:179], v[184:187], v[112:115]
	v_mfma_f32_16x16x32_bf16 v[100:103], v[168:171], v[192:195], v[100:103]
	v_mfma_f32_16x16x32_bf16 v[96:99], v[176:179], v[192:195], v[96:99]
	v_mfma_f32_16x16x32_bf16 v[84:87], v[168:171], v[200:203], v[84:87]
	v_mfma_f32_16x16x32_bf16 v[80:83], v[176:179], v[200:203], v[80:83]
	v_mfma_f32_16x16x32_bf16 v[68:71], v[168:171], v[210:213], v[68:71]
	v_mfma_f32_16x16x32_bf16 v[64:67], v[176:179], v[210:213], v[64:67]
	v_mfma_f32_16x16x32_bf16 v[116:119], v[172:175], v[188:191], v[116:119]
	v_mfma_f32_16x16x32_bf16 v[112:115], v[180:183], v[188:191], v[112:115]
	v_mfma_f32_16x16x32_bf16 v[100:103], v[172:175], v[196:199], v[100:103]
	v_mfma_f32_16x16x32_bf16 v[96:99], v[180:183], v[196:199], v[96:99]
	v_mfma_f32_16x16x32_bf16 v[84:87], v[172:175], v[206:209], v[84:87]
	v_mfma_f32_16x16x32_bf16 v[80:83], v[180:183], v[206:209], v[80:83]
	v_mfma_f32_16x16x32_bf16 v[68:71], v[172:175], v[214:217], v[68:71]
	v_mfma_f32_16x16x32_bf16 v[64:67], v[180:183], v[214:217], v[64:67]
	s_setprio 0
	s_barrier
	s_add_i32 s52, s44, s33
	v_lshl_add_u64 v[218:219], s[30:31], 0, v[132:133]
	s_mov_b32 m0, s52
	ds_read_b128 v[184:187], v154 offset:16384
	ds_read_b128 v[188:191], v154 offset:17408
	ds_read_b128 v[192:195], v154 offset:18432
	ds_read_b128 v[196:199], v154 offset:19456
	ds_read_b128 v[200:203], v154 offset:20480
	ds_read_b128 v[206:209], v154 offset:21504
	ds_read_b128 v[210:213], v154 offset:22528
	ds_read_b128 v[214:217], v154 offset:23552
	global_load_lds_dwordx4 v[218:219], off
	s_add_i32 m0, s52, 0x2000
	s_add_u32 s52, s30, 0x100000
	v_lshl_add_u64 v[220:221], s[30:31], 0, v[136:137]
	s_addc_u32 s53, s31, 0
	s_add_i32 s54, s45, s33
	global_load_lds_dwordx4 v[220:221], off
	v_lshl_add_u64 v[222:223], s[52:53], 0, v[132:133]
	s_mov_b32 m0, s54
	v_lshl_add_u64 v[224:225], s[34:35], 0, v[134:135]
	global_load_lds_dwordx4 v[222:223], off
	v_lshl_add_u64 v[222:223], s[52:53], 0, v[136:137]
	s_add_i32 m0, s54, 0x2000
	s_nop 0
	global_load_lds_dwordx4 v[222:223], off
	v_lshl_add_u64 v[222:223], s[34:35], 0, v[130:131]
	s_mov_b32 m0, s27
	s_nop 0
	global_load_lds_dwordx4 v[222:223], off
	s_mov_b32 m0, s36
	s_nop 0
	global_load_lds_dwordx4 v[224:225], off
	s_waitcnt vmcnt(8)
	s_waitcnt lgkmcnt(0)
	s_setprio 1
	s_barrier
; #define PG8_STAGE(bufoff, gbase, voff) do { _Pragma("unroll") for (int _i = 0; _i < 2; ++_i) \
;         __builtin_amdgcn_global_load_lds((const unsigned*)((const char*)(gbase) + (voff)[_i]), (PG8_LAS unsigned*)(lds + (bufoff) + ldsw + _i * 8192), 16, 0, 0); } while (0)
; #define PG8_LDA(dst, b, h) do { _Pragma("unroll") for (int m = 0; m < 4; ++m) _Pragma("unroll") for (int k = 0; k < 2; ++k) dst[m][k] = *(const PG8_LAS bf16x8*)(lds + PG8_SA(b, h) + aoff + m * 2048 + k * 1024); } while (0)
; #define PG8_LDB(dst, b, h) do { _Pragma("unroll") for (int n = 0; n < 2; ++n) _Pragma("unroll") for (int k = 0; k < 2; ++k) dst[n][k] = *(const PG8_LAS bf16x8*)(lds + PG8_SB(b, h) + boff + n * 2048 + k * 1024); } while (0)
; #define PG8_MMA(ai, bj, At, Bt) do { __builtin_amdgcn_s_setprio(1); _Pragma("unroll") for (int m = 0; m < 4; ++m) _Pragma("unroll") for (int n = 0; n < 2; ++n) _Pragma("unroll") for (int k = 0; k < 2; ++k) \
;         acc[ai][bj][m][n] = __builtin_amdgcn_mfma_f32_16x16x32_bf16(Bt[n][k], At[m][k], acc[ai][bj][m][n], 0, 0, 0); __builtin_amdgcn_s_setprio(0); } while (0)
; #define PG8_WAIT_V(n) asm volatile("s_waitcnt vmcnt(" #n ")" ::: "memory")
; #define PG8_WAIT_L(n) asm volatile("s_waitcnt lgkmcnt(" #n ")" ::: "memory")
; #define PG8_BAR __builtin_amdgcn_s_barrier()
; #define PG8_SCHED __builtin_amdgcn_sched_barrier(0)
; template <class Epi, class Sched, bool ALIGN_EPI = false, bool SP2 = false>
; __device__ __forceinline__ void gemm_phase(PG8_LAS unsigned char* lds, const Gemm g, const Sched& S, const Epi& E) {
;     ...
;             PG8_WAIT_V(8); PG8_WAIT_L(0); PG8_BAR; PG8_MMA(1, 0, At, B0); PG8_MMA(1, 1, At, B1); PG8_BAR; PG8_SCHED;
;             PG8_LDB(B0, 1, 0); PG8_LDB(B1, 1, 1); PG8_SCHED; PG8_LDA(At, 1, 0); PG8_STAGE(PG8_SA(0, 1), a2 + hstep, voffA);
;             PG8_WAIT_V(8); PG8_WAIT_L(0); PG8_BAR; PG8_MMA(0, 0, At, B0); PG8_MMA(0, 1, At, B1); PG8_BAR; PG8_SCHED;
	v_mfma_f32_16x16x32_bf16 v[60:63], v[146:149], v[184:187], v[60:63]
	v_mfma_f32_16x16x32_bf16 v[56:59], v[160:163], v[184:187], v[56:59]
	v_mfma_f32_16x16x32_bf16 v[44:47], v[146:149], v[192:195], v[44:47]
	v_mfma_f32_16x16x32_bf16 v[40:43], v[160:163], v[192:195], v[40:43]
	v_mfma_f32_16x16x32_bf16 v[28:31], v[146:149], v[200:203], v[28:31]
	v_mfma_f32_16x16x32_bf16 v[24:27], v[160:163], v[200:203], v[24:27]
	v_mfma_f32_16x16x32_bf16 v[12:15], v[146:149], v[210:213], v[12:15]
	v_mfma_f32_16x16x32_bf16 v[8:11], v[160:163], v[210:213], v[8:11]
	v_mfma_f32_16x16x32_bf16 v[60:63], v[156:159], v[188:191], v[60:63]
	v_mfma_f32_16x16x32_bf16 v[56:59], v[164:167], v[188:191], v[56:59]
	v_mfma_f32_16x16x32_bf16 v[44:47], v[156:159], v[196:199], v[44:47]
	v_mfma_f32_16x16x32_bf16 v[40:43], v[164:167], v[196:199], v[40:43]
	v_mfma_f32_16x16x32_bf16 v[28:31], v[156:159], v[206:209], v[28:31]
	v_mfma_f32_16x16x32_bf16 v[24:27], v[164:167], v[206:209], v[24:27]
	v_mfma_f32_16x16x32_bf16 v[12:15], v[156:159], v[214:217], v[12:15]
	v_mfma_f32_16x16x32_bf16 v[8:11], v[164:167], v[214:217], v[8:11]
	v_mfma_f32_16x16x32_bf16 v[52:55], v[168:171], v[184:187], v[52:55]
	v_mfma_f32_16x16x32_bf16 v[48:51], v[176:179], v[184:187], v[48:51]
	v_mfma_f32_16x16x32_bf16 v[36:39], v[168:171], v[192:195], v[36:39]
	v_mfma_f32_16x16x32_bf16 v[32:35], v[176:179], v[192:195], v[32:35]
	v_mfma_f32_16x16x32_bf16 v[20:23], v[168:171], v[200:203], v[20:23]
	v_mfma_f32_16x16x32_bf16 v[16:19], v[176:179], v[200:203], v[16:19]
	v_mfma_f32_16x16x32_bf16 v[4:7], v[168:171], v[210:213], v[4:7]
	v_mfma_f32_16x16x32_bf16 v[0:3], v[176:179], v[210:213], v[0:3]
	v_mfma_f32_16x16x32_bf16 v[52:55], v[172:175], v[188:191], v[52:55]
	v_mfma_f32_16x16x32_bf16 v[48:51], v[180:183], v[188:191], v[48:51]
	v_mfma_f32_16x16x32_bf16 v[36:39], v[172:175], v[196:199], v[36:39]
	v_mfma_f32_16x16x32_bf16 v[32:35], v[180:183], v[196:199], v[32:35]
	v_mfma_f32_16x16x32_bf16 v[20:23], v[172:175], v[206:209], v[20:23]
	v_mfma_f32_16x16x32_bf16 v[16:19], v[180:183], v[206:209], v[16:19]
	v_mfma_f32_16x16x32_bf16 v[4:7], v[172:175], v[214:217], v[4:7]
	v_mfma_f32_16x16x32_bf16 v[0:3], v[180:183], v[214:217], v[0:3]
	s_setprio 0
	s_barrier
	s_add_i32 s52, 0, 0x18000
	v_add_u32_e32 v155, s52, v150
	s_add_i32 s53, 0, 0x1c000
	ds_read_b128 v[146:149], v155
	ds_read_b128 v[156:159], v155 offset:1024
	ds_read_b128 v[160:163], v155 offset:2048
	ds_read_b128 v[164:167], v155 offset:3072
	v_add_u32_e32 v155, s53, v150
	ds_read_b128 v[168:171], v155
	ds_read_b128 v[172:175], v155 offset:1024
	ds_read_b128 v[176:179], v155 offset:2048
	ds_read_b128 v[180:183], v155 offset:3072
	s_add_u32 s34, s34, 0x100000
	s_addc_u32 s35, s35, 0
	s_mov_b32 m0, s37
	v_lshl_add_u64 v[226:227], s[34:35], 0, v[130:131]
	ds_read_b128 v[184:187], v154 offset:32768
	ds_read_b128 v[188:191], v154 offset:33792
	ds_read_b128 v[192:195], v154 offset:34816
	ds_read_b128 v[196:199], v154 offset:35840
	ds_read_b128 v[200:203], v154 offset:36864
	ds_read_b128 v[206:209], v154 offset:37888
	ds_read_b128 v[210:213], v154 offset:38912
	ds_read_b128 v[214:217], v154 offset:39936
	global_load_lds_dwordx4 v[226:227], off
	v_lshl_add_u64 v[226:227], s[34:35], 0, v[134:135]
	s_mov_b32 m0, s38
	s_nop 0
	global_load_lds_dwordx4 v[226:227], off
	s_waitcnt vmcnt(8)
	s_waitcnt lgkmcnt(0)
	s_setprio 1
	s_barrier
	v_mfma_f32_16x16x32_bf16 v[124:127], v[146:149], v[184:187], v[124:127]
	v_mfma_f32_16x16x32_bf16 v[120:123], v[160:163], v[184:187], v[120:123]
	v_mfma_f32_16x16x32_bf16 v[108:111], v[146:149], v[192:195], v[108:111]
	v_mfma_f32_16x16x32_bf16 v[104:107], v[160:163], v[192:195], v[104:107]
	v_mfma_f32_16x16x32_bf16 v[92:95], v[146:149], v[200:203], v[92:95]
	v_mfma_f32_16x16x32_bf16 v[88:91], v[160:163], v[200:203], v[88:91]
	v_mfma_f32_16x16x32_bf16 v[76:79], v[146:149], v[210:213], v[76:79]
	v_mfma_f32_16x16x32_bf16 v[72:75], v[160:163], v[210:213], v[72:75]
	v_mfma_f32_16x16x32_bf16 v[124:127], v[156:159], v[188:191], v[124:127]
	v_mfma_f32_16x16x32_bf16 v[120:123], v[164:167], v[188:191], v[120:123]
	v_mfma_f32_16x16x32_bf16 v[108:111], v[156:159], v[196:199], v[108:111]
	v_mfma_f32_16x16x32_bf16 v[104:107], v[164:167], v[196:199], v[104:107]
	v_mfma_f32_16x16x32_bf16 v[92:95], v[156:159], v[206:209], v[92:95]
	v_mfma_f32_16x16x32_bf16 v[88:91], v[164:167], v[206:209], v[88:91]
	v_mfma_f32_16x16x32_bf16 v[76:79], v[156:159], v[214:217], v[76:79]
	v_mfma_f32_16x16x32_bf16 v[72:75], v[164:167], v[214:217], v[72:75]
	v_mfma_f32_16x16x32_bf16 v[116:119], v[168:171], v[184:187], v[116:119]
	v_mfma_f32_16x16x32_bf16 v[112:115], v[176:179], v[184:187], v[112:115]
	v_mfma_f32_16x16x32_bf16 v[100:103], v[168:171], v[192:195], v[100:103]
	v_mfma_f32_16x16x32_bf16 v[96:99], v[176:179], v[192:195], v[96:99]
	v_mfma_f32_16x16x32_bf16 v[84:87], v[168:171], v[200:203], v[84:87]
	v_mfma_f32_16x16x32_bf16 v[80:83], v[176:179], v[200:203], v[80:83]
	v_mfma_f32_16x16x32_bf16 v[68:71], v[168:171], v[210:213], v[68:71]
	v_mfma_f32_16x16x32_bf16 v[64:67], v[176:179], v[210:213], v[64:67]
	v_mfma_f32_16x16x32_bf16 v[116:119], v[172:175], v[188:191], v[116:119]
	v_mfma_f32_16x16x32_bf16 v[112:115], v[180:183], v[188:191], v[112:115]
	v_mfma_f32_16x16x32_bf16 v[100:103], v[172:175], v[196:199], v[100:103]
	v_mfma_f32_16x16x32_bf16 v[96:99], v[180:183], v[196:199], v[96:99]
	v_mfma_f32_16x16x32_bf16 v[84:87], v[172:175], v[206:209], v[84:87]
	v_mfma_f32_16x16x32_bf16 v[80:83], v[180:183], v[206:209], v[80:83]
	v_mfma_f32_16x16x32_bf16 v[68:71], v[172:175], v[214:217], v[68:71]
	v_mfma_f32_16x16x32_bf16 v[64:67], v[180:183], v[214:217], v[64:67]
	s_setprio 0
	s_barrier
; #define PG8_STAGE(bufoff, gbase, voff) do { _Pragma("unroll") for (int _i = 0; _i < 2; ++_i) \
;         __builtin_amdgcn_global_load_lds((const unsigned*)((const char*)(gbase) + (voff)[_i]), (PG8_LAS unsigned*)(lds + (bufoff) + ldsw + _i * 8192), 16, 0, 0); } while (0)
; #define PG8_LDA(dst, b, h) do { _Pragma("unroll") for (int m = 0; m < 4; ++m) _Pragma("unroll") for (int k = 0; k < 2; ++k) dst[m][k] = *(const PG8_LAS bf16x8*)(lds + PG8_SA(b, h) + aoff + m * 2048 + k * 1024); } while (0)
; #define PG8_MMA(ai, bj, At, Bt) do { __builtin_amdgcn_s_setprio(1); _Pragma("unroll") for (int m = 0; m < 4; ++m) _Pragma("unroll") for (int n = 0; n < 2; ++n) _Pragma("unroll") for (int k = 0; k < 2; ++k) \
;         acc[ai][bj][m][n] = __builtin_amdgcn_mfma_f32_16x16x32_bf16(Bt[n][k], At[m][k], acc[ai][bj][m][n], 0, 0, 0); __builtin_amdgcn_s_setprio(0); } while (0)
; #define PG8_WAIT_V(n) asm volatile("s_waitcnt vmcnt(" #n ")" ::: "memory")
; #define PG8_WAIT_L(n) asm volatile("s_waitcnt lgkmcnt(" #n ")" ::: "memory")
; #define PG8_BAR __builtin_amdgcn_s_barrier()
; #define PG8_SCHED __builtin_amdgcn_sched_barrier(0)
; template <class Epi, class Sched, bool ALIGN_EPI = false, bool SP2 = false>
; __device__ __forceinline__ void gemm_phase(PG8_LAS unsigned char* lds, const Gemm g, const Sched& S, const Epi& E) {
;     ...
;             PG8_LDA(At, 1, 1); PG8_STAGE(PG8_SB(1, 0), b3, voffB); PG8_STAGE(PG8_SB(1, 1), b3 + hstep, voffB); PG8_STAGE(PG8_SA(1, 0), a3, voffA);
;             PG8_WAIT_V(8); PG8_WAIT_L(0); PG8_BAR; PG8_MMA(1, 0, At, B0); PG8_MMA(1, 1, At, B1); PG8_BAR; PG8_SCHED;
;     ...
;         if constexpr (ALIGN_EPI) { if (wr == 0) PG8_BAR; }
	s_add_i32 s34, s52, s33
	v_lshl_add_u64 v[218:219], v[218:219], 0, s[12:13]
	s_mov_b32 m0, s34
	ds_read_b128 v[184:187], v154 offset:49152
	ds_read_b128 v[188:191], v154 offset:50176
	ds_read_b128 v[192:195], v154 offset:51200
	ds_read_b128 v[196:199], v154 offset:52224
	ds_read_b128 v[200:203], v154 offset:53248
	ds_read_b128 v[206:209], v154 offset:54272
	ds_read_b128 v[210:213], v154 offset:55296
	ds_read_b128 v[214:217], v154 offset:56320
	global_load_lds_dwordx4 v[218:219], off
	s_add_i32 m0, s34, 0x2000
	s_add_u32 s30, s30, 0x100080
	v_lshl_add_u64 v[218:219], v[220:221], 0, s[12:13]
	s_addc_u32 s31, s31, 0
	s_add_i32 s34, s53, s33
	global_load_lds_dwordx4 v[218:219], off
	v_lshl_add_u64 v[218:219], s[30:31], 0, v[132:133]
	s_mov_b32 m0, s34
	s_nop 0
	global_load_lds_dwordx4 v[218:219], off
	v_lshl_add_u64 v[218:219], s[30:31], 0, v[136:137]
	s_add_i32 m0, s34, 0x2000
	s_nop 0
	global_load_lds_dwordx4 v[218:219], off
	v_lshl_add_u64 v[218:219], v[222:223], 0, s[12:13]
	s_mov_b32 m0, s40
	s_nop 0
	global_load_lds_dwordx4 v[218:219], off
	v_lshl_add_u64 v[218:219], v[224:225], 0, s[12:13]
	s_mov_b32 m0, s41
	s_nop 0
	global_load_lds_dwordx4 v[218:219], off
	s_waitcnt vmcnt(8)
	s_waitcnt lgkmcnt(0)
	s_setprio 1
	s_barrier
	v_mfma_f32_16x16x32_bf16 v[60:63], v[146:149], v[184:187], v[60:63]
	v_mfma_f32_16x16x32_bf16 v[56:59], v[160:163], v[184:187], v[56:59]
	v_mfma_f32_16x16x32_bf16 v[44:47], v[146:149], v[192:195], v[44:47]
	v_mfma_f32_16x16x32_bf16 v[40:43], v[160:163], v[192:195], v[40:43]
	v_mfma_f32_16x16x32_bf16 v[28:31], v[146:149], v[200:203], v[28:31]
	v_mfma_f32_16x16x32_bf16 v[24:27], v[160:163], v[200:203], v[24:27]
	v_mfma_f32_16x16x32_bf16 v[12:15], v[146:149], v[210:213], v[12:15]
	v_mfma_f32_16x16x32_bf16 v[8:11], v[160:163], v[210:213], v[8:11]
	v_mfma_f32_16x16x32_bf16 v[60:63], v[156:159], v[188:191], v[60:63]
	v_mfma_f32_16x16x32_bf16 v[56:59], v[164:167], v[188:191], v[56:59]
	v_mfma_f32_16x16x32_bf16 v[44:47], v[156:159], v[196:199], v[44:47]
	v_mfma_f32_16x16x32_bf16 v[40:43], v[164:167], v[196:199], v[40:43]
	v_mfma_f32_16x16x32_bf16 v[28:31], v[156:159], v[206:209], v[28:31]
	v_mfma_f32_16x16x32_bf16 v[24:27], v[164:167], v[206:209], v[24:27]
	v_mfma_f32_16x16x32_bf16 v[12:15], v[156:159], v[214:217], v[12:15]
	v_mfma_f32_16x16x32_bf16 v[8:11], v[164:167], v[214:217], v[8:11]
	v_mfma_f32_16x16x32_bf16 v[52:55], v[168:171], v[184:187], v[52:55]
	v_mfma_f32_16x16x32_bf16 v[48:51], v[176:179], v[184:187], v[48:51]
	v_mfma_f32_16x16x32_bf16 v[36:39], v[168:171], v[192:195], v[36:39]
	v_mfma_f32_16x16x32_bf16 v[32:35], v[176:179], v[192:195], v[32:35]
	v_mfma_f32_16x16x32_bf16 v[20:23], v[168:171], v[200:203], v[20:23]
	v_mfma_f32_16x16x32_bf16 v[16:19], v[176:179], v[200:203], v[16:19]
	v_mfma_f32_16x16x32_bf16 v[4:7], v[168:171], v[210:213], v[4:7]
	v_mfma_f32_16x16x32_bf16 v[0:3], v[176:179], v[210:213], v[0:3]
	v_mfma_f32_16x16x32_bf16 v[52:55], v[172:175], v[188:191], v[52:55]
	v_mfma_f32_16x16x32_bf16 v[48:51], v[180:183], v[188:191], v[48:51]
	v_mfma_f32_16x16x32_bf16 v[36:39], v[172:175], v[196:199], v[36:39]
	v_mfma_f32_16x16x32_bf16 v[32:35], v[180:183], v[196:199], v[32:35]
	v_mfma_f32_16x16x32_bf16 v[20:23], v[172:175], v[206:209], v[20:23]
	v_mfma_f32_16x16x32_bf16 v[16:19], v[180:183], v[206:209], v[16:19]
	v_mfma_f32_16x16x32_bf16 v[4:7], v[172:175], v[214:217], v[4:7]
	v_mfma_f32_16x16x32_bf16 v[0:3], v[180:183], v[214:217], v[0:3]
	s_setprio 0
	s_barrier
	s_add_i32 s51, s51, 2
	s_add_u32 s28, s28, 0x100
	s_addc_u32 s29, s29, 0
	s_add_u32 s49, s49, 0x100
	s_addc_u32 s50, s50, 0
	s_cmp_gt_u32 s51, 61
	s_cbranch_scc0 .LBB0_1001
	s_and_b64 vcc, exec, s[14:15]
	s_cbranch_vccz .LBB0_1004
	s_barrier

; #define PG8_STAGE(bufoff, gbase, voff) do { _Pragma("unroll") for (int _i = 0; _i < 2; ++_i) \
;         __builtin_amdgcn_global_load_lds((const unsigned*)((const char*)(gbase) + (voff)[_i]), (PG8_LAS unsigned*)(lds + (bufoff) + ldsw + _i * 8192), 16, 0, 0); } while (0)
; #define PG8_LDA(dst, b, h) do { _Pragma("unroll") for (int m = 0; m < 4; ++m) _Pragma("unroll") for (int k = 0; k < 2; ++k) dst[m][k] = *(const PG8_LAS bf16x8*)(lds + PG8_SA(b, h) + aoff + m * 2048 + k * 1024); } while (0)
; #define PG8_LDB(dst, b, h) do { _Pragma("unroll") for (int n = 0; n < 2; ++n) _Pragma("unroll") for (int k = 0; k < 2; ++k) dst[n][k] = *(const PG8_LAS bf16x8*)(lds + PG8_SB(b, h) + boff + n * 2048 + k * 1024); } while (0)
; #define PG8_MMA(ai, bj, At, Bt) do { __builtin_amdgcn_s_setprio(1); _Pragma("unroll") for (int m = 0; m < 4; ++m) _Pragma("unroll") for (int n = 0; n < 2; ++n) _Pragma("unroll") for (int k = 0; k < 2; ++k) \
;         acc[ai][bj][m][n] = __builtin_amdgcn_mfma_f32_16x16x32_bf16(Bt[n][k], At[m][k], acc[ai][bj][m][n], 0, 0, 0); __builtin_amdgcn_s_setprio(0); } while (0)
; #define PG8_WAIT_V(n) asm volatile("s_waitcnt vmcnt(" #n ")" ::: "memory")
; #define PG8_WAIT_L(n) asm volatile("s_waitcnt lgkmcnt(" #n ")" ::: "memory")
; template <class Epi, class Sched, bool ALIGN_EPI = false, bool SP2 = false>
; __device__ __forceinline__ void gemm_phase(PG8_LAS unsigned char* lds, const Gemm g, const Sched& S, const Epi& E) {
;     ...
;             const bool last = (t == nt - 2);
;             const char* a1 = cA + (size_t)(t + 1) * kstep;
;             const char* a2 = last ? nA : cA + (size_t)(t + 2) * kstep; const char* b2 = last ? nB : cB + (size_t)(t + 2) * kstep;
;             const char* a3 = a2 + kstep; const char* b3 = b2 + kstep;
;             if (last && has_next) S.a_ready(nxt);
;             if constexpr (SP2) {
;             PG8_LDB(B0, 0, 0); PG8_LDB(B1, 0, 1); PG8_SCHED; PG8_LDA(At, 0, 0); PG8_STAGE(PG8_SA(1, 1), a1 + hstep, voffA);
;             PG8_WAIT_V(8); PG8_WAIT_L(0); PG8_BAR; PG8_MMA(0, 0, At, B0); PG8_MMA(0, 1, At, B1); PG8_BAR; PG8_SCHED;
;             PG8_LDA(At, 0, 1); PG8_STAGE(PG8_SB(0, 0), b2, voffB); PG8_STAGE(PG8_SB(0, 1), b2 + hstep, voffB); PG8_STAGE(PG8_SA(0, 0), a2, voffA);
;             PG8_WAIT_V(8); PG8_WAIT_L(0); PG8_BAR; PG8_MMA(1, 0, At, B0); PG8_MMA(1, 1, At, B1); PG8_BAR; PG8_SCHED;
.LBB0_1025:
	v_add_u32_e32 v160, s46, v146
	v_add_u32_e32 v176, s47, v146
	s_add_u32 s30, s12, s28
	ds_read_b128 v[148:151], v160
	ds_read_b128 v[152:155], v160 offset:1024
	ds_read_b128 v[156:159], v160 offset:2048
	ds_read_b128 v[160:163], v160 offset:3072
	ds_read_b128 v[164:167], v176
	ds_read_b128 v[168:171], v176 offset:1024
	ds_read_b128 v[172:175], v176 offset:2048
	ds_read_b128 v[176:179], v176 offset:3072
	s_addc_u32 s31, s13, s29
	s_add_u32 s30, s30, 0x100
	s_addc_u32 s31, s31, 0
	s_add_u32 s52, s25, s28
	s_addc_u32 s53, s48, s29
	s_cmpk_eq_i32 s28, 0x1f00
	s_cselect_b32 s35, s21, s31
	s_cselect_b32 s34, s49, s30
	s_cselect_b32 s31, s19, s53
	s_cselect_b32 s30, s50, s52
	v_lshl_add_u64 v[214:215], v[140:141], 0, s[28:29]
	s_add_i32 m0, s11, 0xc000
	ds_read_b128 v[180:183], v147
	ds_read_b128 v[184:187], v147 offset:1024
	ds_read_b128 v[188:191], v147 offset:2048
	ds_read_b128 v[192:195], v147 offset:3072
	ds_read_b128 v[196:199], v147 offset:4096
	ds_read_b128 v[200:203], v147 offset:5120
	ds_read_b128 v[206:209], v147 offset:6144
	ds_read_b128 v[210:213], v147 offset:7168
	global_load_lds_dwordx4 v[214:215], off
	v_lshl_add_u64 v[214:215], v[142:143], 0, s[28:29]
	s_add_i32 m0, s11, 0xe000
	s_nop 0
	global_load_lds_dwordx4 v[214:215], off
	s_waitcnt vmcnt(8)
	s_waitcnt lgkmcnt(0)
	s_setprio 1
	s_barrier
	v_mfma_f32_16x16x32_bf16 v[124:127], v[148:151], v[180:183], v[124:127]
	v_mfma_f32_16x16x32_bf16 v[120:123], v[156:159], v[180:183], v[120:123]
	v_mfma_f32_16x16x32_bf16 v[108:111], v[148:151], v[188:191], v[108:111]
	v_mfma_f32_16x16x32_bf16 v[104:107], v[156:159], v[188:191], v[104:107]
	v_mfma_f32_16x16x32_bf16 v[92:95], v[148:151], v[196:199], v[92:95]
	v_mfma_f32_16x16x32_bf16 v[88:91], v[156:159], v[196:199], v[88:91]
	v_mfma_f32_16x16x32_bf16 v[76:79], v[148:151], v[206:209], v[76:79]
	v_mfma_f32_16x16x32_bf16 v[72:75], v[156:159], v[206:209], v[72:75]
	v_mfma_f32_16x16x32_bf16 v[124:127], v[152:155], v[184:187], v[124:127]
	v_mfma_f32_16x16x32_bf16 v[120:123], v[160:163], v[184:187], v[120:123]
	v_mfma_f32_16x16x32_bf16 v[108:111], v[152:155], v[192:195], v[108:111]
	v_mfma_f32_16x16x32_bf16 v[104:107], v[160:163], v[192:195], v[104:107]
	v_mfma_f32_16x16x32_bf16 v[92:95], v[152:155], v[200:203], v[92:95]
	v_mfma_f32_16x16x32_bf16 v[88:91], v[160:163], v[200:203], v[88:91]
	v_mfma_f32_16x16x32_bf16 v[76:79], v[152:155], v[210:213], v[76:79]
	v_mfma_f32_16x16x32_bf16 v[72:75], v[160:163], v[210:213], v[72:75]
	v_mfma_f32_16x16x32_bf16 v[116:119], v[164:167], v[180:183], v[116:119]
	v_mfma_f32_16x16x32_bf16 v[112:115], v[172:175], v[180:183], v[112:115]
	v_mfma_f32_16x16x32_bf16 v[100:103], v[164:167], v[188:191], v[100:103]
	v_mfma_f32_16x16x32_bf16 v[96:99], v[172:175], v[188:191], v[96:99]
	v_mfma_f32_16x16x32_bf16 v[84:87], v[164:167], v[196:199], v[84:87]
	v_mfma_f32_16x16x32_bf16 v[80:83], v[172:175], v[196:199], v[80:83]
	v_mfma_f32_16x16x32_bf16 v[68:71], v[164:167], v[206:209], v[68:71]
	v_mfma_f32_16x16x32_bf16 v[64:67], v[172:175], v[206:209], v[64:67]
	v_mfma_f32_16x16x32_bf16 v[116:119], v[168:171], v[184:187], v[116:119]
	v_mfma_f32_16x16x32_bf16 v[112:115], v[176:179], v[184:187], v[112:115]
	v_mfma_f32_16x16x32_bf16 v[100:103], v[168:171], v[192:195], v[100:103]
	v_mfma_f32_16x16x32_bf16 v[96:99], v[176:179], v[192:195], v[96:99]
	v_mfma_f32_16x16x32_bf16 v[84:87], v[168:171], v[200:203], v[84:87]
	v_mfma_f32_16x16x32_bf16 v[80:83], v[176:179], v[200:203], v[80:83]
	v_mfma_f32_16x16x32_bf16 v[68:71], v[168:171], v[210:213], v[68:71]
	v_mfma_f32_16x16x32_bf16 v[64:67], v[176:179], v[210:213], v[64:67]
	s_setprio 0
	s_barrier
	s_add_i32 s52, s46, s36
	v_lshl_add_u64 v[214:215], s[30:31], 0, v[130:131]
	s_mov_b32 m0, s52
	ds_read_b128 v[180:183], v147 offset:16384
	ds_read_b128 v[184:187], v147 offset:17408
	ds_read_b128 v[188:191], v147 offset:18432
	ds_read_b128 v[192:195], v147 offset:19456
	ds_read_b128 v[196:199], v147 offset:20480
	ds_read_b128 v[200:203], v147 offset:21504
	ds_read_b128 v[206:209], v147 offset:22528
	ds_read_b128 v[210:213], v147 offset:23552
	global_load_lds_dwordx4 v[214:215], off
	s_add_i32 m0, s52, 0x2000
	s_add_u32 s52, s30, 0x100000
	v_lshl_add_u64 v[216:217], s[30:31], 0, v[132:133]
	s_addc_u32 s53, s31, 0
	s_add_i32 s54, s47, s36
	global_load_lds_dwordx4 v[216:217], off
	v_lshl_add_u64 v[218:219], s[52:53], 0, v[130:131]
	s_mov_b32 m0, s54
	v_lshl_add_u64 v[220:221], s[34:35], 0, v[132:133]
	global_load_lds_dwordx4 v[218:219], off
	v_lshl_add_u64 v[218:219], s[52:53], 0, v[132:133]
	s_add_i32 m0, s54, 0x2000
	s_nop 0
	global_load_lds_dwordx4 v[218:219], off
	v_lshl_add_u64 v[218:219], s[34:35], 0, v[130:131]
	s_mov_b32 m0, s11
	s_nop 0
	global_load_lds_dwordx4 v[218:219], off
	s_mov_b32 m0, s37
	s_nop 0
	global_load_lds_dwordx4 v[220:221], off
	s_waitcnt vmcnt(8)
	s_waitcnt lgkmcnt(0)
	s_setprio 1
	s_barrier
; #define PG8_STAGE(bufoff, gbase, voff) do { _Pragma("unroll") for (int _i = 0; _i < 2; ++_i) \
;         __builtin_amdgcn_global_load_lds((const unsigned*)((const char*)(gbase) + (voff)[_i]), (PG8_LAS unsigned*)(lds + (bufoff) + ldsw + _i * 8192), 16, 0, 0); } while (0)
; #define PG8_LDA(dst, b, h) do { _Pragma("unroll") for (int m = 0; m < 4; ++m) _Pragma("unroll") for (int k = 0; k < 2; ++k) dst[m][k] = *(const PG8_LAS bf16x8*)(lds + PG8_SA(b, h) + aoff + m * 2048 + k * 1024); } while (0)
; #define PG8_LDB(dst, b, h) do { _Pragma("unroll") for (int n = 0; n < 2; ++n) _Pragma("unroll") for (int k = 0; k < 2; ++k) dst[n][k] = *(const PG8_LAS bf16x8*)(lds + PG8_SB(b, h) + boff + n * 2048 + k * 1024); } while (0)
; #define PG8_MMA(ai, bj, At, Bt) do { __builtin_amdgcn_s_setprio(1); _Pragma("unroll") for (int m = 0; m < 4; ++m) _Pragma("unroll") for (int n = 0; n < 2; ++n) _Pragma("unroll") for (int k = 0; k < 2; ++k) \
;         acc[ai][bj][m][n] = __builtin_amdgcn_mfma_f32_16x16x32_bf16(Bt[n][k], At[m][k], acc[ai][bj][m][n], 0, 0, 0); __builtin_amdgcn_s_setprio(0); } while (0)
; #define PG8_WAIT_V(n) asm volatile("s_waitcnt vmcnt(" #n ")" ::: "memory")
; #define PG8_WAIT_L(n) asm volatile("s_waitcnt lgkmcnt(" #n ")" ::: "memory")
; #define PG8_BAR __builtin_amdgcn_s_barrier()
; #define PG8_SCHED __builtin_amdgcn_sched_barrier(0)
; template <class Epi, class Sched, bool ALIGN_EPI = false, bool SP2 = false>
; __device__ __forceinline__ void gemm_phase(PG8_LAS unsigned char* lds, const Gemm g, const Sched& S, const Epi& E) {
;     ...
;             PG8_WAIT_V(8); PG8_WAIT_L(0); PG8_BAR; PG8_MMA(1, 0, At, B0); PG8_MMA(1, 1, At, B1); PG8_BAR; PG8_SCHED;
;             PG8_LDB(B0, 1, 0); PG8_LDB(B1, 1, 1); PG8_SCHED; PG8_LDA(At, 1, 0); PG8_STAGE(PG8_SA(0, 1), a2 + hstep, voffA);
;             PG8_WAIT_V(8); PG8_WAIT_L(0); PG8_BAR; PG8_MMA(0, 0, At, B0); PG8_MMA(0, 1, At, B1); PG8_BAR; PG8_SCHED;
	v_mfma_f32_16x16x32_bf16 v[60:63], v[148:151], v[180:183], v[60:63]
	v_mfma_f32_16x16x32_bf16 v[56:59], v[156:159], v[180:183], v[56:59]
	v_mfma_f32_16x16x32_bf16 v[44:47], v[148:151], v[188:191], v[44:47]
	v_mfma_f32_16x16x32_bf16 v[40:43], v[156:159], v[188:191], v[40:43]
	v_mfma_f32_16x16x32_bf16 v[28:31], v[148:151], v[196:199], v[28:31]
	v_mfma_f32_16x16x32_bf16 v[24:27], v[156:159], v[196:199], v[24:27]
	v_mfma_f32_16x16x32_bf16 v[12:15], v[148:151], v[206:209], v[12:15]
	v_mfma_f32_16x16x32_bf16 v[8:11], v[156:159], v[206:209], v[8:11]
	v_mfma_f32_16x16x32_bf16 v[60:63], v[152:155], v[184:187], v[60:63]
	v_mfma_f32_16x16x32_bf16 v[56:59], v[160:163], v[184:187], v[56:59]
	v_mfma_f32_16x16x32_bf16 v[44:47], v[152:155], v[192:195], v[44:47]
	v_mfma_f32_16x16x32_bf16 v[40:43], v[160:163], v[192:195], v[40:43]
	v_mfma_f32_16x16x32_bf16 v[28:31], v[152:155], v[200:203], v[28:31]
	v_mfma_f32_16x16x32_bf16 v[24:27], v[160:163], v[200:203], v[24:27]
	v_mfma_f32_16x16x32_bf16 v[12:15], v[152:155], v[210:213], v[12:15]
	v_mfma_f32_16x16x32_bf16 v[8:11], v[160:163], v[210:213], v[8:11]
	v_mfma_f32_16x16x32_bf16 v[52:55], v[164:167], v[180:183], v[52:55]
	v_mfma_f32_16x16x32_bf16 v[48:51], v[172:175], v[180:183], v[48:51]
	v_mfma_f32_16x16x32_bf16 v[36:39], v[164:167], v[188:191], v[36:39]
	v_mfma_f32_16x16x32_bf16 v[32:35], v[172:175], v[188:191], v[32:35]
	v_mfma_f32_16x16x32_bf16 v[20:23], v[164:167], v[196:199], v[20:23]
	v_mfma_f32_16x16x32_bf16 v[16:19], v[172:175], v[196:199], v[16:19]
	v_mfma_f32_16x16x32_bf16 v[4:7], v[164:167], v[206:209], v[4:7]
	v_mfma_f32_16x16x32_bf16 v[0:3], v[172:175], v[206:209], v[0:3]
	v_mfma_f32_16x16x32_bf16 v[52:55], v[168:171], v[184:187], v[52:55]
	v_mfma_f32_16x16x32_bf16 v[48:51], v[176:179], v[184:187], v[48:51]
	v_mfma_f32_16x16x32_bf16 v[36:39], v[168:171], v[192:195], v[36:39]
	v_mfma_f32_16x16x32_bf16 v[32:35], v[176:179], v[192:195], v[32:35]
	v_mfma_f32_16x16x32_bf16 v[20:23], v[168:171], v[200:203], v[20:23]
	v_mfma_f32_16x16x32_bf16 v[16:19], v[176:179], v[200:203], v[16:19]
	v_mfma_f32_16x16x32_bf16 v[4:7], v[168:171], v[210:213], v[4:7]
	v_mfma_f32_16x16x32_bf16 v[0:3], v[176:179], v[210:213], v[0:3]
	s_setprio 0
	s_barrier
	s_add_i32 s52, 0, 0x18000
	s_add_i32 s53, 0, 0x1c000
	v_add_u32_e32 v160, s52, v146
	v_add_u32_e32 v176, s53, v146
	ds_read_b128 v[148:151], v160
	ds_read_b128 v[152:155], v160 offset:1024
	ds_read_b128 v[156:159], v160 offset:2048
	ds_read_b128 v[160:163], v160 offset:3072
	ds_read_b128 v[164:167], v176
	ds_read_b128 v[168:171], v176 offset:1024
	ds_read_b128 v[172:175], v176 offset:2048
	ds_read_b128 v[176:179], v176 offset:3072
	s_add_u32 s34, s34, 0x100000
	s_addc_u32 s35, s35, 0
	s_mov_b32 m0, s38
	v_lshl_add_u64 v[222:223], s[34:35], 0, v[130:131]
	ds_read_b128 v[180:183], v147 offset:32768
	ds_read_b128 v[184:187], v147 offset:33792
	ds_read_b128 v[188:191], v147 offset:34816
	ds_read_b128 v[192:195], v147 offset:35840
	ds_read_b128 v[196:199], v147 offset:36864
	ds_read_b128 v[200:203], v147 offset:37888
	ds_read_b128 v[206:209], v147 offset:38912
	ds_read_b128 v[210:213], v147 offset:39936
	global_load_lds_dwordx4 v[222:223], off
	v_lshl_add_u64 v[222:223], s[34:35], 0, v[132:133]
	s_mov_b32 m0, s40
	s_nop 0
	global_load_lds_dwordx4 v[222:223], off
	s_waitcnt vmcnt(8)
	s_waitcnt lgkmcnt(0)
	s_setprio 1
	s_barrier
	v_mfma_f32_16x16x32_bf16 v[124:127], v[148:151], v[180:183], v[124:127]
	v_mfma_f32_16x16x32_bf16 v[120:123], v[156:159], v[180:183], v[120:123]
	v_mfma_f32_16x16x32_bf16 v[108:111], v[148:151], v[188:191], v[108:111]
	v_mfma_f32_16x16x32_bf16 v[104:107], v[156:159], v[188:191], v[104:107]
	v_mfma_f32_16x16x32_bf16 v[92:95], v[148:151], v[196:199], v[92:95]
	v_mfma_f32_16x16x32_bf16 v[88:91], v[156:159], v[196:199], v[88:91]
	v_mfma_f32_16x16x32_bf16 v[76:79], v[148:151], v[206:209], v[76:79]
	v_mfma_f32_16x16x32_bf16 v[72:75], v[156:159], v[206:209], v[72:75]
	v_mfma_f32_16x16x32_bf16 v[124:127], v[152:155], v[184:187], v[124:127]
	v_mfma_f32_16x16x32_bf16 v[120:123], v[160:163], v[184:187], v[120:123]
	v_mfma_f32_16x16x32_bf16 v[108:111], v[152:155], v[192:195], v[108:111]
	v_mfma_f32_16x16x32_bf16 v[104:107], v[160:163], v[192:195], v[104:107]
	v_mfma_f32_16x16x32_bf16 v[92:95], v[152:155], v[200:203], v[92:95]
	v_mfma_f32_16x16x32_bf16 v[88:91], v[160:163], v[200:203], v[88:91]
	v_mfma_f32_16x16x32_bf16 v[76:79], v[152:155], v[210:213], v[76:79]
	v_mfma_f32_16x16x32_bf16 v[72:75], v[160:163], v[210:213], v[72:75]
	v_mfma_f32_16x16x32_bf16 v[116:119], v[164:167], v[180:183], v[116:119]
	v_mfma_f32_16x16x32_bf16 v[112:115], v[172:175], v[180:183], v[112:115]
	v_mfma_f32_16x16x32_bf16 v[100:103], v[164:167], v[188:191], v[100:103]
	v_mfma_f32_16x16x32_bf16 v[96:99], v[172:175], v[188:191], v[96:99]
	v_mfma_f32_16x16x32_bf16 v[84:87], v[164:167], v[196:199], v[84:87]
	v_mfma_f32_16x16x32_bf16 v[80:83], v[172:175], v[196:199], v[80:83]
	v_mfma_f32_16x16x32_bf16 v[68:71], v[164:167], v[206:209], v[68:71]
	v_mfma_f32_16x16x32_bf16 v[64:67], v[172:175], v[206:209], v[64:67]
	v_mfma_f32_16x16x32_bf16 v[116:119], v[168:171], v[184:187], v[116:119]
	v_mfma_f32_16x16x32_bf16 v[112:115], v[176:179], v[184:187], v[112:115]
	v_mfma_f32_16x16x32_bf16 v[100:103], v[168:171], v[192:195], v[100:103]
	v_mfma_f32_16x16x32_bf16 v[96:99], v[176:179], v[192:195], v[96:99]
	v_mfma_f32_16x16x32_bf16 v[84:87], v[168:171], v[200:203], v[84:87]
	v_mfma_f32_16x16x32_bf16 v[80:83], v[176:179], v[200:203], v[80:83]
	v_mfma_f32_16x16x32_bf16 v[68:71], v[168:171], v[210:213], v[68:71]
	v_mfma_f32_16x16x32_bf16 v[64:67], v[176:179], v[210:213], v[64:67]
	s_setprio 0
	s_barrier
; #define PG8_WAIT_V(n) asm volatile("s_waitcnt vmcnt(" #n ")" ::: "memory")
; #define PG8_WAIT_L(n) asm volatile("s_waitcnt lgkmcnt(" #n ")" ::: "memory")
; template <class Epi, class Sched, bool ALIGN_EPI = false, bool SP2 = false>
; __device__ __forceinline__ void gemm_phase(PG8_LAS unsigned char* lds, const Gemm g, const Sched& S, const Epi& E) {
;     ...
;             PG8_LDA(At, 1, 1); PG8_STAGE(PG8_SB(1, 0), b3, voffB); PG8_STAGE(PG8_SB(1, 1), b3 + hstep, voffB); PG8_STAGE(PG8_SA(1, 0), a3, voffA);
;             PG8_WAIT_V(8); PG8_WAIT_L(0); PG8_BAR; PG8_MMA(1, 0, At, B0); PG8_MMA(1, 1, At, B1); PG8_BAR; PG8_SCHED;
;             } else {
;             PG8_LDB(B0, 0, 0); PG8_SCHED; PG8_LDA(At, 0, 0); PG8_STAGE(PG8_SA(1, 1), a1 + hstep, voffA);
;             PG8_WAIT_L(8); PG8_BAR; PG8_WAIT_L(0); PG8_MMA(0, 0, At, B0); PG8_BAR; PG8_SCHED;
;             PG8_LDB(B1, 0, 1); PG8_STAGE(PG8_SB(0, 0), b2, voffB);
;             PG8_BAR; PG8_WAIT_L(0); PG8_MMA(0, 1, At, B1); PG8_BAR;
;             PG8_LDA(At, 0, 1); PG8_STAGE(PG8_SA(0, 0), a2, voffA);
;             PG8_BAR; PG8_WAIT_L(0); PG8_MMA(1, 0, At, B0); PG8_BAR; PG8_SCHED;
;             PG8_STAGE(PG8_SB(0, 1), b2 + hstep, voffB);
;             PG8_WAIT_V(6); PG8_BAR; PG8_MMA(1, 1, At, B1); PG8_BAR;
;             PG8_LDB(B0, 1, 0); PG8_SCHED; PG8_LDA(At, 1, 0); PG8_STAGE(PG8_SA(0, 1), a2 + hstep, voffA);
;             PG8_WAIT_L(8); PG8_BAR; PG8_WAIT_L(0); PG8_MMA(0, 0, At, B0); PG8_BAR; PG8_SCHED;
;             PG8_LDB(B1, 1, 1); PG8_STAGE(PG8_SB(1, 0), b3, voffB);
;             PG8_BAR; PG8_WAIT_L(0); PG8_MMA(0, 1, At, B1); PG8_BAR;
;             PG8_LDA(At, 1, 1); PG8_STAGE(PG8_SA(1, 0), a3, voffA);
;             PG8_BAR; PG8_WAIT_L(0); PG8_MMA(1, 0, At, B0); PG8_BAR; PG8_SCHED;
;             PG8_STAGE(PG8_SB(1, 1), b3 + hstep, voffB);
;             PG8_WAIT_V(6); PG8_BAR; PG8_MMA(1, 1, At, B1); PG8_BAR;
;             }
;         }
;         if constexpr (ALIGN_EPI) { if (wr == 0) PG8_BAR; }
;         if constexpr (!Epi::AFTER_DRAIN) { E(acc, cur, wr, wc, fr, fq); S.done(cur); }
;         if (!has_next) break;
; #pragma unroll
;         for (int a = 0; a < 2; ++a)
; #pragma unroll
;             for (int b = 0; b < 2; ++b)
; #pragma unroll
;                 for (int m = 0; m < 4; ++m)
; #pragma unroll
;                     for (int n = 0; n < 2; ++n) acc[a][b][m][n] = (f32x4){0.f, 0.f, 0.f, 0.f};
	s_add_i32 s34, s52, s36
	v_lshl_add_u64 v[214:215], v[214:215], 0, s[14:15]
	s_mov_b32 m0, s34
	ds_read_b128 v[180:183], v147 offset:49152
	ds_read_b128 v[184:187], v147 offset:50176
	ds_read_b128 v[188:191], v147 offset:51200
	ds_read_b128 v[192:195], v147 offset:52224
	ds_read_b128 v[196:199], v147 offset:53248
	ds_read_b128 v[200:203], v147 offset:54272
	ds_read_b128 v[206:209], v147 offset:55296
	ds_read_b128 v[210:213], v147 offset:56320
	global_load_lds_dwordx4 v[214:215], off
	s_add_i32 m0, s34, 0x2000
	s_add_u32 s30, s30, 0x100080
	v_lshl_add_u64 v[214:215], v[216:217], 0, s[14:15]
	s_addc_u32 s31, s31, 0
	s_add_i32 s34, s53, s36
	global_load_lds_dwordx4 v[214:215], off
	v_lshl_add_u64 v[214:215], s[30:31], 0, v[130:131]
	s_mov_b32 m0, s34
	s_nop 0
	global_load_lds_dwordx4 v[214:215], off
	v_lshl_add_u64 v[214:215], s[30:31], 0, v[132:133]
	s_add_i32 m0, s34, 0x2000
	s_nop 0
	global_load_lds_dwordx4 v[214:215], off
	v_lshl_add_u64 v[214:215], v[218:219], 0, s[14:15]
	s_mov_b32 m0, s42
	s_nop 0
	global_load_lds_dwordx4 v[214:215], off
	v_lshl_add_u64 v[214:215], v[220:221], 0, s[14:15]
	s_mov_b32 m0, s43
	s_nop 0
	global_load_lds_dwordx4 v[214:215], off
	s_waitcnt vmcnt(8)
	s_waitcnt lgkmcnt(0)
	s_setprio 1
	s_barrier
	v_mfma_f32_16x16x32_bf16 v[60:63], v[148:151], v[180:183], v[60:63]
	v_mfma_f32_16x16x32_bf16 v[56:59], v[156:159], v[180:183], v[56:59]
	v_mfma_f32_16x16x32_bf16 v[44:47], v[148:151], v[188:191], v[44:47]
	v_mfma_f32_16x16x32_bf16 v[40:43], v[156:159], v[188:191], v[40:43]
	v_mfma_f32_16x16x32_bf16 v[28:31], v[148:151], v[196:199], v[28:31]
	v_mfma_f32_16x16x32_bf16 v[24:27], v[156:159], v[196:199], v[24:27]
	v_mfma_f32_16x16x32_bf16 v[12:15], v[148:151], v[206:209], v[12:15]
	v_mfma_f32_16x16x32_bf16 v[8:11], v[156:159], v[206:209], v[8:11]
	v_mfma_f32_16x16x32_bf16 v[60:63], v[152:155], v[184:187], v[60:63]
	v_mfma_f32_16x16x32_bf16 v[56:59], v[160:163], v[184:187], v[56:59]
	v_mfma_f32_16x16x32_bf16 v[44:47], v[152:155], v[192:195], v[44:47]
	v_mfma_f32_16x16x32_bf16 v[40:43], v[160:163], v[192:195], v[40:43]
	v_mfma_f32_16x16x32_bf16 v[28:31], v[152:155], v[200:203], v[28:31]
	v_mfma_f32_16x16x32_bf16 v[24:27], v[160:163], v[200:203], v[24:27]
	v_mfma_f32_16x16x32_bf16 v[12:15], v[152:155], v[210:213], v[12:15]
	v_mfma_f32_16x16x32_bf16 v[8:11], v[160:163], v[210:213], v[8:11]
	v_mfma_f32_16x16x32_bf16 v[52:55], v[164:167], v[180:183], v[52:55]
	v_mfma_f32_16x16x32_bf16 v[48:51], v[172:175], v[180:183], v[48:51]
	v_mfma_f32_16x16x32_bf16 v[36:39], v[164:167], v[188:191], v[36:39]
	v_mfma_f32_16x16x32_bf16 v[32:35], v[172:175], v[188:191], v[32:35]
	v_mfma_f32_16x16x32_bf16 v[20:23], v[164:167], v[196:199], v[20:23]
	v_mfma_f32_16x16x32_bf16 v[16:19], v[172:175], v[196:199], v[16:19]
	v_mfma_f32_16x16x32_bf16 v[4:7], v[164:167], v[206:209], v[4:7]
	v_mfma_f32_16x16x32_bf16 v[0:3], v[172:175], v[206:209], v[0:3]
	v_mfma_f32_16x16x32_bf16 v[52:55], v[168:171], v[184:187], v[52:55]
	v_mfma_f32_16x16x32_bf16 v[48:51], v[176:179], v[184:187], v[48:51]
	v_mfma_f32_16x16x32_bf16 v[36:39], v[168:171], v[192:195], v[36:39]
	v_mfma_f32_16x16x32_bf16 v[32:35], v[176:179], v[192:195], v[32:35]
	v_mfma_f32_16x16x32_bf16 v[20:23], v[168:171], v[200:203], v[20:23]
	v_mfma_f32_16x16x32_bf16 v[16:19], v[176:179], v[200:203], v[16:19]
	v_mfma_f32_16x16x32_bf16 v[4:7], v[168:171], v[210:213], v[4:7]
	v_mfma_f32_16x16x32_bf16 v[0:3], v[176:179], v[210:213], v[0:3]
	s_setprio 0
	s_barrier
	s_add_i32 s51, s51, 2
	s_add_u32 s28, s28, 0x100
	s_addc_u32 s29, s29, 0
	s_cmp_gt_u32 s51, 61
	s_cbranch_scc0 .LBB0_1025
	s_add_u32 s28, s25, 0xffffff00
	s_addc_u32 s29, s48, -1
	s_andn2_b64 vcc, exec, s[6:7]
	s_cbranch_vccnz .LBB0_1028
	v_mov_b32_e32 v0, 0
	s_mov_b32 s44, s18
	s_mov_b32 s10, s20
	s_mov_b64 s[12:13], s[26:27]
	s_mov_b32 s45, s24
	v_mov_b32_e32 v1, v0
	v_mov_b32_e32 v2, v0
	v_mov_b32_e32 v3, v0
	v_mov_b32_e32 v4, v0
	v_mov_b32_e32 v5, v0
	v_mov_b32_e32 v6, v0
	v_mov_b32_e32 v7, v0
	v_mov_b32_e32 v16, v0
	v_mov_b32_e32 v17, v0
	v_mov_b32_e32 v18, v0
	v_mov_b32_e32 v19, v0
	v_mov_b32_e32 v20, v0
	v_mov_b32_e32 v21, v0
	v_mov_b32_e32 v22, v0
	v_mov_b32_e32 v23, v0
	v_mov_b32_e32 v32, v0
	v_mov_b32_e32 v33, v0
	v_mov_b32_e32 v34, v0
	v_mov_b32_e32 v35, v0
	v_mov_b32_e32 v36, v0
	v_mov_b32_e32 v37, v0
	v_mov_b32_e32 v38, v0
	v_mov_b32_e32 v39, v0
	v_mov_b32_e32 v48, v0
	v_mov_b32_e32 v49, v0
	v_mov_b32_e32 v50, v0
	v_mov_b32_e32 v51, v0
	v_mov_b32_e32 v52, v0
	v_mov_b32_e32 v53, v0
	v_mov_b32_e32 v54, v0
	v_mov_b32_e32 v55, v0
	v_mov_b32_e32 v8, v0
	v_mov_b32_e32 v9, v0
	v_mov_b32_e32 v10, v0
	v_mov_b32_e32 v11, v0
	v_mov_b32_e32 v12, v0
	v_mov_b32_e32 v13, v0
	v_mov_b32_e32 v14, v0
	v_mov_b32_e32 v15, v0
	v_mov_b32_e32 v24, v0
	v_mov_b32_e32 v25, v0
	v_mov_b32_e32 v26, v0
	v_mov_b32_e32 v27, v0
	v_mov_b32_e32 v28, v0
	v_mov_b32_e32 v29, v0
	v_mov_b32_e32 v30, v0
	v_mov_b32_e32 v31, v0
	v_mov_b32_e32 v40, v0
	v_mov_b32_e32 v41, v0
	v_mov_b32_e32 v42, v0
	v_mov_b32_e32 v43, v0
	v_mov_b32_e32 v44, v0
	v_mov_b32_e32 v45, v0
	v_mov_b32_e32 v46, v0
	v_mov_b32_e32 v47, v0
	v_mov_b32_e32 v56, v0
	v_mov_b32_e32 v57, v0
	v_mov_b32_e32 v58, v0
	v_mov_b32_e32 v59, v0
	v_mov_b32_e32 v60, v0
	v_mov_b32_e32 v61, v0
	v_mov_b32_e32 v62, v0
	v_mov_b32_e32 v63, v0
	v_mov_b32_e32 v64, v0
	v_mov_b32_e32 v65, v0
	v_mov_b32_e32 v66, v0
	v_mov_b32_e32 v67, v0
	v_mov_b32_e32 v68, v0
	v_mov_b32_e32 v69, v0
	v_mov_b32_e32 v70, v0
	v_mov_b32_e32 v71, v0
	v_mov_b32_e32 v80, v0
	v_mov_b32_e32 v81, v0
	v_mov_b32_e32 v82, v0
	v_mov_b32_e32 v83, v0
	v_mov_b32_e32 v84, v0
	v_mov_b32_e32 v85, v0
	v_mov_b32_e32 v86, v0
	v_mov_b32_e32 v87, v0
	v_mov_b32_e32 v96, v0
	v_mov_b32_e32 v97, v0
	v_mov_b32_e32 v98, v0
	v_mov_b32_e32 v99, v0
	v_mov_b32_e32 v100, v0
	v_mov_b32_e32 v101, v0
	v_mov_b32_e32 v102, v0
	v_mov_b32_e32 v103, v0
	v_mov_b32_e32 v112, v0
	v_mov_b32_e32 v113, v0
	v_mov_b32_e32 v114, v0
	v_mov_b32_e32 v115, v0
	v_mov_b32_e32 v116, v0
	v_mov_b32_e32 v117, v0
	v_mov_b32_e32 v118, v0
	v_mov_b32_e32 v119, v0
	v_mov_b32_e32 v72, v0
	v_mov_b32_e32 v73, v0
	v_mov_b32_e32 v74, v0
	v_mov_b32_e32 v75, v0
	v_mov_b32_e32 v76, v0
	v_mov_b32_e32 v77, v0
	v_mov_b32_e32 v78, v0
	v_mov_b32_e32 v79, v0
	v_mov_b32_e32 v88, v0
	v_mov_b32_e32 v89, v0
	v_mov_b32_e32 v90, v0
	v_mov_b32_e32 v91, v0
	v_mov_b32_e32 v92, v0
	v_mov_b32_e32 v93, v0
	v_mov_b32_e32 v94, v0
	v_mov_b32_e32 v95, v0
	v_mov_b32_e32 v104, v0
	v_mov_b32_e32 v105, v0
	v_mov_b32_e32 v106, v0
	v_mov_b32_e32 v107, v0
	v_mov_b32_e32 v108, v0
	v_mov_b32_e32 v109, v0
	v_mov_b32_e32 v110, v0
	v_mov_b32_e32 v111, v0
	v_mov_b32_e32 v120, v0
	v_mov_b32_e32 v121, v0
	v_mov_b32_e32 v122, v0
	v_mov_b32_e32 v123, v0
	v_mov_b32_e32 v124, v0
	v_mov_b32_e32 v125, v0
	v_mov_b32_e32 v126, v0
	v_mov_b32_e32 v127, v0
	s_andn2_b64 vcc, exec, s[0:1]
	s_cbranch_vccnz .LBB0_1029
	s_branch .LBB0_1030
